# hyena FFT: also split ds_write2_b64 into two ds_write_b64 (13 vs 2x6 store-path cycles)
# speedup vs baseline: 1.0051x; 1.0044x over previous
.LBB0_275:
	s_or_b64 exec, exec, s[10:11]
	s_add_i32 s77, 0, 0x22000
	v_mov_b32_e32 v0, s77
	s_waitcnt lgkmcnt(0)
	s_barrier
	ds_read_b128 v[28:31], v0
	v_mov_b32_e32 v0, s92
	ds_read_b128 v[32:35], v0
	s_waitcnt vmcnt(1)
	v_mov_b32_e32 v59, v58
	v_mov_b32_e32 v57, v56
	s_waitcnt lgkmcnt(1)
	v_add_f32_e32 v0, 0, v28
	v_add_f32_e32 v0, v0, v29
	v_add_f32_e32 v0, v0, v30
	v_add_f32_e32 v0, v0, v31
	s_waitcnt lgkmcnt(0)
	v_add_f32_e32 v0, v0, v32
	v_add_f32_e32 v0, v0, v33
	v_add_f32_e32 v0, v0, v34
	v_add_f32_e32 v0, v0, v35
	v_add_f32_e32 v0, 0x358637bd, v0
	v_mul_f32_e32 v28, 0x4f800000, v0
	v_cmp_gt_f32_e32 vcc, s23, v0
	s_waitcnt vmcnt(0)
	v_mov_b32_e32 v61, v60
	s_mov_b64 s[18:19], -1
	v_cndmask_b32_e32 v0, v0, v28, vcc
	v_sqrt_f32_e32 v28, v0
	s_nop 0
	v_add_u32_e32 v29, -1, v28
	v_fma_f32 v30, -v29, v28, v0
	v_cmp_ge_f32_e64 s[50:51], 0, v30
	v_add_u32_e32 v30, 1, v28
	s_nop 0
	v_cndmask_b32_e64 v29, v28, v29, s[50:51]
	v_fma_f32 v28, -v30, v28, v0
	v_cmp_lt_f32_e64 s[50:51], 0, v28
	s_nop 1
	v_cndmask_b32_e64 v28, v29, v30, s[50:51]
	v_mul_f32_e32 v29, 0x37800000, v28
	v_cndmask_b32_e32 v28, v28, v29, vcc
	v_cmp_class_f32_e32 vcc, v0, v210
	v_cmp_gt_i32_e64 s[50:51], s52, v137
	s_nop 0
	v_cndmask_b32_e32 v0, v28, v0, vcc
	v_div_scale_f32 v28, s[10:11], v0, v0, 1.0
	v_rcp_f32_e32 v29, v28
	s_mul_hi_i32 s10, s16, 0x8800
	s_mul_i32 s16, s16, 0x8800
	s_add_u32 s40, s85, s16
	v_fma_f32 v30, -v28, v29, 1.0
	v_fmac_f32_e32 v29, v30, v29
	v_div_scale_f32 v30, vcc, 1.0, v0, 1.0
	v_mul_f32_e32 v31, v30, v29
	v_fma_f32 v32, -v28, v31, v30
	v_fmac_f32_e32 v31, v32, v29
	v_fma_f32 v28, -v28, v31, v30
	v_div_fmas_f32 v28, v28, v29, v31
	v_div_fixup_f32 v0, v28, v0, 1.0
	v_mov_b32_e32 v29, v208
	v_mul_f32_e32 v28, v7, v0
	s_addc_u32 s41, s39, s10
	v_and_b32_e32 v0, 0xff, v29
	v_lshlrev_b32_e32 v30, 4, v29
	v_and_or_b32 v0, v30, s93, v0
	v_ashrrev_i32_e32 v30, 4, v0
	v_lshlrev_b32_e32 v30, 3, v30
	v_lshlrev_b32_e32 v0, 3, v0
	v_add3_u32 v55, 0, v30, v0
	ds_read_b64 v[32:33], v55
	ds_read_b64 v[34:35], v55 offset:2176
	ds_read_b64 v[62:63], v55 offset:4352
	ds_read_b64 v[64:65], v55 offset:6528
	ds_read_b64 v[66:67], v55 offset:8704
	ds_read_b64 v[68:69], v55 offset:10880
	ds_read_b64 v[70:71], v55 offset:13056
	ds_read_b64 v[72:73], v55 offset:15232
	ds_read_b64 v[74:75], v55 offset:17408
	ds_read_b64 v[76:77], v55 offset:19584
	ds_read_b64 v[78:79], v55 offset:21760
	ds_read_b64 v[80:81], v55 offset:23936
	ds_read_b64 v[82:83], v55 offset:26112
	ds_read_b64 v[84:85], v55 offset:28288
	ds_read_b64 v[86:87], v55 offset:30464
	ds_read_b64 v[88:89], v55 offset:32640
	s_waitcnt lgkmcnt(5)
	v_pk_add_f32 v[96:97], v[62:63], v[78:79]
	v_pk_add_f32 v[62:63], v[62:63], v[78:79] neg_lo:[0,1] neg_hi:[0,1]
	s_waitcnt lgkmcnt(2)
	v_pk_add_f32 v[106:107], v[68:69], v[84:85]
	s_waitcnt lgkmcnt(1)
	v_pk_add_f32 v[98:99], v[70:71], v[86:87]
	v_pk_add_f32 v[70:71], v[70:71], v[86:87] neg_lo:[0,1] neg_hi:[0,1]
	v_pk_add_f32 v[68:69], v[68:69], v[84:85] neg_lo:[0,1] neg_hi:[0,1]
	v_xor_b32_e32 v79, 0x80000000, v70
	v_mov_b32_e32 v78, v71
	v_pk_add_f32 v[104:105], v[34:35], v[76:77]
	v_pk_add_f32 v[70:71], v[62:63], v[78:79]
	v_pk_add_f32 v[34:35], v[34:35], v[76:77] neg_lo:[0,1] neg_hi:[0,1]
	v_xor_b32_e32 v77, 0x80000000, v68
	v_mov_b32_e32 v76, v69
	v_pk_add_f32 v[92:93], v[66:67], v[82:83]
	v_pk_add_f32 v[66:67], v[66:67], v[82:83] neg_lo:[0,1] neg_hi:[0,1]
	v_pk_mul_f32 v[82:83], v[70:71], s[24:25] op_sel_hi:[1,0]
	v_pk_add_f32 v[68:69], v[34:35], v[76:77]
	v_pk_fma_f32 v[86:87], v[70:71], s[24:25], v[82:83] op_sel:[0,0,1] op_sel_hi:[1,0,0]
	v_pk_fma_f32 v[70:71], v[70:71], s[24:25], v[82:83] op_sel_hi:[1,0,0] neg_lo:[0,0,1] neg_hi:[0,0,1]
	v_pk_mul_f32 v[82:83], v[68:69], s[30:31] op_sel_hi:[1,0]
	v_pk_add_f32 v[90:91], v[32:33], v[74:75]
	v_pk_fma_f32 v[84:85], v[68:69], s[22:23], v[82:83] op_sel:[0,0,1] op_sel_hi:[1,0,0]
	v_pk_fma_f32 v[68:69], v[68:69], s[22:23], v[82:83] op_sel:[0,0,1] op_sel_hi:[1,0,0] neg_lo:[0,0,1] neg_hi:[0,0,1]
	v_pk_add_f32 v[94:95], v[90:91], v[92:93]
	v_pk_add_f32 v[100:101], v[96:97], v[98:99]
	s_waitcnt lgkmcnt(0)
	v_pk_add_f32 v[112:113], v[72:73], v[88:89]
	v_mov_b32_e32 v85, v69
	v_pk_add_f32 v[68:69], v[72:73], v[88:89] neg_lo:[0,1] neg_hi:[0,1]
	v_pk_add_f32 v[88:89], v[90:91], v[92:93] neg_lo:[0,1] neg_hi:[0,1]
	v_pk_add_f32 v[90:91], v[96:97], v[98:99] neg_lo:[0,1] neg_hi:[0,1]
	v_pk_add_f32 v[96:97], v[104:105], v[106:107] neg_lo:[0,1] neg_hi:[0,1]
	v_pk_add_f32 v[110:111], v[64:65], v[80:81]
	v_pk_add_f32 v[64:65], v[64:65], v[80:81] neg_lo:[0,1] neg_hi:[0,1]
	v_xor_b32_e32 v73, 0x80000000, v68
	v_mov_b32_e32 v72, v69
	v_pk_mul_f32 v[98:99], v[96:97], s[24:25] op_sel_hi:[1,0]
	v_pk_add_f32 v[108:109], v[104:105], v[106:107]
	v_pk_add_f32 v[68:69], v[64:65], v[72:73]
	v_pk_fma_f32 v[104:105], v[96:97], s[24:25], v[98:99] op_sel:[0,0,1] op_sel_hi:[1,0,0]
	v_pk_fma_f32 v[96:97], v[96:97], s[24:25], v[98:99] op_sel_hi:[1,0,0] neg_lo:[0,0,1] neg_hi:[0,0,1]
	v_pk_mul_f32 v[80:81], v[68:69], s[22:23] op_sel_hi:[1,0]
	v_mov_b32_e32 v105, v97
	v_pk_add_f32 v[96:97], v[110:111], v[112:113] neg_lo:[0,1] neg_hi:[0,1]
	v_pk_add_f32 v[34:35], v[34:35], v[76:77] neg_lo:[0,1] neg_hi:[0,1]
	v_pk_fma_f32 v[82:83], v[68:69], s[30:31], v[80:81] op_sel:[0,0,1] op_sel_hi:[1,0,0]
	v_pk_fma_f32 v[68:69], v[68:69], s[30:31], v[80:81] op_sel:[0,0,1] op_sel_hi:[1,0,0] neg_lo:[0,0,1] neg_hi:[0,0,1]
	v_mul_f32_e32 v0, 0x3f3504f3, v96
	v_pk_add_f32 v[62:63], v[62:63], v[78:79] neg_lo:[0,1] neg_hi:[0,1]
	v_pk_mul_f32 v[76:77], v[34:35], s[22:23] op_sel_hi:[1,0]
	v_pk_add_f32 v[32:33], v[32:33], v[74:75] neg_lo:[0,1] neg_hi:[0,1]
	v_xor_b32_e32 v75, 0x80000000, v66
	v_mov_b32_e32 v74, v67
	v_mov_b32_e32 v83, v69
	v_pk_fma_f32 v[96:97], v[96:97], s[24:25], v[0:1] op_sel:[1,0,0] op_sel_hi:[1,1,0] neg_lo:[0,0,1] neg_hi:[0,0,1]
	v_mul_f32_e32 v0, 0x3f3504f3, v62
	v_pk_fma_f32 v[78:79], v[34:35], s[30:31], v[76:77] op_sel:[0,0,1] op_sel_hi:[1,0,0]
	v_pk_fma_f32 v[34:35], v[34:35], s[30:31], v[76:77] op_sel:[0,0,1] op_sel_hi:[1,0,0] neg_lo:[0,0,1] neg_hi:[0,0,1]
	v_pk_add_f32 v[66:67], v[32:33], v[74:75]
	v_mov_b32_e32 v87, v71
	v_pk_add_f32 v[68:69], v[84:85], v[82:83] neg_lo:[0,1] neg_hi:[0,1]
	v_xor_b32_e32 v93, 0x80000000, v90
	v_mov_b32_e32 v92, v91
	v_pk_add_f32 v[98:99], v[104:105], v[96:97] neg_lo:[0,1] neg_hi:[0,1]
	v_pk_fma_f32 v[62:63], v[62:63], s[24:25], v[0:1] op_sel:[1,0,0] op_sel_hi:[1,1,0] neg_lo:[0,0,1] neg_hi:[0,0,1]
	v_mov_b32_e32 v79, v35
	v_pk_add_f32 v[34:35], v[64:65], v[72:73] neg_lo:[0,1] neg_hi:[0,1]
	v_cvt_f32_ubyte0_e32 v0, v29
	v_pk_add_f32 v[70:71], v[66:67], v[86:87] neg_lo:[0,1] neg_hi:[0,1]
	v_xor_b32_e32 v81, 0x80000000, v68
	v_mov_b32_e32 v80, v69
	v_pk_add_f32 v[90:91], v[88:89], v[92:93] neg_lo:[0,1] neg_hi:[0,1]
	v_xor_b32_e32 v107, 0x80000000, v98
	v_mov_b32_e32 v106, v99
	v_pk_mul_f32 v[64:65], v[34:35], s[30:31]
	v_mul_f32_e32 v0, 0x39800000, v0
	v_pk_add_f32 v[68:69], v[70:71], v[80:81]
	v_pk_add_f32 v[98:99], v[90:91], v[106:107]
	v_pk_fma_f32 v[34:35], v[34:35], s[22:23], v[64:65] op_sel:[0,0,1] op_sel_hi:[1,0,0] neg_lo:[1,0,0] neg_hi:[1,0,0]
	v_pk_add_f32 v[70:71], v[70:71], v[80:81] neg_lo:[0,1] neg_hi:[0,1]
	v_pk_add_f32 v[80:81], v[90:91], v[106:107] neg_lo:[0,1] neg_hi:[0,1]
	v_sin_f32_e32 v90, v0
	v_pk_add_f32 v[102:103], v[94:95], v[100:101]
	v_pk_add_f32 v[64:65], v[78:79], v[34:35] neg_lo:[0,1] neg_hi:[0,1]
	v_pk_add_f32 v[34:35], v[78:79], v[34:35]
	v_pk_add_f32 v[78:79], v[94:95], v[100:101] neg_lo:[0,1] neg_hi:[0,1]
	v_cos_f32_e32 v100, v0
	v_pk_add_f32 v[32:33], v[32:33], v[74:75] neg_lo:[0,1] neg_hi:[0,1]
	v_pk_add_f32 v[66:67], v[66:67], v[86:87]
	v_pk_add_f32 v[82:83], v[84:85], v[82:83]
	v_pk_add_f32 v[74:75], v[32:33], v[62:63] neg_lo:[0,1] neg_hi:[0,1]
	v_xor_b32_e32 v73, 0x80000000, v64
	v_mov_b32_e32 v72, v65
	v_pk_add_f32 v[84:85], v[66:67], v[82:83] neg_lo:[0,1] neg_hi:[0,1]
	v_pk_add_f32 v[66:67], v[66:67], v[82:83]
	v_pk_add_f32 v[64:65], v[74:75], v[72:73]
	v_pk_add_f32 v[72:73], v[74:75], v[72:73] neg_lo:[0,1] neg_hi:[0,1]
	v_pk_mul_f32 v[74:75], v[90:91], v[66:67] op_sel:[0,1] op_sel_hi:[0,0]
	v_pk_add_f32 v[86:87], v[88:89], v[92:93]
	v_pk_add_f32 v[88:89], v[104:105], v[96:97]
	v_pk_fma_f32 v[82:83], v[100:101], v[66:67], v[74:75]
	v_pk_fma_f32 v[66:67], v[100:101], v[66:67], v[74:75] op_sel_hi:[0,1,1] neg_lo:[0,0,1] neg_hi:[0,0,1]
	v_mov_b32_e32 v101, v90
	v_pk_add_f32 v[92:93], v[86:87], v[88:89] neg_lo:[0,1] neg_hi:[0,1]
	v_mov_b32_e32 v83, v67
	v_pk_mul_f32 v[66:67], v[100:101], v[100:101]
	v_pk_add_f32 v[74:75], v[86:87], v[88:89]
	v_mul_f32_e32 v87, v100, v90
	v_mov_b32_e32 v86, v66
	v_mov_b32_e32 v66, v67
	v_mov_b32_e32 v67, v87
	v_pk_add_f32 v[114:115], v[110:111], v[112:113]
	v_pk_add_f32 v[88:89], v[86:87], v[66:67] neg_lo:[0,1] neg_hi:[0,1]
	v_pk_add_f32 v[66:67], v[86:87], v[66:67]
	v_pk_add_f32 v[116:117], v[108:109], v[114:115]
	v_pk_add_f32 v[32:33], v[32:33], v[62:63]
	v_mov_b32_e32 v86, v88
	v_mov_b32_e32 v87, v67
	v_pk_mul_f32 v[66:67], v[66:67], v[74:75] op_sel:[1,1] op_sel_hi:[1,0]
	v_mov_b32_e32 v91, v100
	v_pk_add_f32 v[30:31], v[102:103], v[116:117]
	v_pk_add_f32 v[76:77], v[102:103], v[116:117] neg_lo:[0,1] neg_hi:[0,1]
	v_pk_add_f32 v[62:63], v[32:33], v[34:35] neg_lo:[0,1] neg_hi:[0,1]
	v_pk_fma_f32 v[102:103], v[88:89], v[74:75], v[66:67]
	v_pk_fma_f32 v[66:67], v[88:89], v[74:75], v[66:67] op_sel_hi:[0,1,1] neg_lo:[0,0,1] neg_hi:[0,0,1]
	v_pk_add_f32 v[32:33], v[32:33], v[34:35]
	v_pk_mul_f32 v[34:35], v[90:91], v[86:87]
	v_mov_b32_e32 v103, v67
	v_pk_mul_f32 v[66:67], v[100:101], v[86:87]
	v_pk_add_f32 v[34:35], v[34:35], v[34:35] op_sel:[1,0] op_sel_hi:[1,0]
	v_pk_add_f32 v[66:67], v[66:67], v[66:67] op_sel:[0,1] op_sel_hi:[0,1] neg_lo:[0,1] neg_hi:[0,1]
	v_pk_mul_f32 v[34:35], v[34:35], v[32:33] op_sel:[0,1] op_sel_hi:[1,0]
	v_mul_f32_e32 v29, 4.0, v0
	v_pk_fma_f32 v[74:75], v[66:67], v[32:33], v[34:35]
	v_pk_fma_f32 v[32:33], v[66:67], v[32:33], v[34:35] neg_lo:[0,0,1] neg_hi:[0,0,1]
	v_pk_add_f32 v[94:95], v[108:109], v[114:115] neg_lo:[0,1] neg_hi:[0,1]
	v_sin_f32_e32 v32, v29
	v_cos_f32_e32 v34, v29
	v_xor_b32_e32 v97, 0x80000000, v94
	v_mov_b32_e32 v96, v95
	v_pk_add_f32 v[66:67], v[78:79], v[96:97]
	v_pk_add_f32 v[94:95], v[78:79], v[96:97] neg_lo:[0,1] neg_hi:[0,1]
	v_pk_mul_f32 v[78:79], v[32:33], v[66:67] op_sel:[0,1] op_sel_hi:[0,0]
	v_mov_b32_e32 v75, v33
	v_pk_fma_f32 v[86:87], v[34:35], v[66:67], v[78:79]
	v_pk_fma_f32 v[66:67], v[34:35], v[66:67], v[78:79] op_sel_hi:[0,1,1] neg_lo:[0,0,1] neg_hi:[0,0,1]
	v_mov_b32_e32 v35, v32
	v_mov_b32_e32 v33, v34
	v_mov_b32_e32 v87, v67
	v_pk_mul_f32 v[66:67], v[100:101], v[34:35]
	v_pk_mul_f32 v[32:33], v[100:101], v[32:33]
	v_mov_b32_e32 v34, v66
	v_mov_b32_e32 v35, v32
	v_mov_b32_e32 v32, v67
	v_pk_add_f32 v[66:67], v[34:35], v[32:33] neg_lo:[0,1] neg_hi:[0,1]
	v_pk_add_f32 v[32:33], v[34:35], v[32:33]
	v_mov_b32_e32 v34, v66
	v_mov_b32_e32 v35, v33
	v_pk_mul_f32 v[32:33], v[32:33], v[68:69] op_sel:[1,1] op_sel_hi:[1,0]
	v_mul_f32_e32 v29, 0x41000000, v0
	v_pk_fma_f32 v[78:79], v[66:67], v[68:69], v[32:33]
	v_pk_fma_f32 v[32:33], v[66:67], v[68:69], v[32:33] op_sel_hi:[0,1,1] neg_lo:[0,0,1] neg_hi:[0,0,1]
	v_mov_b32_e32 v79, v33
	v_pk_mul_f32 v[32:33], v[100:101], v[34:35]
	v_pk_mul_f32 v[34:35], v[90:91], v[34:35]
	v_mov_b32_e32 v66, v32
	v_mov_b32_e32 v67, v35
	v_pk_mov_b32 v[32:33], v[32:33], v[34:35] op_sel:[1,0]
	v_sin_f32_e32 v88, v29
	v_pk_add_f32 v[34:35], v[66:67], v[32:33] neg_lo:[0,1] neg_hi:[0,1]
	v_pk_add_f32 v[32:33], v[66:67], v[32:33]
	v_mov_b32_e32 v66, v34
	v_mov_b32_e32 v67, v33
	v_pk_mul_f32 v[32:33], v[32:33], v[98:99] op_sel:[1,1] op_sel_hi:[1,0]
	v_cos_f32_e32 v96, v29
	v_pk_fma_f32 v[68:69], v[34:35], v[98:99], v[32:33]
	v_pk_fma_f32 v[32:33], v[34:35], v[98:99], v[32:33] op_sel_hi:[0,1,1] neg_lo:[0,0,1] neg_hi:[0,0,1]
	v_pk_mul_f32 v[34:35], v[90:91], v[66:67]
	v_mov_b32_e32 v69, v33
	v_pk_mul_f32 v[32:33], v[100:101], v[66:67]
	v_pk_add_f32 v[34:35], v[34:35], v[34:35] op_sel:[1,0] op_sel_hi:[1,0]
	v_pk_add_f32 v[32:33], v[32:33], v[32:33] op_sel:[0,1] op_sel_hi:[0,1] neg_lo:[0,1] neg_hi:[0,1]
	v_pk_mul_f32 v[34:35], v[34:35], v[64:65] op_sel:[0,1] op_sel_hi:[1,0]
	v_mul_f32_e32 v0, 0x41400000, v0
	v_pk_fma_f32 v[66:67], v[32:33], v[64:65], v[34:35]
	v_pk_fma_f32 v[32:33], v[32:33], v[64:65], v[34:35] neg_lo:[0,0,1] neg_hi:[0,0,1]
	s_ashr_i32 s53, s52, 31
	v_mov_b32_e32 v67, v33
	v_pk_mul_f32 v[32:33], v[88:89], v[76:77] op_sel:[0,1] op_sel_hi:[0,0]
	v_pk_fma_f32 v[34:35], v[96:97], v[76:77], v[32:33]
	v_pk_fma_f32 v[32:33], v[96:97], v[76:77], v[32:33] op_sel_hi:[0,1,1] neg_lo:[0,0,1] neg_hi:[0,0,1]
	v_mov_b32_e32 v97, v88
	v_mov_b32_e32 v89, v96
	v_mov_b32_e32 v35, v33
	v_pk_mul_f32 v[32:33], v[100:101], v[96:97]
	v_pk_mul_f32 v[64:65], v[100:101], v[88:89]
	v_mov_b32_e32 v76, v32
	v_mov_b32_e32 v77, v64
	v_mov_b32_e32 v64, v33
	v_pk_add_f32 v[32:33], v[76:77], v[64:65] neg_lo:[0,1] neg_hi:[0,1]
	v_pk_add_f32 v[64:65], v[76:77], v[64:65]
	v_mov_b32_e32 v76, v32
	v_mov_b32_e32 v77, v65
	v_pk_mul_f32 v[64:65], v[64:65], v[84:85] op_sel:[1,1] op_sel_hi:[1,0]
	v_cos_f32_e32 v96, v0
	v_pk_fma_f32 v[88:89], v[32:33], v[84:85], v[64:65]
	v_pk_fma_f32 v[32:33], v[32:33], v[84:85], v[64:65] op_sel_hi:[0,1,1] neg_lo:[0,0,1] neg_hi:[0,0,1]
	v_mov_b32_e32 v89, v33
	v_pk_mul_f32 v[32:33], v[100:101], v[76:77]
	v_pk_mul_f32 v[64:65], v[90:91], v[76:77]
	v_mov_b32_e32 v76, v32
	v_mov_b32_e32 v77, v65
	v_pk_mov_b32 v[32:33], v[32:33], v[64:65] op_sel:[1,0]
	s_mov_b32 s10, 0
	v_pk_add_f32 v[64:65], v[76:77], v[32:33] neg_lo:[0,1] neg_hi:[0,1]
	v_pk_add_f32 v[32:33], v[76:77], v[32:33]
	v_mov_b32_e32 v76, v64
	v_mov_b32_e32 v77, v33
	v_pk_mul_f32 v[32:33], v[32:33], v[92:93] op_sel:[1,1] op_sel_hi:[1,0]
	s_nop 0
	v_pk_fma_f32 v[84:85], v[64:65], v[92:93], v[32:33]
	v_pk_fma_f32 v[32:33], v[64:65], v[92:93], v[32:33] op_sel_hi:[0,1,1] neg_lo:[0,0,1] neg_hi:[0,0,1]
	v_pk_mul_f32 v[64:65], v[90:91], v[76:77]
	v_sin_f32_e32 v92, v0
	v_mov_b32_e32 v85, v33
	v_pk_mul_f32 v[32:33], v[100:101], v[76:77]
	v_pk_add_f32 v[64:65], v[64:65], v[64:65] op_sel:[1,0] op_sel_hi:[1,0]
	v_pk_add_f32 v[32:33], v[32:33], v[32:33] op_sel:[0,1] op_sel_hi:[0,1] neg_lo:[0,1] neg_hi:[0,1]
	v_pk_mul_f32 v[64:65], v[64:65], v[62:63] op_sel:[0,1] op_sel_hi:[1,0]
	v_mov_b32_e32 v0, v208
	v_pk_fma_f32 v[76:77], v[32:33], v[62:63], v[64:65]
	v_pk_fma_f32 v[32:33], v[32:33], v[62:63], v[64:65] neg_lo:[0,0,1] neg_hi:[0,0,1]
	s_nop 0
	v_mov_b32_e32 v77, v33
	v_pk_mul_f32 v[32:33], v[92:93], v[94:95] op_sel:[0,1] op_sel_hi:[0,0]
	v_pk_fma_f32 v[62:63], v[96:97], v[94:95], v[32:33]
	v_pk_fma_f32 v[32:33], v[96:97], v[94:95], v[32:33] op_sel_hi:[0,1,1] neg_lo:[0,0,1] neg_hi:[0,0,1]
	v_mov_b32_e32 v97, v92
	v_mov_b32_e32 v93, v96
	v_mov_b32_e32 v63, v33
	v_pk_mul_f32 v[32:33], v[100:101], v[96:97]
	v_pk_mul_f32 v[64:65], v[100:101], v[92:93]
	v_mov_b32_e32 v92, v32
	v_mov_b32_e32 v93, v64
	v_mov_b32_e32 v64, v33
	v_pk_add_f32 v[32:33], v[92:93], v[64:65] neg_lo:[0,1] neg_hi:[0,1]
	v_pk_add_f32 v[64:65], v[92:93], v[64:65]
	v_mov_b32_e32 v92, v32
	v_mov_b32_e32 v93, v65
	v_pk_mul_f32 v[64:65], v[64:65], v[70:71] op_sel:[1,1] op_sel_hi:[1,0]
	s_nop 0
	v_pk_fma_f32 v[94:95], v[32:33], v[70:71], v[64:65]
	v_pk_fma_f32 v[32:33], v[32:33], v[70:71], v[64:65] op_sel_hi:[0,1,1] neg_lo:[0,0,1] neg_hi:[0,0,1]
	v_mov_b32_e32 v95, v33
	v_pk_mul_f32 v[32:33], v[100:101], v[92:93]
	v_pk_mul_f32 v[64:65], v[90:91], v[92:93]
	v_mov_b32_e32 v70, v32
	v_mov_b32_e32 v71, v65
	v_pk_mov_b32 v[32:33], v[32:33], v[64:65] op_sel:[1,0]
	s_nop 0
	v_pk_add_f32 v[64:65], v[70:71], v[32:33] neg_lo:[0,1] neg_hi:[0,1]
	v_pk_add_f32 v[32:33], v[70:71], v[32:33]
	v_mov_b32_e32 v70, v64
	v_mov_b32_e32 v71, v33
	v_pk_mul_f32 v[32:33], v[32:33], v[80:81] op_sel:[1,1] op_sel_hi:[1,0]
	s_nop 0
	v_pk_fma_f32 v[92:93], v[64:65], v[80:81], v[32:33]
	v_pk_fma_f32 v[32:33], v[64:65], v[80:81], v[32:33] op_sel_hi:[0,1,1] neg_lo:[0,0,1] neg_hi:[0,0,1]
	v_pk_mul_f32 v[64:65], v[90:91], v[70:71]
	v_mov_b32_e32 v93, v33
	v_pk_mul_f32 v[32:33], v[100:101], v[70:71]
	v_pk_add_f32 v[64:65], v[64:65], v[64:65] op_sel:[1,0] op_sel_hi:[1,0]
	v_pk_add_f32 v[32:33], v[32:33], v[32:33] op_sel:[0,1] op_sel_hi:[0,1] neg_lo:[0,1] neg_hi:[0,1]
	v_pk_mul_f32 v[64:65], v[64:65], v[72:73] op_sel:[0,1] op_sel_hi:[1,0]
	s_nop 0
	v_pk_fma_f32 v[70:71], v[32:33], v[72:73], v[64:65]
	v_pk_fma_f32 v[32:33], v[32:33], v[72:73], v[64:65] neg_lo:[0,0,1] neg_hi:[0,0,1]
	s_nop 0
	v_mov_b32_e32 v71, v33
	ds_write_b64 v55, v[30:31]
	ds_write_b64 v55, v[82:83] offset:2176
	ds_write_b64 v55, v[102:103] offset:4352
	ds_write_b64 v55, v[74:75] offset:6528
	ds_write_b64 v55, v[86:87] offset:8704
	ds_write_b64 v55, v[78:79] offset:10880
	ds_write_b64 v55, v[68:69] offset:13056
	ds_write_b64 v55, v[66:67] offset:15232
	ds_write_b64 v55, v[34:35] offset:17408
	ds_write_b64 v55, v[88:89] offset:19584
	ds_write_b64 v55, v[84:85] offset:21760
	ds_write_b64 v55, v[76:77] offset:23936
	ds_write_b64 v55, v[62:63] offset:26112
	ds_write_b64 v55, v[94:95] offset:28288
	ds_write_b64 v55, v[92:93] offset:30464
	ds_write_b64 v55, v[70:71] offset:32640
	s_waitcnt lgkmcnt(0)
	s_barrier
	s_nop 0
	v_and_b32_e32 v29, 15, v0
	v_lshlrev_b32_e32 v0, 4, v0
	v_and_b32_e32 v0, 0xffffff00, v0
	v_ashrrev_i32_e32 v30, 1, v0
	v_add_u32_e32 v30, 0, v30
	v_lshlrev_b32_e32 v0, 3, v0
	v_lshlrev_b32_e32 v31, 3, v29
	v_add3_u32 v55, v30, v0, v31
	ds_read_b64 v[32:33], v55
	ds_read_b64 v[34:35], v55 offset:136
	ds_read_b64 v[62:63], v55 offset:272
	ds_read_b64 v[64:65], v55 offset:408
	ds_read_b64 v[66:67], v55 offset:544
	ds_read_b64 v[68:69], v55 offset:680
	ds_read_b64 v[70:71], v55 offset:1088
	ds_read_b64 v[72:73], v55 offset:1224
	ds_read_b64 v[74:75], v55 offset:1632
	ds_read_b64 v[76:77], v55 offset:1768
	ds_read_b64 v[78:79], v55 offset:816
	ds_read_b64 v[80:81], v55 offset:952
	ds_read_b64 v[82:83], v55 offset:1360
	ds_read_b64 v[84:85], v55 offset:1496
	ds_read_b64 v[86:87], v55 offset:1904
	ds_read_b64 v[88:89], v55 offset:2040
	s_waitcnt lgkmcnt(8)
	v_pk_add_f32 v[104:105], v[34:35], v[72:73]
	s_waitcnt lgkmcnt(6)
	v_pk_add_f32 v[92:93], v[66:67], v[74:75]
	v_pk_add_f32 v[106:107], v[68:69], v[76:77]
	v_pk_add_f32 v[66:67], v[66:67], v[74:75] neg_lo:[0,1] neg_hi:[0,1]
	s_waitcnt lgkmcnt(0)
	v_pk_add_f32 v[74:75], v[78:79], v[86:87] neg_lo:[0,1] neg_hi:[0,1]
	v_pk_add_f32 v[68:69], v[68:69], v[76:77] neg_lo:[0,1] neg_hi:[0,1]
	v_pk_add_f32 v[96:97], v[62:63], v[82:83]
	v_pk_add_f32 v[98:99], v[78:79], v[86:87]
	v_pk_add_f32 v[62:63], v[62:63], v[82:83] neg_lo:[0,1] neg_hi:[0,1]
	v_xor_b32_e32 v79, 0x80000000, v74
	v_mov_b32_e32 v78, v75
	v_pk_add_f32 v[34:35], v[34:35], v[72:73] neg_lo:[0,1] neg_hi:[0,1]
	v_xor_b32_e32 v73, 0x80000000, v68
	v_mov_b32_e32 v72, v69
	v_pk_add_f32 v[74:75], v[62:63], v[78:79]
	v_pk_add_f32 v[68:69], v[34:35], v[72:73]
	v_pk_mul_f32 v[82:83], v[74:75], s[24:25] op_sel_hi:[1,0]
	v_pk_mul_f32 v[76:77], v[68:69], s[30:31] op_sel_hi:[1,0]
	v_pk_add_f32 v[90:91], v[32:33], v[70:71]
	v_pk_fma_f32 v[86:87], v[74:75], s[24:25], v[82:83] op_sel:[0,0,1] op_sel_hi:[1,0,0]
	v_pk_fma_f32 v[74:75], v[74:75], s[24:25], v[82:83] op_sel_hi:[1,0,0] neg_lo:[0,0,1] neg_hi:[0,0,1]
	v_pk_fma_f32 v[82:83], v[68:69], s[22:23], v[76:77] op_sel:[0,0,1] op_sel_hi:[1,0,0]
	v_pk_fma_f32 v[68:69], v[68:69], s[22:23], v[76:77] op_sel:[0,0,1] op_sel_hi:[1,0,0] neg_lo:[0,0,1] neg_hi:[0,0,1]
	v_pk_add_f32 v[94:95], v[90:91], v[92:93]
	v_pk_add_f32 v[100:101], v[96:97], v[98:99]
	v_pk_add_f32 v[112:113], v[80:81], v[88:89]
	v_mov_b32_e32 v83, v69
	v_pk_add_f32 v[68:69], v[80:81], v[88:89] neg_lo:[0,1] neg_hi:[0,1]
	v_pk_add_f32 v[88:89], v[90:91], v[92:93] neg_lo:[0,1] neg_hi:[0,1]
	v_pk_add_f32 v[90:91], v[96:97], v[98:99] neg_lo:[0,1] neg_hi:[0,1]
	v_pk_add_f32 v[96:97], v[104:105], v[106:107] neg_lo:[0,1] neg_hi:[0,1]
	v_pk_add_f32 v[110:111], v[64:65], v[84:85]
	v_pk_add_f32 v[64:65], v[64:65], v[84:85] neg_lo:[0,1] neg_hi:[0,1]
	v_xor_b32_e32 v77, 0x80000000, v68
	v_mov_b32_e32 v76, v69
	v_pk_mul_f32 v[98:99], v[96:97], s[24:25] op_sel_hi:[1,0]
	v_pk_add_f32 v[108:109], v[104:105], v[106:107]
	v_pk_add_f32 v[68:69], v[64:65], v[76:77]
	v_pk_fma_f32 v[104:105], v[96:97], s[24:25], v[98:99] op_sel:[0,0,1] op_sel_hi:[1,0,0]
	v_pk_fma_f32 v[96:97], v[96:97], s[24:25], v[98:99] op_sel_hi:[1,0,0] neg_lo:[0,0,1] neg_hi:[0,0,1]
	v_pk_mul_f32 v[80:81], v[68:69], s[22:23] op_sel_hi:[1,0]
	v_mov_b32_e32 v105, v97
	v_pk_add_f32 v[96:97], v[110:111], v[112:113] neg_lo:[0,1] neg_hi:[0,1]
	v_pk_add_f32 v[34:35], v[34:35], v[72:73] neg_lo:[0,1] neg_hi:[0,1]
	v_pk_fma_f32 v[84:85], v[68:69], s[30:31], v[80:81] op_sel:[0,0,1] op_sel_hi:[1,0,0]
	v_pk_fma_f32 v[68:69], v[68:69], s[30:31], v[80:81] op_sel:[0,0,1] op_sel_hi:[1,0,0] neg_lo:[0,0,1] neg_hi:[0,0,1]
	v_mul_f32_e32 v0, 0x3f3504f3, v96
	v_pk_add_f32 v[62:63], v[62:63], v[78:79] neg_lo:[0,1] neg_hi:[0,1]
	v_pk_mul_f32 v[72:73], v[34:35], s[22:23] op_sel_hi:[1,0]
	v_pk_add_f32 v[32:33], v[32:33], v[70:71] neg_lo:[0,1] neg_hi:[0,1]
	v_xor_b32_e32 v71, 0x80000000, v66
	v_mov_b32_e32 v70, v67
	v_mov_b32_e32 v85, v69
	v_pk_fma_f32 v[96:97], v[96:97], s[24:25], v[0:1] op_sel:[1,0,0] op_sel_hi:[1,1,0] neg_lo:[0,0,1] neg_hi:[0,0,1]
	v_mul_f32_e32 v0, 0x3f3504f3, v62
	v_pk_fma_f32 v[78:79], v[34:35], s[30:31], v[72:73] op_sel:[0,0,1] op_sel_hi:[1,0,0]
	v_pk_fma_f32 v[34:35], v[34:35], s[30:31], v[72:73] op_sel:[0,0,1] op_sel_hi:[1,0,0] neg_lo:[0,0,1] neg_hi:[0,0,1]
	v_pk_add_f32 v[66:67], v[32:33], v[70:71]
	v_mov_b32_e32 v87, v75
	v_pk_add_f32 v[68:69], v[82:83], v[84:85] neg_lo:[0,1] neg_hi:[0,1]
	v_xor_b32_e32 v93, 0x80000000, v90
	v_mov_b32_e32 v92, v91
	v_pk_add_f32 v[98:99], v[104:105], v[96:97] neg_lo:[0,1] neg_hi:[0,1]
	v_pk_fma_f32 v[62:63], v[62:63], s[24:25], v[0:1] op_sel:[1,0,0] op_sel_hi:[1,1,0] neg_lo:[0,0,1] neg_hi:[0,0,1]
	v_mov_b32_e32 v79, v35
	v_pk_add_f32 v[34:35], v[64:65], v[76:77] neg_lo:[0,1] neg_hi:[0,1]
	v_cvt_f32_ubyte0_e32 v0, v29
	v_pk_add_f32 v[74:75], v[66:67], v[86:87] neg_lo:[0,1] neg_hi:[0,1]
	v_xor_b32_e32 v81, 0x80000000, v68
	v_mov_b32_e32 v80, v69
	v_pk_add_f32 v[90:91], v[88:89], v[92:93] neg_lo:[0,1] neg_hi:[0,1]
	v_xor_b32_e32 v107, 0x80000000, v98
	v_mov_b32_e32 v106, v99
	v_pk_mul_f32 v[64:65], v[34:35], s[30:31]
	v_mul_f32_e32 v0, 0x3b800000, v0
	v_pk_add_f32 v[68:69], v[74:75], v[80:81]
	v_pk_add_f32 v[98:99], v[90:91], v[106:107]
	v_pk_fma_f32 v[34:35], v[34:35], s[22:23], v[64:65] op_sel:[0,0,1] op_sel_hi:[1,0,0] neg_lo:[1,0,0] neg_hi:[1,0,0]
	v_pk_add_f32 v[74:75], v[74:75], v[80:81] neg_lo:[0,1] neg_hi:[0,1]
	v_pk_add_f32 v[80:81], v[90:91], v[106:107] neg_lo:[0,1] neg_hi:[0,1]
	v_sin_f32_e32 v90, v0
	v_pk_add_f32 v[102:103], v[94:95], v[100:101]
	v_pk_add_f32 v[64:65], v[78:79], v[34:35] neg_lo:[0,1] neg_hi:[0,1]
	v_pk_add_f32 v[34:35], v[78:79], v[34:35]
	v_pk_add_f32 v[78:79], v[94:95], v[100:101] neg_lo:[0,1] neg_hi:[0,1]
	v_cos_f32_e32 v100, v0
	v_pk_add_f32 v[32:33], v[32:33], v[70:71] neg_lo:[0,1] neg_hi:[0,1]
	v_pk_add_f32 v[66:67], v[66:67], v[86:87]
	v_pk_add_f32 v[82:83], v[82:83], v[84:85]
	v_pk_add_f32 v[70:71], v[32:33], v[62:63] neg_lo:[0,1] neg_hi:[0,1]
	v_xor_b32_e32 v73, 0x80000000, v64
	v_mov_b32_e32 v72, v65
	v_pk_add_f32 v[84:85], v[66:67], v[82:83] neg_lo:[0,1] neg_hi:[0,1]
	v_pk_add_f32 v[66:67], v[66:67], v[82:83]
	v_pk_add_f32 v[64:65], v[70:71], v[72:73]
	v_pk_add_f32 v[70:71], v[70:71], v[72:73] neg_lo:[0,1] neg_hi:[0,1]
	v_pk_mul_f32 v[72:73], v[90:91], v[66:67] op_sel:[0,1] op_sel_hi:[0,0]
	v_pk_add_f32 v[86:87], v[88:89], v[92:93]
	v_pk_add_f32 v[88:89], v[104:105], v[96:97]
	v_pk_fma_f32 v[82:83], v[100:101], v[66:67], v[72:73]
	v_pk_fma_f32 v[66:67], v[100:101], v[66:67], v[72:73] op_sel_hi:[0,1,1] neg_lo:[0,0,1] neg_hi:[0,0,1]
	v_mov_b32_e32 v101, v90
	v_pk_add_f32 v[92:93], v[86:87], v[88:89] neg_lo:[0,1] neg_hi:[0,1]
	v_mov_b32_e32 v83, v67
	v_pk_mul_f32 v[66:67], v[100:101], v[100:101]
	v_pk_add_f32 v[72:73], v[86:87], v[88:89]
	v_mul_f32_e32 v87, v100, v90
	v_mov_b32_e32 v86, v66
	v_mov_b32_e32 v66, v67
	v_mov_b32_e32 v67, v87
	v_pk_add_f32 v[114:115], v[110:111], v[112:113]
	v_pk_add_f32 v[88:89], v[86:87], v[66:67] neg_lo:[0,1] neg_hi:[0,1]
	v_pk_add_f32 v[66:67], v[86:87], v[66:67]
	v_pk_add_f32 v[116:117], v[108:109], v[114:115]
	v_pk_add_f32 v[32:33], v[32:33], v[62:63]
	v_mov_b32_e32 v86, v88
	v_mov_b32_e32 v87, v67
	v_pk_mul_f32 v[66:67], v[66:67], v[72:73] op_sel:[1,1] op_sel_hi:[1,0]
	v_mov_b32_e32 v91, v100
	v_pk_add_f32 v[30:31], v[102:103], v[116:117]
	v_pk_add_f32 v[76:77], v[102:103], v[116:117] neg_lo:[0,1] neg_hi:[0,1]
	v_pk_add_f32 v[62:63], v[32:33], v[34:35] neg_lo:[0,1] neg_hi:[0,1]
	v_pk_fma_f32 v[102:103], v[88:89], v[72:73], v[66:67]
	v_pk_fma_f32 v[66:67], v[88:89], v[72:73], v[66:67] op_sel_hi:[0,1,1] neg_lo:[0,0,1] neg_hi:[0,0,1]
	v_pk_add_f32 v[32:33], v[32:33], v[34:35]
	v_pk_mul_f32 v[34:35], v[90:91], v[86:87]
	v_mov_b32_e32 v103, v67
	v_pk_mul_f32 v[66:67], v[100:101], v[86:87]
	v_pk_add_f32 v[34:35], v[34:35], v[34:35] op_sel:[1,0] op_sel_hi:[1,0]
	v_pk_add_f32 v[66:67], v[66:67], v[66:67] op_sel:[0,1] op_sel_hi:[0,1] neg_lo:[0,1] neg_hi:[0,1]
	v_pk_mul_f32 v[34:35], v[34:35], v[32:33] op_sel:[0,1] op_sel_hi:[1,0]
	v_mul_f32_e32 v29, 4.0, v0
	v_pk_fma_f32 v[72:73], v[66:67], v[32:33], v[34:35]
	v_pk_fma_f32 v[32:33], v[66:67], v[32:33], v[34:35] neg_lo:[0,0,1] neg_hi:[0,0,1]
	v_pk_add_f32 v[94:95], v[108:109], v[114:115] neg_lo:[0,1] neg_hi:[0,1]
	v_sin_f32_e32 v32, v29
	v_cos_f32_e32 v34, v29
	v_xor_b32_e32 v97, 0x80000000, v94
	v_mov_b32_e32 v96, v95
	v_pk_add_f32 v[66:67], v[78:79], v[96:97]
	v_pk_add_f32 v[94:95], v[78:79], v[96:97] neg_lo:[0,1] neg_hi:[0,1]
	v_pk_mul_f32 v[78:79], v[32:33], v[66:67] op_sel:[0,1] op_sel_hi:[0,0]
	v_mov_b32_e32 v73, v33
	v_pk_fma_f32 v[86:87], v[34:35], v[66:67], v[78:79]
	v_pk_fma_f32 v[66:67], v[34:35], v[66:67], v[78:79] op_sel_hi:[0,1,1] neg_lo:[0,0,1] neg_hi:[0,0,1]
	v_mov_b32_e32 v35, v32
	v_mov_b32_e32 v33, v34
	v_mov_b32_e32 v87, v67
	v_pk_mul_f32 v[66:67], v[100:101], v[34:35]
	v_pk_mul_f32 v[32:33], v[100:101], v[32:33]
	v_mov_b32_e32 v34, v66
	v_mov_b32_e32 v35, v32
	v_mov_b32_e32 v32, v67
	v_pk_add_f32 v[66:67], v[34:35], v[32:33] neg_lo:[0,1] neg_hi:[0,1]
	v_pk_add_f32 v[32:33], v[34:35], v[32:33]
	v_mov_b32_e32 v34, v66
	v_mov_b32_e32 v35, v33
	v_pk_mul_f32 v[32:33], v[32:33], v[68:69] op_sel:[1,1] op_sel_hi:[1,0]
	v_mul_f32_e32 v29, 0x41000000, v0
	v_pk_fma_f32 v[78:79], v[66:67], v[68:69], v[32:33]
	v_pk_fma_f32 v[32:33], v[66:67], v[68:69], v[32:33] op_sel_hi:[0,1,1] neg_lo:[0,0,1] neg_hi:[0,0,1]
	v_mov_b32_e32 v79, v33
	v_pk_mul_f32 v[32:33], v[100:101], v[34:35]
	v_pk_mul_f32 v[34:35], v[90:91], v[34:35]
	v_mov_b32_e32 v66, v32
	v_mov_b32_e32 v67, v35
	v_pk_mov_b32 v[32:33], v[32:33], v[34:35] op_sel:[1,0]
	v_sin_f32_e32 v88, v29
	v_pk_add_f32 v[34:35], v[66:67], v[32:33] neg_lo:[0,1] neg_hi:[0,1]
	v_pk_add_f32 v[32:33], v[66:67], v[32:33]
	v_mov_b32_e32 v66, v34
	v_mov_b32_e32 v67, v33
	v_pk_mul_f32 v[32:33], v[32:33], v[98:99] op_sel:[1,1] op_sel_hi:[1,0]
	v_cos_f32_e32 v96, v29
	v_pk_fma_f32 v[68:69], v[34:35], v[98:99], v[32:33]
	v_pk_fma_f32 v[32:33], v[34:35], v[98:99], v[32:33] op_sel_hi:[0,1,1] neg_lo:[0,0,1] neg_hi:[0,0,1]
	v_pk_mul_f32 v[34:35], v[90:91], v[66:67]
	v_mov_b32_e32 v69, v33
	v_pk_mul_f32 v[32:33], v[100:101], v[66:67]
	v_pk_add_f32 v[34:35], v[34:35], v[34:35] op_sel:[1,0] op_sel_hi:[1,0]
	v_pk_add_f32 v[32:33], v[32:33], v[32:33] op_sel:[0,1] op_sel_hi:[0,1] neg_lo:[0,1] neg_hi:[0,1]
	v_pk_mul_f32 v[34:35], v[34:35], v[64:65] op_sel:[0,1] op_sel_hi:[1,0]
	v_mul_f32_e32 v0, 0x41400000, v0
	v_pk_fma_f32 v[66:67], v[32:33], v[64:65], v[34:35]
	v_pk_fma_f32 v[32:33], v[32:33], v[64:65], v[34:35] neg_lo:[0,0,1] neg_hi:[0,0,1]
	s_nop 0
	v_mov_b32_e32 v67, v33
	v_pk_mul_f32 v[32:33], v[88:89], v[76:77] op_sel:[0,1] op_sel_hi:[0,0]
	v_pk_fma_f32 v[34:35], v[96:97], v[76:77], v[32:33]
	v_pk_fma_f32 v[32:33], v[96:97], v[76:77], v[32:33] op_sel_hi:[0,1,1] neg_lo:[0,0,1] neg_hi:[0,0,1]
	v_mov_b32_e32 v97, v88
	v_mov_b32_e32 v89, v96
	v_mov_b32_e32 v35, v33
	v_pk_mul_f32 v[32:33], v[100:101], v[96:97]
	v_pk_mul_f32 v[64:65], v[100:101], v[88:89]
	v_mov_b32_e32 v76, v32
	v_mov_b32_e32 v77, v64
	v_mov_b32_e32 v64, v33
	v_pk_add_f32 v[32:33], v[76:77], v[64:65] neg_lo:[0,1] neg_hi:[0,1]
	v_pk_add_f32 v[64:65], v[76:77], v[64:65]
	v_mov_b32_e32 v76, v32
	v_mov_b32_e32 v77, v65
	v_pk_mul_f32 v[64:65], v[64:65], v[84:85] op_sel:[1,1] op_sel_hi:[1,0]
	v_cos_f32_e32 v96, v0
	v_pk_fma_f32 v[88:89], v[32:33], v[84:85], v[64:65]
	v_pk_fma_f32 v[32:33], v[32:33], v[84:85], v[64:65] op_sel_hi:[0,1,1] neg_lo:[0,0,1] neg_hi:[0,0,1]
	v_mov_b32_e32 v89, v33
	v_pk_mul_f32 v[32:33], v[100:101], v[76:77]
	v_pk_mul_f32 v[64:65], v[90:91], v[76:77]
	v_mov_b32_e32 v76, v32
	v_mov_b32_e32 v77, v65
	v_pk_mov_b32 v[32:33], v[32:33], v[64:65] op_sel:[1,0]
	s_nop 0
	v_pk_add_f32 v[64:65], v[76:77], v[32:33] neg_lo:[0,1] neg_hi:[0,1]
	v_pk_add_f32 v[32:33], v[76:77], v[32:33]
	v_mov_b32_e32 v76, v64
	v_mov_b32_e32 v77, v33
	v_pk_mul_f32 v[32:33], v[32:33], v[92:93] op_sel:[1,1] op_sel_hi:[1,0]
	s_nop 0
	v_pk_fma_f32 v[84:85], v[64:65], v[92:93], v[32:33]
	v_pk_fma_f32 v[32:33], v[64:65], v[92:93], v[32:33] op_sel_hi:[0,1,1] neg_lo:[0,0,1] neg_hi:[0,0,1]
	v_pk_mul_f32 v[64:65], v[90:91], v[76:77]
	v_sin_f32_e32 v92, v0
	v_mov_b32_e32 v85, v33
	v_pk_mul_f32 v[32:33], v[100:101], v[76:77]
	v_pk_add_f32 v[64:65], v[64:65], v[64:65] op_sel:[1,0] op_sel_hi:[1,0]
	v_pk_add_f32 v[32:33], v[32:33], v[32:33] op_sel:[0,1] op_sel_hi:[0,1] neg_lo:[0,1] neg_hi:[0,1]
	v_pk_mul_f32 v[64:65], v[64:65], v[62:63] op_sel:[0,1] op_sel_hi:[1,0]
	v_mov_b32_e32 v0, v208
	v_pk_fma_f32 v[76:77], v[32:33], v[62:63], v[64:65]
	v_pk_fma_f32 v[32:33], v[32:33], v[62:63], v[64:65] neg_lo:[0,0,1] neg_hi:[0,0,1]
	s_nop 0
	v_mov_b32_e32 v77, v33
	v_pk_mul_f32 v[32:33], v[92:93], v[94:95] op_sel:[0,1] op_sel_hi:[0,0]
	v_pk_fma_f32 v[62:63], v[96:97], v[94:95], v[32:33]
	v_pk_fma_f32 v[32:33], v[96:97], v[94:95], v[32:33] op_sel_hi:[0,1,1] neg_lo:[0,0,1] neg_hi:[0,0,1]
	v_mov_b32_e32 v97, v92
	v_mov_b32_e32 v93, v96
	v_mov_b32_e32 v63, v33
	v_pk_mul_f32 v[32:33], v[100:101], v[96:97]
	v_pk_mul_f32 v[64:65], v[100:101], v[92:93]
	v_mov_b32_e32 v92, v32
	v_mov_b32_e32 v93, v64
	v_mov_b32_e32 v64, v33
	v_pk_add_f32 v[32:33], v[92:93], v[64:65] neg_lo:[0,1] neg_hi:[0,1]
	v_pk_add_f32 v[64:65], v[92:93], v[64:65]
	v_mov_b32_e32 v92, v32
	v_mov_b32_e32 v93, v65
	v_pk_mul_f32 v[64:65], v[64:65], v[74:75] op_sel:[1,1] op_sel_hi:[1,0]
	s_nop 0
	v_pk_fma_f32 v[94:95], v[32:33], v[74:75], v[64:65]
	v_pk_fma_f32 v[32:33], v[32:33], v[74:75], v[64:65] op_sel_hi:[0,1,1] neg_lo:[0,0,1] neg_hi:[0,0,1]
	v_mov_b32_e32 v95, v33
	v_pk_mul_f32 v[32:33], v[100:101], v[92:93]
	v_pk_mul_f32 v[64:65], v[90:91], v[92:93]
	v_mov_b32_e32 v74, v32
	v_mov_b32_e32 v75, v65
	v_pk_mov_b32 v[32:33], v[32:33], v[64:65] op_sel:[1,0]
	s_nop 0
	v_pk_add_f32 v[64:65], v[74:75], v[32:33] neg_lo:[0,1] neg_hi:[0,1]
	v_pk_add_f32 v[32:33], v[74:75], v[32:33]
	v_mov_b32_e32 v74, v64
	v_mov_b32_e32 v75, v33
	v_pk_mul_f32 v[32:33], v[32:33], v[80:81] op_sel:[1,1] op_sel_hi:[1,0]
	s_nop 0
	v_pk_fma_f32 v[92:93], v[64:65], v[80:81], v[32:33]
	v_pk_fma_f32 v[32:33], v[64:65], v[80:81], v[32:33] op_sel_hi:[0,1,1] neg_lo:[0,0,1] neg_hi:[0,0,1]
	v_pk_mul_f32 v[64:65], v[90:91], v[74:75]
	v_mov_b32_e32 v93, v33
	v_pk_mul_f32 v[32:33], v[100:101], v[74:75]
	v_pk_add_f32 v[64:65], v[64:65], v[64:65] op_sel:[1,0] op_sel_hi:[1,0]
	v_pk_add_f32 v[32:33], v[32:33], v[32:33] op_sel:[0,1] op_sel_hi:[0,1] neg_lo:[0,1] neg_hi:[0,1]
	v_pk_mul_f32 v[64:65], v[64:65], v[70:71] op_sel:[0,1] op_sel_hi:[1,0]
	s_nop 0
	v_pk_fma_f32 v[74:75], v[32:33], v[70:71], v[64:65]
	v_pk_fma_f32 v[32:33], v[32:33], v[70:71], v[64:65] neg_lo:[0,0,1] neg_hi:[0,0,1]
	s_nop 0
	v_mov_b32_e32 v75, v33
	ds_write_b64 v55, v[30:31]
	ds_write_b64 v55, v[82:83] offset:136
	ds_write_b64 v55, v[102:103] offset:272
	ds_write_b64 v55, v[72:73] offset:408
	ds_write_b64 v55, v[86:87] offset:544
	ds_write_b64 v55, v[78:79] offset:680
	ds_write_b64 v55, v[68:69] offset:816
	ds_write_b64 v55, v[66:67] offset:952
	ds_write_b64 v55, v[34:35] offset:1088
	ds_write_b64 v55, v[88:89] offset:1224
	ds_write_b64 v55, v[84:85] offset:1360
	ds_write_b64 v55, v[76:77] offset:1496
	ds_write_b64 v55, v[62:63] offset:1632
	ds_write_b64 v55, v[94:95] offset:1768
	ds_write_b64 v55, v[92:93] offset:1904
	ds_write_b64 v55, v[74:75] offset:2040
	s_waitcnt lgkmcnt(0)
	s_nop 0
	v_lshlrev_b32_e32 v29, 4, v0
	v_ashrrev_i32_e32 v29, 1, v29
	v_lshlrev_b32_e32 v0, 7, v0
	v_add3_u32 v29, 0, v29, v0
	ds_read_b64 v[30:31], v29
	ds_read_b64 v[32:33], v29 offset:8
	ds_read_b64 v[62:63], v29 offset:16
	ds_read_b64 v[64:65], v29 offset:24
	ds_read_b64 v[66:67], v29 offset:64
	ds_read_b64 v[68:69], v29 offset:72
	ds_read_b64 v[70:71], v29 offset:32
	ds_read_b64 v[72:73], v29 offset:40
	ds_read_b64 v[74:75], v29 offset:48
	ds_read_b64 v[76:77], v29 offset:56
	ds_read_b64 v[78:79], v29 offset:96
	ds_read_b64 v[80:81], v29 offset:104
	ds_read_b64 v[82:83], v29 offset:80
	ds_read_b64 v[84:85], v29 offset:88
	ds_read_b64 v[86:87], v29 offset:112
	ds_read_b64 v[88:89], v29 offset:120
	s_waitcnt lgkmcnt(10)
	v_pk_add_f32 v[34:35], v[30:31], v[66:67]
	v_pk_add_f32 v[30:31], v[30:31], v[66:67] neg_lo:[0,1] neg_hi:[0,1]
	s_waitcnt lgkmcnt(4)
	v_pk_add_f32 v[66:67], v[70:71], v[78:79]
	v_pk_add_f32 v[70:71], v[70:71], v[78:79] neg_lo:[0,1] neg_hi:[0,1]
	s_nop 0
	v_xor_b32_e32 v79, 0x80000000, v70
	v_mov_b32_e32 v78, v71
	v_pk_add_f32 v[70:71], v[34:35], v[66:67]
	v_pk_add_f32 v[34:35], v[34:35], v[66:67] neg_lo:[0,1] neg_hi:[0,1]
	v_pk_add_f32 v[66:67], v[30:31], v[78:79]
	v_pk_add_f32 v[30:31], v[30:31], v[78:79] neg_lo:[0,1] neg_hi:[0,1]
	v_pk_add_f32 v[78:79], v[32:33], v[68:69]
	v_pk_add_f32 v[32:33], v[32:33], v[68:69] neg_lo:[0,1] neg_hi:[0,1]
	v_pk_add_f32 v[68:69], v[72:73], v[80:81]
	v_pk_add_f32 v[72:73], v[72:73], v[80:81] neg_lo:[0,1] neg_hi:[0,1]
	s_nop 0
	v_xor_b32_e32 v81, 0x80000000, v72
	v_mov_b32_e32 v80, v73
	v_pk_add_f32 v[72:73], v[78:79], v[68:69]
	v_pk_add_f32 v[68:69], v[78:79], v[68:69] neg_lo:[0,1] neg_hi:[0,1]
	v_pk_add_f32 v[78:79], v[32:33], v[80:81]
	v_pk_add_f32 v[32:33], v[32:33], v[80:81] neg_lo:[0,1] neg_hi:[0,1]
	s_waitcnt lgkmcnt(2)
	v_pk_add_f32 v[80:81], v[62:63], v[82:83]
	v_pk_add_f32 v[62:63], v[62:63], v[82:83] neg_lo:[0,1] neg_hi:[0,1]
	s_waitcnt lgkmcnt(0)
	v_pk_add_f32 v[82:83], v[74:75], v[86:87]
	v_pk_add_f32 v[74:75], v[74:75], v[86:87] neg_lo:[0,1] neg_hi:[0,1]
	s_nop 0
	v_xor_b32_e32 v87, 0x80000000, v74
	v_mov_b32_e32 v86, v75
	v_pk_add_f32 v[74:75], v[80:81], v[82:83]
	v_pk_add_f32 v[80:81], v[80:81], v[82:83] neg_lo:[0,1] neg_hi:[0,1]
	v_pk_add_f32 v[82:83], v[62:63], v[86:87]
	v_pk_add_f32 v[62:63], v[62:63], v[86:87] neg_lo:[0,1] neg_hi:[0,1]
	v_pk_add_f32 v[86:87], v[64:65], v[84:85]
	v_pk_add_f32 v[64:65], v[64:65], v[84:85] neg_lo:[0,1] neg_hi:[0,1]
	v_pk_add_f32 v[84:85], v[76:77], v[88:89]
	v_pk_add_f32 v[76:77], v[76:77], v[88:89] neg_lo:[0,1] neg_hi:[0,1]
	v_mul_f32_e32 v0, 0x3f3504f3, v62
	v_xor_b32_e32 v89, 0x80000000, v76
	v_mov_b32_e32 v88, v77
	v_pk_add_f32 v[76:77], v[86:87], v[84:85]
	v_pk_add_f32 v[84:85], v[86:87], v[84:85] neg_lo:[0,1] neg_hi:[0,1]
	v_pk_add_f32 v[86:87], v[64:65], v[88:89]
	v_pk_add_f32 v[64:65], v[64:65], v[88:89] neg_lo:[0,1] neg_hi:[0,1]
	v_pk_mul_f32 v[88:89], v[78:79], s[30:31] op_sel_hi:[1,0]
	v_pk_fma_f32 v[62:63], v[62:63], s[24:25], v[0:1] op_sel:[1,0,0] op_sel_hi:[1,1,0] neg_lo:[0,0,1] neg_hi:[0,0,1]
	v_pk_fma_f32 v[90:91], v[78:79], s[22:23], v[88:89] op_sel:[0,0,1] op_sel_hi:[1,0,0]
	v_pk_fma_f32 v[78:79], v[78:79], s[22:23], v[88:89] op_sel:[0,0,1] op_sel_hi:[1,0,0] neg_lo:[0,0,1] neg_hi:[0,0,1]
	v_mul_f32_e32 v0, 0x3f3504f3, v84
	v_mov_b32_e32 v91, v79
	v_pk_mul_f32 v[78:79], v[68:69], s[24:25] op_sel_hi:[1,0]
	s_nop 0
	v_pk_fma_f32 v[88:89], v[68:69], s[24:25], v[78:79] op_sel:[0,0,1] op_sel_hi:[1,0,0]
	v_pk_fma_f32 v[68:69], v[68:69], s[24:25], v[78:79] op_sel_hi:[1,0,0] neg_lo:[0,0,1] neg_hi:[0,0,1]
	s_nop 0
	v_mov_b32_e32 v89, v69
	v_pk_mul_f32 v[68:69], v[32:33], s[22:23] op_sel_hi:[1,0]
	s_nop 0
	v_pk_fma_f32 v[78:79], v[32:33], s[30:31], v[68:69] op_sel:[0,0,1] op_sel_hi:[1,0,0]
	v_pk_fma_f32 v[32:33], v[32:33], s[30:31], v[68:69] op_sel:[0,0,1] op_sel_hi:[1,0,0] neg_lo:[0,0,1] neg_hi:[0,0,1]
	s_nop 0
	v_mov_b32_e32 v79, v33
	v_pk_mul_f32 v[32:33], v[82:83], s[24:25] op_sel_hi:[1,0]
	s_nop 0
	v_pk_fma_f32 v[68:69], v[82:83], s[24:25], v[32:33] op_sel:[0,0,1] op_sel_hi:[1,0,0]
	v_pk_fma_f32 v[32:33], v[82:83], s[24:25], v[32:33] op_sel_hi:[1,0,0] neg_lo:[0,0,1] neg_hi:[0,0,1]
	s_nop 0
	v_mov_b32_e32 v69, v33
	v_xor_b32_e32 v33, 0x80000000, v80
	v_mov_b32_e32 v32, v81
	v_pk_mul_f32 v[80:81], v[86:87], s[22:23] op_sel_hi:[1,0]
	s_nop 0
	v_pk_fma_f32 v[82:83], v[86:87], s[30:31], v[80:81] op_sel:[0,0,1] op_sel_hi:[1,0,0]
	v_pk_fma_f32 v[80:81], v[86:87], s[30:31], v[80:81] op_sel:[0,0,1] op_sel_hi:[1,0,0] neg_lo:[0,0,1] neg_hi:[0,0,1]
	s_nop 0
	v_mov_b32_e32 v83, v81
	v_pk_fma_f32 v[80:81], v[84:85], s[24:25], v[0:1] op_sel:[1,0,0] op_sel_hi:[1,1,0] neg_lo:[0,0,1] neg_hi:[0,0,1]
	v_pk_mul_f32 v[84:85], v[64:65], s[30:31]
	v_mul_f32_e32 v0, v7, v138
	v_pk_fma_f32 v[64:65], v[64:65], s[22:23], v[84:85] op_sel:[0,0,1] op_sel_hi:[1,0,0] neg_lo:[1,0,0] neg_hi:[1,0,0]
	v_pk_add_f32 v[84:85], v[70:71], v[74:75]
	v_pk_add_f32 v[70:71], v[70:71], v[74:75] neg_lo:[0,1] neg_hi:[0,1]
	v_pk_add_f32 v[74:75], v[72:73], v[76:77]
	v_pk_add_f32 v[72:73], v[72:73], v[76:77] neg_lo:[0,1] neg_hi:[0,1]
	s_nop 0
	v_xor_b32_e32 v77, 0x80000000, v72
	v_mov_b32_e32 v76, v73
	v_pk_add_f32 v[72:73], v[84:85], v[74:75]
	v_pk_add_f32 v[74:75], v[84:85], v[74:75] neg_lo:[0,1] neg_hi:[0,1]
	v_pk_add_f32 v[84:85], v[70:71], v[76:77]
	v_pk_add_f32 v[70:71], v[70:71], v[76:77] neg_lo:[0,1] neg_hi:[0,1]
	v_pk_add_f32 v[76:77], v[66:67], v[68:69]
	v_pk_add_f32 v[66:67], v[66:67], v[68:69] neg_lo:[0,1] neg_hi:[0,1]
	v_pk_add_f32 v[68:69], v[90:91], v[82:83]
	v_pk_add_f32 v[82:83], v[90:91], v[82:83] neg_lo:[0,1] neg_hi:[0,1]
	s_nop 0
	v_xor_b32_e32 v87, 0x80000000, v82
	v_mov_b32_e32 v86, v83
	v_pk_add_f32 v[82:83], v[76:77], v[68:69]
	v_pk_add_f32 v[68:69], v[76:77], v[68:69] neg_lo:[0,1] neg_hi:[0,1]
	v_pk_add_f32 v[76:77], v[66:67], v[86:87]
	v_pk_add_f32 v[66:67], v[66:67], v[86:87] neg_lo:[0,1] neg_hi:[0,1]
	v_pk_add_f32 v[86:87], v[34:35], v[32:33]
	v_pk_add_f32 v[32:33], v[34:35], v[32:33] neg_lo:[0,1] neg_hi:[0,1]
	v_pk_add_f32 v[34:35], v[88:89], v[80:81]
	v_pk_add_f32 v[80:81], v[88:89], v[80:81] neg_lo:[0,1] neg_hi:[0,1]
	s_nop 0
	v_xor_b32_e32 v89, 0x80000000, v80
	v_mov_b32_e32 v88, v81
	v_pk_add_f32 v[80:81], v[86:87], v[34:35]
	v_pk_add_f32 v[34:35], v[86:87], v[34:35] neg_lo:[0,1] neg_hi:[0,1]
	v_pk_add_f32 v[86:87], v[32:33], v[88:89]
	v_pk_add_f32 v[32:33], v[32:33], v[88:89] neg_lo:[0,1] neg_hi:[0,1]
	v_pk_add_f32 v[88:89], v[30:31], v[62:63]
	v_pk_add_f32 v[30:31], v[30:31], v[62:63] neg_lo:[0,1] neg_hi:[0,1]
	v_pk_add_f32 v[62:63], v[78:79], v[64:65]
	v_pk_add_f32 v[64:65], v[78:79], v[64:65] neg_lo:[0,1] neg_hi:[0,1]
	s_nop 0
	v_xor_b32_e32 v79, 0x80000000, v64
	v_mov_b32_e32 v78, v65
	v_pk_add_f32 v[64:65], v[88:89], v[62:63]
	v_pk_add_f32 v[62:63], v[88:89], v[62:63] neg_lo:[0,1] neg_hi:[0,1]
	v_pk_add_f32 v[88:89], v[30:31], v[78:79]
	v_pk_add_f32 v[30:31], v[30:31], v[78:79] neg_lo:[0,1] neg_hi:[0,1]
	ds_write_b64 v29, v[72:73]
	ds_write_b64 v29, v[82:83] offset:8
	ds_write_b64 v29, v[80:81] offset:16
	ds_write_b64 v29, v[64:65] offset:24
	ds_write_b64 v29, v[84:85] offset:32
	ds_write_b64 v29, v[76:77] offset:40
	ds_write_b64 v29, v[86:87] offset:48
	ds_write_b64 v29, v[88:89] offset:56
	ds_write_b64 v29, v[74:75] offset:64
	ds_write_b64 v29, v[68:69] offset:72
	ds_write_b64 v29, v[34:35] offset:80
	ds_write_b64 v29, v[62:63] offset:88
	ds_write_b64 v29, v[70:71] offset:96
	ds_write_b64 v29, v[66:67] offset:104
	ds_write_b64 v29, v[32:33] offset:112
	ds_write_b64 v29, v[30:31] offset:120
	v_cos_f32_e32 v30, v0
	v_sin_f32_e32 v32, v0
	v_add_u32_e32 v0, s52, v48
	v_ashrrev_i32_e32 v29, 4, v0
	v_lshlrev_b32_e32 v29, 3, v29
	v_lshlrev_b32_e32 v55, 3, v0
	v_add3_u32 v0, s35, v29, v55
	v_mul_f32_e32 v29, v7, v141
	v_cos_f32_e32 v31, v29
	v_sin_f32_e32 v33, v29
	v_add_u32_e32 v29, s52, v140
	v_ashrrev_i32_e32 v29, 4, v29
	v_lshlrev_b32_e32 v29, 3, v29
	v_add3_u32 v165, s35, v29, v55
	v_mul_f32_e32 v29, v7, v143
	v_cos_f32_e32 v34, v29
	v_sin_f32_e32 v62, v29
	v_add_u32_e32 v29, s52, v142
	v_ashrrev_i32_e32 v29, 4, v29
	v_lshlrev_b32_e32 v29, 3, v29
	v_add3_u32 v166, s35, v29, v55
	v_mul_f32_e32 v29, v7, v145
	v_cos_f32_e32 v35, v29
	v_sin_f32_e32 v63, v29
	v_add_u32_e32 v29, s52, v144
	v_ashrrev_i32_e32 v29, 4, v29
	v_lshlrev_b32_e32 v29, 3, v29
	v_add3_u32 v167, s35, v29, v55
	v_mul_f32_e32 v29, v7, v147
	v_cos_f32_e32 v64, v29
	v_sin_f32_e32 v66, v29
	v_add_u32_e32 v29, s52, v146
	v_ashrrev_i32_e32 v29, 4, v29
	v_lshlrev_b32_e32 v29, 3, v29
	v_add3_u32 v168, s35, v29, v55
	v_mul_f32_e32 v29, v7, v149
	v_cos_f32_e32 v65, v29
	v_sin_f32_e32 v67, v29
	v_add_u32_e32 v29, s52, v148
	v_ashrrev_i32_e32 v29, 4, v29
	v_lshlrev_b32_e32 v29, 3, v29
	v_add3_u32 v169, s35, v29, v55
	v_mul_f32_e32 v29, v7, v151
	v_mul_f32_e32 v7, v7, v153
	v_cos_f32_e32 v68, v29
	v_sin_f32_e32 v70, v29
	v_cos_f32_e32 v69, v7
	v_sin_f32_e32 v71, v7
	v_add_u32_e32 v29, s52, v150
	v_add_u32_e32 v7, s52, v152
	v_ashrrev_i32_e32 v29, 4, v29
	v_ashrrev_i32_e32 v7, 4, v7
	v_lshlrev_b32_e32 v29, 3, v29
	v_lshlrev_b32_e32 v7, 3, v7
	v_add3_u32 v174, s35, v29, v55
	v_add3_u32 v175, s35, v7, v55
	v_mov_b32_e32 v55, v54
	v_mov_b32_e32 v7, v6
	v_mov_b32_e32 v29, v28
	v_mov_b32_e32 v72, v30
	v_mov_b32_e32 v73, v30
	v_mov_b32_e32 v74, v32
	v_mov_b32_e32 v75, v32
	v_mov_b32_e32 v76, v31
	v_mov_b32_e32 v77, v31
	v_mov_b32_e32 v78, v33
	v_mov_b32_e32 v79, v33
	v_mov_b32_e32 v80, v34
	v_mov_b32_e32 v81, v34
	v_mov_b32_e32 v82, v62
	v_mov_b32_e32 v83, v62
	v_mov_b32_e32 v84, v35
	v_mov_b32_e32 v85, v35
	v_mov_b32_e32 v86, v63
	v_mov_b32_e32 v87, v63
	v_mov_b32_e32 v88, v64
	v_mov_b32_e32 v89, v64
	v_mov_b32_e32 v90, v66
	v_mov_b32_e32 v91, v66
	v_mov_b32_e32 v92, v65
	v_mov_b32_e32 v93, v65
	v_mov_b32_e32 v94, v67
	v_mov_b32_e32 v95, v67
	v_mov_b32_e32 v96, v68
	v_mov_b32_e32 v97, v68
	v_mov_b32_e32 v98, v70
	v_mov_b32_e32 v99, v70
	v_mov_b32_e32 v100, v69
	v_mov_b32_e32 v101, v69
	v_mov_b32_e32 v102, v71
	v_mov_b32_e32 v103, v71
	s_waitcnt lgkmcnt(0)
	s_barrier
	s_branch .LBB0_277

.LBB0_299:
	s_or_b64 exec, exec, s[16:17]
	v_mov_b32_e32 v206, v208
	s_waitcnt lgkmcnt(0)
	s_barrier
	s_xor_b64 s[16:17], s[18:19], -1
	v_and_b32_e32 v104, 0xff, v206
	v_lshlrev_b32_e32 v105, 4, v206
	v_and_or_b32 v104, v105, s93, v104
	v_ashrrev_i32_e32 v105, 4, v104
	v_lshlrev_b32_e32 v105, 3, v105
	v_lshlrev_b32_e32 v104, 3, v104
	v_add3_u32 v207, s35, v105, v104
	ds_read_b64 v[106:107], v207
	ds_read_b64 v[108:109], v207 offset:2176
	ds_read_b64 v[110:111], v207 offset:4352
	ds_read_b64 v[112:113], v207 offset:6528
	ds_read_b64 v[114:115], v207 offset:8704
	ds_read_b64 v[116:117], v207 offset:10880
	ds_read_b64 v[118:119], v207 offset:13056
	ds_read_b64 v[120:121], v207 offset:15232
	ds_read_b64 v[122:123], v207 offset:17408
	ds_read_b64 v[124:125], v207 offset:19584
	ds_read_b64 v[126:127], v207 offset:21760
	ds_read_b64 v[128:129], v207 offset:23936
	ds_read_b64 v[130:131], v207 offset:26112
	ds_read_b64 v[132:133], v207 offset:28288
	ds_read_b64 v[134:135], v207 offset:30464
	ds_read_b64 v[176:177], v207 offset:32640
	s_waitcnt lgkmcnt(5)
	v_pk_add_f32 v[184:185], v[110:111], v[126:127]
	v_pk_add_f32 v[110:111], v[110:111], v[126:127] neg_lo:[0,1] neg_hi:[0,1]
	s_waitcnt lgkmcnt(2)
	v_pk_add_f32 v[194:195], v[116:117], v[132:133]
	s_waitcnt lgkmcnt(1)
	v_pk_add_f32 v[186:187], v[118:119], v[134:135]
	v_pk_add_f32 v[118:119], v[118:119], v[134:135] neg_lo:[0,1] neg_hi:[0,1]
	v_pk_add_f32 v[116:117], v[116:117], v[132:133] neg_lo:[0,1] neg_hi:[0,1]
	v_xor_b32_e32 v127, 0x80000000, v118
	v_mov_b32_e32 v126, v119
	v_pk_add_f32 v[192:193], v[108:109], v[124:125]
	v_pk_add_f32 v[118:119], v[110:111], v[126:127]
	v_pk_add_f32 v[108:109], v[108:109], v[124:125] neg_lo:[0,1] neg_hi:[0,1]
	v_xor_b32_e32 v125, 0x80000000, v116
	v_mov_b32_e32 v124, v117
	v_pk_add_f32 v[180:181], v[114:115], v[130:131]
	v_pk_add_f32 v[114:115], v[114:115], v[130:131] neg_lo:[0,1] neg_hi:[0,1]
	v_pk_mul_f32 v[130:131], v[118:119], s[24:25] op_sel_hi:[1,0]
	v_pk_add_f32 v[116:117], v[108:109], v[124:125]
	v_pk_fma_f32 v[134:135], v[118:119], s[24:25], v[130:131] op_sel:[0,0,1] op_sel_hi:[1,0,0]
	v_pk_fma_f32 v[118:119], v[118:119], s[24:25], v[130:131] op_sel_hi:[1,0,0] neg_lo:[0,0,1] neg_hi:[0,0,1]
	v_pk_mul_f32 v[130:131], v[116:117], s[30:31] op_sel_hi:[1,0]
	v_pk_add_f32 v[178:179], v[106:107], v[122:123]
	v_pk_fma_f32 v[132:133], v[116:117], s[22:23], v[130:131] op_sel:[0,0,1] op_sel_hi:[1,0,0]
	v_pk_fma_f32 v[116:117], v[116:117], s[22:23], v[130:131] op_sel:[0,0,1] op_sel_hi:[1,0,0] neg_lo:[0,0,1] neg_hi:[0,0,1]
	v_pk_add_f32 v[182:183], v[178:179], v[180:181]
	v_pk_add_f32 v[188:189], v[184:185], v[186:187]
	s_waitcnt lgkmcnt(0)
	v_pk_add_f32 v[200:201], v[120:121], v[176:177]
	v_mov_b32_e32 v133, v117
	v_pk_add_f32 v[116:117], v[120:121], v[176:177] neg_lo:[0,1] neg_hi:[0,1]
	v_pk_add_f32 v[176:177], v[178:179], v[180:181] neg_lo:[0,1] neg_hi:[0,1]
	v_pk_add_f32 v[178:179], v[184:185], v[186:187] neg_lo:[0,1] neg_hi:[0,1]
	v_pk_add_f32 v[184:185], v[192:193], v[194:195] neg_lo:[0,1] neg_hi:[0,1]
	v_pk_add_f32 v[198:199], v[112:113], v[128:129]
	v_pk_add_f32 v[112:113], v[112:113], v[128:129] neg_lo:[0,1] neg_hi:[0,1]
	v_xor_b32_e32 v121, 0x80000000, v116
	v_mov_b32_e32 v120, v117
	v_pk_mul_f32 v[186:187], v[184:185], s[24:25] op_sel_hi:[1,0]
	v_pk_add_f32 v[196:197], v[192:193], v[194:195]
	v_pk_add_f32 v[116:117], v[112:113], v[120:121]
	v_pk_fma_f32 v[192:193], v[184:185], s[24:25], v[186:187] op_sel:[0,0,1] op_sel_hi:[1,0,0]
	v_pk_fma_f32 v[184:185], v[184:185], s[24:25], v[186:187] op_sel_hi:[1,0,0] neg_lo:[0,0,1] neg_hi:[0,0,1]
	v_pk_mul_f32 v[128:129], v[116:117], s[22:23] op_sel_hi:[1,0]
	v_mov_b32_e32 v193, v185
	v_pk_add_f32 v[184:185], v[198:199], v[200:201] neg_lo:[0,1] neg_hi:[0,1]
	v_pk_fma_f32 v[130:131], v[116:117], s[30:31], v[128:129] op_sel:[0,0,1] op_sel_hi:[1,0,0]
	v_pk_fma_f32 v[116:117], v[116:117], s[30:31], v[128:129] op_sel:[0,0,1] op_sel_hi:[1,0,0] neg_lo:[0,0,1] neg_hi:[0,0,1]
	v_mul_f32_e32 v186, 0x3f3504f3, v184
	v_pk_add_f32 v[106:107], v[106:107], v[122:123] neg_lo:[0,1] neg_hi:[0,1]
	v_xor_b32_e32 v123, 0x80000000, v114
	v_mov_b32_e32 v122, v115
	v_mov_b32_e32 v131, v117
	v_pk_fma_f32 v[184:185], v[184:185], s[24:25], v[186:187] op_sel:[1,0,0] op_sel_hi:[1,1,0] neg_lo:[0,0,1] neg_hi:[0,0,1]
	v_pk_add_f32 v[108:109], v[108:109], v[124:125] neg_lo:[0,1] neg_hi:[0,1]
	v_pk_add_f32 v[114:115], v[106:107], v[122:123]
	v_mov_b32_e32 v135, v119
	v_pk_add_f32 v[116:117], v[132:133], v[130:131] neg_lo:[0,1] neg_hi:[0,1]
	v_xor_b32_e32 v181, 0x80000000, v178
	v_mov_b32_e32 v180, v179
	v_pk_add_f32 v[186:187], v[192:193], v[184:185] neg_lo:[0,1] neg_hi:[0,1]
	v_pk_mul_f32 v[124:125], v[108:109], s[22:23] op_sel_hi:[1,0]
	v_pk_add_f32 v[118:119], v[114:115], v[134:135] neg_lo:[0,1] neg_hi:[0,1]
	v_xor_b32_e32 v129, 0x80000000, v116
	v_mov_b32_e32 v128, v117
	v_pk_add_f32 v[178:179], v[176:177], v[180:181] neg_lo:[0,1] neg_hi:[0,1]
	v_xor_b32_e32 v195, 0x80000000, v186
	v_mov_b32_e32 v194, v187
	v_pk_add_f32 v[110:111], v[110:111], v[126:127] neg_lo:[0,1] neg_hi:[0,1]
	v_pk_fma_f32 v[126:127], v[108:109], s[30:31], v[124:125] op_sel:[0,0,1] op_sel_hi:[1,0,0]
	v_pk_fma_f32 v[108:109], v[108:109], s[30:31], v[124:125] op_sel:[0,0,1] op_sel_hi:[1,0,0] neg_lo:[0,0,1] neg_hi:[0,0,1]
	v_pk_add_f32 v[116:117], v[118:119], v[128:129]
	v_pk_add_f32 v[186:187], v[178:179], v[194:195]
	v_mov_b32_e32 v127, v109
	v_pk_add_f32 v[108:109], v[112:113], v[120:121] neg_lo:[0,1] neg_hi:[0,1]
	v_pk_add_f32 v[118:119], v[118:119], v[128:129] neg_lo:[0,1] neg_hi:[0,1]
	v_pk_add_f32 v[128:129], v[178:179], v[194:195] neg_lo:[0,1] neg_hi:[0,1]
	v_cvt_f32_ubyte0_e32 v178, v206
	v_pk_mul_f32 v[112:113], v[108:109], s[30:31]
	v_pk_add_f32 v[114:115], v[114:115], v[134:135]
	v_pk_add_f32 v[134:135], v[176:177], v[180:181]
	v_pk_add_f32 v[176:177], v[192:193], v[184:185]
	v_mul_f32_e32 v192, 0x39800000, v178
	v_pk_fma_f32 v[108:109], v[108:109], s[22:23], v[112:113] op_sel:[0,0,1] op_sel_hi:[1,0,0] neg_lo:[1,0,0] neg_hi:[1,0,0]
	v_sin_f32_e32 v178, v192
	v_pk_add_f32 v[190:191], v[182:183], v[188:189]
	v_pk_add_f32 v[106:107], v[106:107], v[122:123] neg_lo:[0,1] neg_hi:[0,1]
	v_mul_f32_e32 v122, 0x3f3504f3, v110
	v_pk_add_f32 v[112:113], v[126:127], v[108:109] neg_lo:[0,1] neg_hi:[0,1]
	v_pk_add_f32 v[108:109], v[126:127], v[108:109]
	v_pk_add_f32 v[126:127], v[182:183], v[188:189] neg_lo:[0,1] neg_hi:[0,1]
	v_cos_f32_e32 v188, v192
	v_pk_fma_f32 v[110:111], v[110:111], s[24:25], v[122:123] op_sel:[1,0,0] op_sel_hi:[1,1,0] neg_lo:[0,0,1] neg_hi:[0,0,1]
	v_pk_add_f32 v[130:131], v[132:133], v[130:131]
	v_pk_add_f32 v[122:123], v[106:107], v[110:111] neg_lo:[0,1] neg_hi:[0,1]
	v_xor_b32_e32 v121, 0x80000000, v112
	v_mov_b32_e32 v120, v113
	v_pk_add_f32 v[132:133], v[114:115], v[130:131] neg_lo:[0,1] neg_hi:[0,1]
	v_pk_add_f32 v[114:115], v[114:115], v[130:131]
	v_pk_add_f32 v[112:113], v[122:123], v[120:121]
	v_pk_add_f32 v[120:121], v[122:123], v[120:121] neg_lo:[0,1] neg_hi:[0,1]
	v_pk_mul_f32 v[122:123], v[178:179], v[114:115] op_sel:[0,1] op_sel_hi:[0,0]
	v_pk_fma_f32 v[130:131], v[188:189], v[114:115], v[122:123]
	v_pk_fma_f32 v[114:115], v[188:189], v[114:115], v[122:123] op_sel_hi:[0,1,1] neg_lo:[0,0,1] neg_hi:[0,0,1]
	v_mov_b32_e32 v189, v178
	v_pk_add_f32 v[180:181], v[134:135], v[176:177] neg_lo:[0,1] neg_hi:[0,1]
	v_mov_b32_e32 v131, v115
	v_pk_mul_f32 v[114:115], v[188:189], v[188:189]
	v_pk_add_f32 v[122:123], v[134:135], v[176:177]
	v_mul_f32_e32 v135, v188, v178
	v_mov_b32_e32 v134, v114
	v_mov_b32_e32 v114, v115
	v_mov_b32_e32 v115, v135
	v_pk_add_f32 v[202:203], v[198:199], v[200:201]
	v_pk_add_f32 v[176:177], v[134:135], v[114:115] neg_lo:[0,1] neg_hi:[0,1]
	v_pk_add_f32 v[114:115], v[134:135], v[114:115]
	v_pk_add_f32 v[204:205], v[196:197], v[202:203]
	v_pk_add_f32 v[106:107], v[106:107], v[110:111]
	v_mov_b32_e32 v134, v176
	v_mov_b32_e32 v135, v115
	v_pk_mul_f32 v[114:115], v[114:115], v[122:123] op_sel:[1,1] op_sel_hi:[1,0]
	v_mov_b32_e32 v179, v188
	v_pk_add_f32 v[104:105], v[190:191], v[204:205]
	v_pk_add_f32 v[124:125], v[190:191], v[204:205] neg_lo:[0,1] neg_hi:[0,1]
	v_pk_add_f32 v[110:111], v[106:107], v[108:109] neg_lo:[0,1] neg_hi:[0,1]
	v_pk_fma_f32 v[190:191], v[176:177], v[122:123], v[114:115]
	v_pk_fma_f32 v[114:115], v[176:177], v[122:123], v[114:115] op_sel_hi:[0,1,1] neg_lo:[0,0,1] neg_hi:[0,0,1]
	v_pk_add_f32 v[106:107], v[106:107], v[108:109]
	v_pk_mul_f32 v[108:109], v[178:179], v[134:135]
	v_mov_b32_e32 v191, v115
	v_pk_mul_f32 v[114:115], v[188:189], v[134:135]
	v_pk_add_f32 v[108:109], v[108:109], v[108:109] op_sel:[1,0] op_sel_hi:[1,0]
	v_pk_add_f32 v[114:115], v[114:115], v[114:115] op_sel:[0,1] op_sel_hi:[0,1] neg_lo:[0,1] neg_hi:[0,1]
	v_pk_mul_f32 v[108:109], v[108:109], v[106:107] op_sel:[0,1] op_sel_hi:[1,0]
	v_pk_add_f32 v[182:183], v[196:197], v[202:203] neg_lo:[0,1] neg_hi:[0,1]
	v_pk_fma_f32 v[122:123], v[114:115], v[106:107], v[108:109]
	v_pk_fma_f32 v[106:107], v[114:115], v[106:107], v[108:109] neg_lo:[0,0,1] neg_hi:[0,0,1]
	v_mul_f32_e32 v108, 4.0, v192
	v_sin_f32_e32 v106, v108
	v_cos_f32_e32 v108, v108
	v_xor_b32_e32 v185, 0x80000000, v182
	v_mov_b32_e32 v184, v183
	v_pk_add_f32 v[114:115], v[126:127], v[184:185]
	v_pk_add_f32 v[182:183], v[126:127], v[184:185] neg_lo:[0,1] neg_hi:[0,1]
	v_pk_mul_f32 v[126:127], v[106:107], v[114:115] op_sel:[0,1] op_sel_hi:[0,0]
	v_mov_b32_e32 v123, v107
	v_pk_fma_f32 v[134:135], v[108:109], v[114:115], v[126:127]
	v_pk_fma_f32 v[114:115], v[108:109], v[114:115], v[126:127] op_sel_hi:[0,1,1] neg_lo:[0,0,1] neg_hi:[0,0,1]
	v_mov_b32_e32 v109, v106
	v_mov_b32_e32 v107, v108
	v_mov_b32_e32 v135, v115
	v_pk_mul_f32 v[114:115], v[188:189], v[108:109]
	v_pk_mul_f32 v[106:107], v[188:189], v[106:107]
	v_mov_b32_e32 v108, v114
	v_mov_b32_e32 v109, v106
	v_mov_b32_e32 v106, v115
	v_pk_add_f32 v[114:115], v[108:109], v[106:107] neg_lo:[0,1] neg_hi:[0,1]
	v_pk_add_f32 v[106:107], v[108:109], v[106:107]
	v_mov_b32_e32 v108, v114
	v_mov_b32_e32 v109, v107
	v_pk_mul_f32 v[106:107], v[106:107], v[116:117] op_sel:[1,1] op_sel_hi:[1,0]
	s_mov_b32 s18, s25
	v_pk_fma_f32 v[126:127], v[114:115], v[116:117], v[106:107]
	v_pk_fma_f32 v[106:107], v[114:115], v[116:117], v[106:107] op_sel_hi:[0,1,1] neg_lo:[0,0,1] neg_hi:[0,0,1]
	v_mov_b32_e32 v127, v107
	v_pk_mul_f32 v[106:107], v[188:189], v[108:109]
	v_pk_mul_f32 v[108:109], v[178:179], v[108:109]
	v_mov_b32_e32 v114, v106
	v_mov_b32_e32 v115, v109
	v_pk_mov_b32 v[106:107], v[106:107], v[108:109] op_sel:[1,0]
	s_mov_b32 s19, s24
	v_pk_add_f32 v[108:109], v[114:115], v[106:107] neg_lo:[0,1] neg_hi:[0,1]
	v_pk_add_f32 v[106:107], v[114:115], v[106:107]
	v_mov_b32_e32 v114, v108
	v_mov_b32_e32 v115, v107
	v_pk_mul_f32 v[106:107], v[106:107], v[186:187] op_sel:[1,1] op_sel_hi:[1,0]
	s_mov_b32 s88, s31
	v_pk_fma_f32 v[116:117], v[108:109], v[186:187], v[106:107]
	v_pk_fma_f32 v[106:107], v[108:109], v[186:187], v[106:107] op_sel_hi:[0,1,1] neg_lo:[0,0,1] neg_hi:[0,0,1]
	v_pk_mul_f32 v[108:109], v[178:179], v[114:115]
	v_mov_b32_e32 v117, v107
	v_pk_mul_f32 v[106:107], v[188:189], v[114:115]
	v_pk_add_f32 v[108:109], v[108:109], v[108:109] op_sel:[1,0] op_sel_hi:[1,0]
	v_pk_add_f32 v[106:107], v[106:107], v[106:107] op_sel:[0,1] op_sel_hi:[0,1] neg_lo:[0,1] neg_hi:[0,1]
	v_pk_mul_f32 v[108:109], v[108:109], v[112:113] op_sel:[0,1] op_sel_hi:[1,0]
	s_mov_b32 s89, s30
	v_pk_fma_f32 v[114:115], v[106:107], v[112:113], v[108:109]
	v_pk_fma_f32 v[106:107], v[106:107], v[112:113], v[108:109] neg_lo:[0,0,1] neg_hi:[0,0,1]
	v_mul_f32_e32 v115, 0x41000000, v192
	v_sin_f32_e32 v176, v115
	v_cos_f32_e32 v184, v115
	v_mov_b32_e32 v115, v107
	v_pk_mul_f32 v[106:107], v[176:177], v[124:125] op_sel:[0,1] op_sel_hi:[0,0]
	v_pk_fma_f32 v[108:109], v[184:185], v[124:125], v[106:107]
	v_pk_fma_f32 v[106:107], v[184:185], v[124:125], v[106:107] op_sel_hi:[0,1,1] neg_lo:[0,0,1] neg_hi:[0,0,1]
	v_mov_b32_e32 v185, v176
	v_mov_b32_e32 v177, v184
	v_mov_b32_e32 v109, v107
	v_pk_mul_f32 v[106:107], v[188:189], v[184:185]
	v_pk_mul_f32 v[112:113], v[188:189], v[176:177]
	v_mov_b32_e32 v124, v106
	v_mov_b32_e32 v125, v112
	v_mov_b32_e32 v112, v107
	v_pk_add_f32 v[106:107], v[124:125], v[112:113] neg_lo:[0,1] neg_hi:[0,1]
	v_pk_add_f32 v[112:113], v[124:125], v[112:113]
	v_mov_b32_e32 v124, v106
	v_mov_b32_e32 v125, v113
	v_pk_mul_f32 v[112:113], v[112:113], v[132:133] op_sel:[1,1] op_sel_hi:[1,0]
	s_nop 0
	v_pk_fma_f32 v[176:177], v[106:107], v[132:133], v[112:113]
	v_pk_fma_f32 v[106:107], v[106:107], v[132:133], v[112:113] op_sel_hi:[0,1,1] neg_lo:[0,0,1] neg_hi:[0,0,1]
	v_mov_b32_e32 v177, v107
	v_pk_mul_f32 v[106:107], v[188:189], v[124:125]
	v_pk_mul_f32 v[112:113], v[178:179], v[124:125]
	v_mov_b32_e32 v124, v106
	v_mov_b32_e32 v125, v113
	v_pk_mov_b32 v[106:107], v[106:107], v[112:113] op_sel:[1,0]
	s_nop 0
	v_pk_add_f32 v[112:113], v[124:125], v[106:107] neg_lo:[0,1] neg_hi:[0,1]
	v_pk_add_f32 v[106:107], v[124:125], v[106:107]
	v_mov_b32_e32 v124, v112
	v_mov_b32_e32 v125, v107
	v_pk_mul_f32 v[106:107], v[106:107], v[180:181] op_sel:[1,1] op_sel_hi:[1,0]
	s_nop 0
	v_pk_fma_f32 v[132:133], v[112:113], v[180:181], v[106:107]
	v_pk_fma_f32 v[106:107], v[112:113], v[180:181], v[106:107] op_sel_hi:[0,1,1] neg_lo:[0,0,1] neg_hi:[0,0,1]
	v_pk_mul_f32 v[112:113], v[178:179], v[124:125]
	v_mov_b32_e32 v133, v107
	v_pk_mul_f32 v[106:107], v[188:189], v[124:125]
	v_pk_add_f32 v[112:113], v[112:113], v[112:113] op_sel:[1,0] op_sel_hi:[1,0]
	v_pk_add_f32 v[106:107], v[106:107], v[106:107] op_sel:[0,1] op_sel_hi:[0,1] neg_lo:[0,1] neg_hi:[0,1]
	v_pk_mul_f32 v[112:113], v[112:113], v[110:111] op_sel:[0,1] op_sel_hi:[1,0]
	s_nop 0
	v_pk_fma_f32 v[124:125], v[106:107], v[110:111], v[112:113]
	v_pk_fma_f32 v[106:107], v[106:107], v[110:111], v[112:113] neg_lo:[0,0,1] neg_hi:[0,0,1]
	v_mul_f32_e32 v125, 0x41400000, v192
	v_sin_f32_e32 v180, v125
	v_cos_f32_e32 v184, v125
	v_mov_b32_e32 v125, v107
	v_pk_mul_f32 v[106:107], v[180:181], v[182:183] op_sel:[0,1] op_sel_hi:[0,0]
	v_pk_fma_f32 v[110:111], v[184:185], v[182:183], v[106:107]
	v_pk_fma_f32 v[106:107], v[184:185], v[182:183], v[106:107] op_sel_hi:[0,1,1] neg_lo:[0,0,1] neg_hi:[0,0,1]
	v_mov_b32_e32 v185, v180
	v_mov_b32_e32 v181, v184
	v_mov_b32_e32 v111, v107
	v_pk_mul_f32 v[106:107], v[188:189], v[184:185]
	v_pk_mul_f32 v[112:113], v[188:189], v[180:181]
	v_mov_b32_e32 v180, v106
	v_mov_b32_e32 v181, v112
	v_mov_b32_e32 v112, v107
	v_pk_add_f32 v[106:107], v[180:181], v[112:113] neg_lo:[0,1] neg_hi:[0,1]
	v_pk_add_f32 v[112:113], v[180:181], v[112:113]
	v_mov_b32_e32 v180, v106
	v_mov_b32_e32 v181, v113
	v_pk_mul_f32 v[112:113], v[112:113], v[118:119] op_sel:[1,1] op_sel_hi:[1,0]
	s_nop 0
	v_pk_fma_f32 v[182:183], v[106:107], v[118:119], v[112:113]
	v_pk_fma_f32 v[106:107], v[106:107], v[118:119], v[112:113] op_sel_hi:[0,1,1] neg_lo:[0,0,1] neg_hi:[0,0,1]
	v_mov_b32_e32 v183, v107
	v_pk_mul_f32 v[106:107], v[188:189], v[180:181]
	v_pk_mul_f32 v[112:113], v[178:179], v[180:181]
	v_mov_b32_e32 v118, v106
	v_mov_b32_e32 v119, v113
	v_pk_mov_b32 v[106:107], v[106:107], v[112:113] op_sel:[1,0]
	s_nop 0
	v_pk_add_f32 v[112:113], v[118:119], v[106:107] neg_lo:[0,1] neg_hi:[0,1]
	v_pk_add_f32 v[106:107], v[118:119], v[106:107]
	v_mov_b32_e32 v118, v112
	v_mov_b32_e32 v119, v107
	v_pk_mul_f32 v[106:107], v[106:107], v[128:129] op_sel:[1,1] op_sel_hi:[1,0]
	s_nop 0
	v_pk_fma_f32 v[180:181], v[112:113], v[128:129], v[106:107]
	v_pk_fma_f32 v[106:107], v[112:113], v[128:129], v[106:107] op_sel_hi:[0,1,1] neg_lo:[0,0,1] neg_hi:[0,0,1]
	v_pk_mul_f32 v[112:113], v[178:179], v[118:119]
	v_mov_b32_e32 v181, v107
	v_pk_mul_f32 v[106:107], v[188:189], v[118:119]
	v_pk_add_f32 v[112:113], v[112:113], v[112:113] op_sel:[1,0] op_sel_hi:[1,0]
	v_pk_add_f32 v[106:107], v[106:107], v[106:107] op_sel:[0,1] op_sel_hi:[0,1] neg_lo:[0,1] neg_hi:[0,1]
	v_pk_mul_f32 v[112:113], v[112:113], v[120:121] op_sel:[0,1] op_sel_hi:[1,0]
	s_nop 0
	v_pk_fma_f32 v[118:119], v[106:107], v[120:121], v[112:113]
	v_pk_fma_f32 v[106:107], v[106:107], v[120:121], v[112:113] neg_lo:[0,0,1] neg_hi:[0,0,1]
	s_nop 0
	v_mov_b32_e32 v119, v107
	ds_write_b64 v207, v[104:105]
	ds_write_b64 v207, v[130:131] offset:2176
	ds_write_b64 v207, v[190:191] offset:4352
	ds_write_b64 v207, v[122:123] offset:6528
	ds_write_b64 v207, v[134:135] offset:8704
	ds_write_b64 v207, v[126:127] offset:10880
	ds_write_b64 v207, v[116:117] offset:13056
	ds_write_b64 v207, v[114:115] offset:15232
	ds_write_b64 v207, v[108:109] offset:17408
	ds_write_b64 v207, v[176:177] offset:19584
	ds_write_b64 v207, v[132:133] offset:21760
	ds_write_b64 v207, v[124:125] offset:23936
	ds_write_b64 v207, v[110:111] offset:26112
	ds_write_b64 v207, v[182:183] offset:28288
	ds_write_b64 v207, v[180:181] offset:30464
	ds_write_b64 v207, v[118:119] offset:32640
	v_mov_b32_e32 v104, v208
	s_waitcnt lgkmcnt(0)
	s_barrier
	s_nop 0
	v_and_b32_e32 v206, 15, v104
	v_lshlrev_b32_e32 v104, 4, v104
	v_and_b32_e32 v104, 0xffffff00, v104
	v_ashrrev_i32_e32 v105, 1, v104
	v_add_u32_e32 v105, s35, v105
	v_lshlrev_b32_e32 v104, 3, v104
	v_lshlrev_b32_e32 v106, 3, v206
	v_add3_u32 v207, v105, v104, v106
	ds_read_b64 v[106:107], v207
	ds_read_b64 v[108:109], v207 offset:136
	ds_read_b64 v[110:111], v207 offset:272
	ds_read_b64 v[112:113], v207 offset:408
	ds_read_b64 v[114:115], v207 offset:544
	ds_read_b64 v[116:117], v207 offset:680
	ds_read_b64 v[118:119], v207 offset:1088
	ds_read_b64 v[120:121], v207 offset:1224
	ds_read_b64 v[122:123], v207 offset:1632
	ds_read_b64 v[124:125], v207 offset:1768
	ds_read_b64 v[126:127], v207 offset:816
	ds_read_b64 v[128:129], v207 offset:952
	ds_read_b64 v[130:131], v207 offset:1360
	ds_read_b64 v[132:133], v207 offset:1496
	ds_read_b64 v[176:177], v207 offset:1904
	ds_read_b64 v[178:179], v207 offset:2040
	s_waitcnt lgkmcnt(8)
	v_pk_add_f32 v[192:193], v[108:109], v[120:121]
	s_waitcnt lgkmcnt(6)
	v_pk_add_f32 v[180:181], v[114:115], v[122:123]
	v_pk_add_f32 v[194:195], v[116:117], v[124:125]
	v_pk_add_f32 v[114:115], v[114:115], v[122:123] neg_lo:[0,1] neg_hi:[0,1]
	s_waitcnt lgkmcnt(0)
	v_pk_add_f32 v[122:123], v[126:127], v[176:177] neg_lo:[0,1] neg_hi:[0,1]
	v_pk_add_f32 v[116:117], v[116:117], v[124:125] neg_lo:[0,1] neg_hi:[0,1]
	v_pk_add_f32 v[184:185], v[110:111], v[130:131]
	v_pk_add_f32 v[186:187], v[126:127], v[176:177]
	v_pk_add_f32 v[110:111], v[110:111], v[130:131] neg_lo:[0,1] neg_hi:[0,1]
	v_xor_b32_e32 v127, 0x80000000, v122
	v_mov_b32_e32 v126, v123
	v_pk_add_f32 v[108:109], v[108:109], v[120:121] neg_lo:[0,1] neg_hi:[0,1]
	v_xor_b32_e32 v121, 0x80000000, v116
	v_mov_b32_e32 v120, v117
	v_pk_add_f32 v[122:123], v[110:111], v[126:127]
	v_pk_add_f32 v[116:117], v[108:109], v[120:121]
	v_pk_mul_f32 v[130:131], v[122:123], s[24:25] op_sel_hi:[1,0]
	v_pk_mul_f32 v[124:125], v[116:117], s[30:31] op_sel_hi:[1,0]
	v_pk_fma_f32 v[176:177], v[122:123], s[24:25], v[130:131] op_sel:[0,0,1] op_sel_hi:[1,0,0]
	v_pk_fma_f32 v[122:123], v[122:123], s[24:25], v[130:131] op_sel_hi:[1,0,0] neg_lo:[0,0,1] neg_hi:[0,0,1]
	v_pk_fma_f32 v[130:131], v[116:117], s[22:23], v[124:125] op_sel:[0,0,1] op_sel_hi:[1,0,0]
	v_pk_fma_f32 v[116:117], v[116:117], s[22:23], v[124:125] op_sel:[0,0,1] op_sel_hi:[1,0,0] neg_lo:[0,0,1] neg_hi:[0,0,1]
	v_pk_add_f32 v[188:189], v[184:185], v[186:187]
	v_pk_add_f32 v[200:201], v[128:129], v[178:179]
	v_mov_b32_e32 v131, v117
	v_pk_add_f32 v[116:117], v[128:129], v[178:179] neg_lo:[0,1] neg_hi:[0,1]
	v_pk_add_f32 v[178:179], v[184:185], v[186:187] neg_lo:[0,1] neg_hi:[0,1]
	v_pk_add_f32 v[184:185], v[192:193], v[194:195] neg_lo:[0,1] neg_hi:[0,1]
	v_pk_add_f32 v[198:199], v[112:113], v[132:133]
	v_pk_add_f32 v[112:113], v[112:113], v[132:133] neg_lo:[0,1] neg_hi:[0,1]
	v_xor_b32_e32 v125, 0x80000000, v116
	v_mov_b32_e32 v124, v117
	v_pk_mul_f32 v[186:187], v[184:185], s[24:25] op_sel_hi:[1,0]
	v_pk_add_f32 v[196:197], v[192:193], v[194:195]
	v_pk_add_f32 v[116:117], v[112:113], v[124:125]
	v_pk_fma_f32 v[192:193], v[184:185], s[24:25], v[186:187] op_sel:[0,0,1] op_sel_hi:[1,0,0]
	v_pk_fma_f32 v[184:185], v[184:185], s[24:25], v[186:187] op_sel_hi:[1,0,0] neg_lo:[0,0,1] neg_hi:[0,0,1]
	v_pk_mul_f32 v[128:129], v[116:117], s[22:23] op_sel_hi:[1,0]
	v_mov_b32_e32 v193, v185
	v_pk_add_f32 v[184:185], v[198:199], v[200:201] neg_lo:[0,1] neg_hi:[0,1]
	v_pk_fma_f32 v[132:133], v[116:117], s[30:31], v[128:129] op_sel:[0,0,1] op_sel_hi:[1,0,0]
	v_pk_fma_f32 v[116:117], v[116:117], s[30:31], v[128:129] op_sel:[0,0,1] op_sel_hi:[1,0,0] neg_lo:[0,0,1] neg_hi:[0,0,1]
	v_mul_f32_e32 v186, 0x3f3504f3, v184
	v_pk_add_f32 v[134:135], v[106:107], v[118:119]
	v_pk_add_f32 v[106:107], v[106:107], v[118:119] neg_lo:[0,1] neg_hi:[0,1]
	v_xor_b32_e32 v119, 0x80000000, v114
	v_mov_b32_e32 v118, v115
	v_mov_b32_e32 v133, v117
	v_pk_fma_f32 v[184:185], v[184:185], s[24:25], v[186:187] op_sel:[1,0,0] op_sel_hi:[1,1,0] neg_lo:[0,0,1] neg_hi:[0,0,1]
	v_pk_add_f32 v[108:109], v[108:109], v[120:121] neg_lo:[0,1] neg_hi:[0,1]
	v_pk_add_f32 v[182:183], v[134:135], v[180:181]
	v_pk_add_f32 v[114:115], v[106:107], v[118:119]
	v_mov_b32_e32 v177, v123
	v_pk_add_f32 v[116:117], v[130:131], v[132:133] neg_lo:[0,1] neg_hi:[0,1]
	v_pk_add_f32 v[134:135], v[134:135], v[180:181] neg_lo:[0,1] neg_hi:[0,1]
	v_xor_b32_e32 v181, 0x80000000, v178
	v_mov_b32_e32 v180, v179
	v_pk_add_f32 v[186:187], v[192:193], v[184:185] neg_lo:[0,1] neg_hi:[0,1]
	v_pk_mul_f32 v[120:121], v[108:109], s[22:23] op_sel_hi:[1,0]
	v_pk_add_f32 v[122:123], v[114:115], v[176:177] neg_lo:[0,1] neg_hi:[0,1]
	v_xor_b32_e32 v129, 0x80000000, v116
	v_mov_b32_e32 v128, v117
	v_pk_add_f32 v[178:179], v[134:135], v[180:181] neg_lo:[0,1] neg_hi:[0,1]
	v_xor_b32_e32 v195, 0x80000000, v186
	v_mov_b32_e32 v194, v187
	v_pk_add_f32 v[110:111], v[110:111], v[126:127] neg_lo:[0,1] neg_hi:[0,1]
	v_pk_fma_f32 v[126:127], v[108:109], s[30:31], v[120:121] op_sel:[0,0,1] op_sel_hi:[1,0,0]
	v_pk_fma_f32 v[108:109], v[108:109], s[30:31], v[120:121] op_sel:[0,0,1] op_sel_hi:[1,0,0] neg_lo:[0,0,1] neg_hi:[0,0,1]
	v_pk_add_f32 v[116:117], v[122:123], v[128:129]
	v_pk_add_f32 v[186:187], v[178:179], v[194:195]
	v_mov_b32_e32 v127, v109
	v_pk_add_f32 v[108:109], v[112:113], v[124:125] neg_lo:[0,1] neg_hi:[0,1]
	v_pk_add_f32 v[122:123], v[122:123], v[128:129] neg_lo:[0,1] neg_hi:[0,1]
	v_pk_add_f32 v[128:129], v[178:179], v[194:195] neg_lo:[0,1] neg_hi:[0,1]
	v_cvt_f32_ubyte0_e32 v178, v206
	v_pk_mul_f32 v[112:113], v[108:109], s[30:31]
	v_pk_add_f32 v[114:115], v[114:115], v[176:177]
	v_pk_add_f32 v[176:177], v[192:193], v[184:185]
	v_mul_f32_e32 v192, 0x3b800000, v178
	v_pk_fma_f32 v[108:109], v[108:109], s[22:23], v[112:113] op_sel:[0,0,1] op_sel_hi:[1,0,0] neg_lo:[1,0,0] neg_hi:[1,0,0]
	v_sin_f32_e32 v178, v192
	v_pk_add_f32 v[190:191], v[182:183], v[188:189]
	v_pk_add_f32 v[106:107], v[106:107], v[118:119] neg_lo:[0,1] neg_hi:[0,1]
	v_mul_f32_e32 v118, 0x3f3504f3, v110
	v_pk_add_f32 v[112:113], v[126:127], v[108:109] neg_lo:[0,1] neg_hi:[0,1]
	v_pk_add_f32 v[108:109], v[126:127], v[108:109]
	v_pk_add_f32 v[126:127], v[182:183], v[188:189] neg_lo:[0,1] neg_hi:[0,1]
	v_cos_f32_e32 v188, v192
	v_pk_fma_f32 v[110:111], v[110:111], s[24:25], v[118:119] op_sel:[1,0,0] op_sel_hi:[1,1,0] neg_lo:[0,0,1] neg_hi:[0,0,1]
	v_pk_add_f32 v[130:131], v[130:131], v[132:133]
	v_pk_add_f32 v[118:119], v[106:107], v[110:111] neg_lo:[0,1] neg_hi:[0,1]
	v_xor_b32_e32 v121, 0x80000000, v112
	v_mov_b32_e32 v120, v113
	v_pk_add_f32 v[132:133], v[114:115], v[130:131] neg_lo:[0,1] neg_hi:[0,1]
	v_pk_add_f32 v[114:115], v[114:115], v[130:131]
	v_pk_add_f32 v[112:113], v[118:119], v[120:121]
	v_pk_add_f32 v[118:119], v[118:119], v[120:121] neg_lo:[0,1] neg_hi:[0,1]
	v_pk_mul_f32 v[120:121], v[178:179], v[114:115] op_sel:[0,1] op_sel_hi:[0,0]
	v_pk_add_f32 v[134:135], v[134:135], v[180:181]
	v_pk_fma_f32 v[130:131], v[188:189], v[114:115], v[120:121]
	v_pk_fma_f32 v[114:115], v[188:189], v[114:115], v[120:121] op_sel_hi:[0,1,1] neg_lo:[0,0,1] neg_hi:[0,0,1]
	v_mov_b32_e32 v189, v178
	v_pk_add_f32 v[180:181], v[134:135], v[176:177] neg_lo:[0,1] neg_hi:[0,1]
	v_mov_b32_e32 v131, v115
	v_pk_mul_f32 v[114:115], v[188:189], v[188:189]
	v_pk_add_f32 v[120:121], v[134:135], v[176:177]
	v_mul_f32_e32 v135, v188, v178
	v_mov_b32_e32 v134, v114
	v_mov_b32_e32 v114, v115
	v_mov_b32_e32 v115, v135
	v_pk_add_f32 v[202:203], v[198:199], v[200:201]
	v_pk_add_f32 v[176:177], v[134:135], v[114:115] neg_lo:[0,1] neg_hi:[0,1]
	v_pk_add_f32 v[114:115], v[134:135], v[114:115]
	v_pk_add_f32 v[204:205], v[196:197], v[202:203]
	v_pk_add_f32 v[106:107], v[106:107], v[110:111]
	v_mov_b32_e32 v134, v176
	v_mov_b32_e32 v135, v115
	v_pk_mul_f32 v[114:115], v[114:115], v[120:121] op_sel:[1,1] op_sel_hi:[1,0]
	v_mov_b32_e32 v179, v188
	v_pk_add_f32 v[104:105], v[190:191], v[204:205]
	v_pk_add_f32 v[124:125], v[190:191], v[204:205] neg_lo:[0,1] neg_hi:[0,1]
	v_pk_add_f32 v[110:111], v[106:107], v[108:109] neg_lo:[0,1] neg_hi:[0,1]
	v_pk_fma_f32 v[190:191], v[176:177], v[120:121], v[114:115]
	v_pk_fma_f32 v[114:115], v[176:177], v[120:121], v[114:115] op_sel_hi:[0,1,1] neg_lo:[0,0,1] neg_hi:[0,0,1]
	v_pk_add_f32 v[106:107], v[106:107], v[108:109]
	v_pk_mul_f32 v[108:109], v[178:179], v[134:135]
	v_mov_b32_e32 v191, v115
	v_pk_mul_f32 v[114:115], v[188:189], v[134:135]
	v_pk_add_f32 v[108:109], v[108:109], v[108:109] op_sel:[1,0] op_sel_hi:[1,0]
	v_pk_add_f32 v[114:115], v[114:115], v[114:115] op_sel:[0,1] op_sel_hi:[0,1] neg_lo:[0,1] neg_hi:[0,1]
	v_pk_mul_f32 v[108:109], v[108:109], v[106:107] op_sel:[0,1] op_sel_hi:[1,0]
	v_pk_add_f32 v[182:183], v[196:197], v[202:203] neg_lo:[0,1] neg_hi:[0,1]
	v_pk_fma_f32 v[120:121], v[114:115], v[106:107], v[108:109]
	v_pk_fma_f32 v[106:107], v[114:115], v[106:107], v[108:109] neg_lo:[0,0,1] neg_hi:[0,0,1]
	v_mul_f32_e32 v108, 4.0, v192
	v_sin_f32_e32 v106, v108
	v_cos_f32_e32 v108, v108
	v_xor_b32_e32 v185, 0x80000000, v182
	v_mov_b32_e32 v184, v183
	v_pk_add_f32 v[114:115], v[126:127], v[184:185]
	v_pk_add_f32 v[182:183], v[126:127], v[184:185] neg_lo:[0,1] neg_hi:[0,1]
	v_pk_mul_f32 v[126:127], v[106:107], v[114:115] op_sel:[0,1] op_sel_hi:[0,0]
	v_mov_b32_e32 v121, v107
	v_pk_fma_f32 v[134:135], v[108:109], v[114:115], v[126:127]
	v_pk_fma_f32 v[114:115], v[108:109], v[114:115], v[126:127] op_sel_hi:[0,1,1] neg_lo:[0,0,1] neg_hi:[0,0,1]
	v_mov_b32_e32 v109, v106
	v_mov_b32_e32 v107, v108
	v_mov_b32_e32 v135, v115
	v_pk_mul_f32 v[114:115], v[188:189], v[108:109]
	v_pk_mul_f32 v[106:107], v[188:189], v[106:107]
	v_mov_b32_e32 v108, v114
	v_mov_b32_e32 v109, v106
	v_mov_b32_e32 v106, v115
	v_pk_add_f32 v[114:115], v[108:109], v[106:107] neg_lo:[0,1] neg_hi:[0,1]
	v_pk_add_f32 v[106:107], v[108:109], v[106:107]
	v_mov_b32_e32 v108, v114
	v_mov_b32_e32 v109, v107
	v_pk_mul_f32 v[106:107], v[106:107], v[116:117] op_sel:[1,1] op_sel_hi:[1,0]
	s_nop 0
	v_pk_fma_f32 v[126:127], v[114:115], v[116:117], v[106:107]
	v_pk_fma_f32 v[106:107], v[114:115], v[116:117], v[106:107] op_sel_hi:[0,1,1] neg_lo:[0,0,1] neg_hi:[0,0,1]
	v_mov_b32_e32 v127, v107
	v_pk_mul_f32 v[106:107], v[188:189], v[108:109]
	v_pk_mul_f32 v[108:109], v[178:179], v[108:109]
	v_mov_b32_e32 v114, v106
	v_mov_b32_e32 v115, v109
	v_pk_mov_b32 v[106:107], v[106:107], v[108:109] op_sel:[1,0]
	s_nop 0
	v_pk_add_f32 v[108:109], v[114:115], v[106:107] neg_lo:[0,1] neg_hi:[0,1]
	v_pk_add_f32 v[106:107], v[114:115], v[106:107]
	v_mov_b32_e32 v114, v108
	v_mov_b32_e32 v115, v107
	v_pk_mul_f32 v[106:107], v[106:107], v[186:187] op_sel:[1,1] op_sel_hi:[1,0]
	s_nop 0
	v_pk_fma_f32 v[116:117], v[108:109], v[186:187], v[106:107]
	v_pk_fma_f32 v[106:107], v[108:109], v[186:187], v[106:107] op_sel_hi:[0,1,1] neg_lo:[0,0,1] neg_hi:[0,0,1]
	v_pk_mul_f32 v[108:109], v[178:179], v[114:115]
	v_mov_b32_e32 v117, v107
	v_pk_mul_f32 v[106:107], v[188:189], v[114:115]
	v_pk_add_f32 v[108:109], v[108:109], v[108:109] op_sel:[1,0] op_sel_hi:[1,0]
	v_pk_add_f32 v[106:107], v[106:107], v[106:107] op_sel:[0,1] op_sel_hi:[0,1] neg_lo:[0,1] neg_hi:[0,1]
	v_pk_mul_f32 v[108:109], v[108:109], v[112:113] op_sel:[0,1] op_sel_hi:[1,0]
	s_nop 0
	v_pk_fma_f32 v[114:115], v[106:107], v[112:113], v[108:109]
	v_pk_fma_f32 v[106:107], v[106:107], v[112:113], v[108:109] neg_lo:[0,0,1] neg_hi:[0,0,1]
	v_mul_f32_e32 v115, 0x41000000, v192
	v_sin_f32_e32 v176, v115
	v_cos_f32_e32 v184, v115
	v_mov_b32_e32 v115, v107
	v_pk_mul_f32 v[106:107], v[176:177], v[124:125] op_sel:[0,1] op_sel_hi:[0,0]
	v_pk_fma_f32 v[108:109], v[184:185], v[124:125], v[106:107]
	v_pk_fma_f32 v[106:107], v[184:185], v[124:125], v[106:107] op_sel_hi:[0,1,1] neg_lo:[0,0,1] neg_hi:[0,0,1]
	v_mov_b32_e32 v185, v176
	v_mov_b32_e32 v177, v184
	v_mov_b32_e32 v109, v107
	v_pk_mul_f32 v[106:107], v[188:189], v[184:185]
	v_pk_mul_f32 v[112:113], v[188:189], v[176:177]
	v_mov_b32_e32 v124, v106
	v_mov_b32_e32 v125, v112
	v_mov_b32_e32 v112, v107
	v_pk_add_f32 v[106:107], v[124:125], v[112:113] neg_lo:[0,1] neg_hi:[0,1]
	v_pk_add_f32 v[112:113], v[124:125], v[112:113]
	v_mov_b32_e32 v124, v106
	v_mov_b32_e32 v125, v113
	v_pk_mul_f32 v[112:113], v[112:113], v[132:133] op_sel:[1,1] op_sel_hi:[1,0]
	s_nop 0
	v_pk_fma_f32 v[176:177], v[106:107], v[132:133], v[112:113]
	v_pk_fma_f32 v[106:107], v[106:107], v[132:133], v[112:113] op_sel_hi:[0,1,1] neg_lo:[0,0,1] neg_hi:[0,0,1]
	v_mov_b32_e32 v177, v107
	v_pk_mul_f32 v[106:107], v[188:189], v[124:125]
	v_pk_mul_f32 v[112:113], v[178:179], v[124:125]
	v_mov_b32_e32 v124, v106
	v_mov_b32_e32 v125, v113
	v_pk_mov_b32 v[106:107], v[106:107], v[112:113] op_sel:[1,0]
	s_nop 0
	v_pk_add_f32 v[112:113], v[124:125], v[106:107] neg_lo:[0,1] neg_hi:[0,1]
	v_pk_add_f32 v[106:107], v[124:125], v[106:107]
	v_mov_b32_e32 v124, v112
	v_mov_b32_e32 v125, v107
	v_pk_mul_f32 v[106:107], v[106:107], v[180:181] op_sel:[1,1] op_sel_hi:[1,0]
	s_nop 0
	v_pk_fma_f32 v[132:133], v[112:113], v[180:181], v[106:107]
	v_pk_fma_f32 v[106:107], v[112:113], v[180:181], v[106:107] op_sel_hi:[0,1,1] neg_lo:[0,0,1] neg_hi:[0,0,1]
	v_pk_mul_f32 v[112:113], v[178:179], v[124:125]
	v_mov_b32_e32 v133, v107
	v_pk_mul_f32 v[106:107], v[188:189], v[124:125]
	v_pk_add_f32 v[112:113], v[112:113], v[112:113] op_sel:[1,0] op_sel_hi:[1,0]
	v_pk_add_f32 v[106:107], v[106:107], v[106:107] op_sel:[0,1] op_sel_hi:[0,1] neg_lo:[0,1] neg_hi:[0,1]
	v_pk_mul_f32 v[112:113], v[112:113], v[110:111] op_sel:[0,1] op_sel_hi:[1,0]
	s_nop 0
	v_pk_fma_f32 v[124:125], v[106:107], v[110:111], v[112:113]
	v_pk_fma_f32 v[106:107], v[106:107], v[110:111], v[112:113] neg_lo:[0,0,1] neg_hi:[0,0,1]
	v_mul_f32_e32 v125, 0x41400000, v192
	v_sin_f32_e32 v180, v125
	v_cos_f32_e32 v184, v125
	v_mov_b32_e32 v125, v107
	v_pk_mul_f32 v[106:107], v[180:181], v[182:183] op_sel:[0,1] op_sel_hi:[0,0]
	v_pk_fma_f32 v[110:111], v[184:185], v[182:183], v[106:107]
	v_pk_fma_f32 v[106:107], v[184:185], v[182:183], v[106:107] op_sel_hi:[0,1,1] neg_lo:[0,0,1] neg_hi:[0,0,1]
	v_mov_b32_e32 v185, v180
	v_mov_b32_e32 v181, v184
	v_mov_b32_e32 v111, v107
	v_pk_mul_f32 v[106:107], v[188:189], v[184:185]
	v_pk_mul_f32 v[112:113], v[188:189], v[180:181]
	v_mov_b32_e32 v180, v106
	v_mov_b32_e32 v181, v112
	v_mov_b32_e32 v112, v107
	v_pk_add_f32 v[106:107], v[180:181], v[112:113] neg_lo:[0,1] neg_hi:[0,1]
	v_pk_add_f32 v[112:113], v[180:181], v[112:113]
	v_mov_b32_e32 v180, v106
	v_mov_b32_e32 v181, v113
	v_pk_mul_f32 v[112:113], v[112:113], v[122:123] op_sel:[1,1] op_sel_hi:[1,0]
	s_nop 0
	v_pk_fma_f32 v[182:183], v[106:107], v[122:123], v[112:113]
	v_pk_fma_f32 v[106:107], v[106:107], v[122:123], v[112:113] op_sel_hi:[0,1,1] neg_lo:[0,0,1] neg_hi:[0,0,1]
	v_mov_b32_e32 v183, v107
	v_pk_mul_f32 v[106:107], v[188:189], v[180:181]
	v_pk_mul_f32 v[112:113], v[178:179], v[180:181]
	v_mov_b32_e32 v122, v106
	v_mov_b32_e32 v123, v113
	v_pk_mov_b32 v[106:107], v[106:107], v[112:113] op_sel:[1,0]
	s_nop 0
	v_pk_add_f32 v[112:113], v[122:123], v[106:107] neg_lo:[0,1] neg_hi:[0,1]
	v_pk_add_f32 v[106:107], v[122:123], v[106:107]
	v_mov_b32_e32 v122, v112
	v_mov_b32_e32 v123, v107
	v_pk_mul_f32 v[106:107], v[106:107], v[128:129] op_sel:[1,1] op_sel_hi:[1,0]
	s_nop 0
	v_pk_fma_f32 v[180:181], v[112:113], v[128:129], v[106:107]
	v_pk_fma_f32 v[106:107], v[112:113], v[128:129], v[106:107] op_sel_hi:[0,1,1] neg_lo:[0,0,1] neg_hi:[0,0,1]
	v_pk_mul_f32 v[112:113], v[178:179], v[122:123]
	v_mov_b32_e32 v181, v107
	v_pk_mul_f32 v[106:107], v[188:189], v[122:123]
	v_pk_add_f32 v[112:113], v[112:113], v[112:113] op_sel:[1,0] op_sel_hi:[1,0]
	v_pk_add_f32 v[106:107], v[106:107], v[106:107] op_sel:[0,1] op_sel_hi:[0,1] neg_lo:[0,1] neg_hi:[0,1]
	v_pk_mul_f32 v[112:113], v[112:113], v[118:119] op_sel:[0,1] op_sel_hi:[1,0]
	s_nop 0
	v_pk_fma_f32 v[122:123], v[106:107], v[118:119], v[112:113]
	v_pk_fma_f32 v[106:107], v[106:107], v[118:119], v[112:113] neg_lo:[0,0,1] neg_hi:[0,0,1]
	s_nop 0
	v_mov_b32_e32 v123, v107
	ds_write_b64 v207, v[104:105]
	ds_write_b64 v207, v[130:131] offset:136
	ds_write_b64 v207, v[190:191] offset:272
	ds_write_b64 v207, v[120:121] offset:408
	ds_write_b64 v207, v[134:135] offset:544
	ds_write_b64 v207, v[126:127] offset:680
	ds_write_b64 v207, v[116:117] offset:816
	ds_write_b64 v207, v[114:115] offset:952
	ds_write_b64 v207, v[108:109] offset:1088
	ds_write_b64 v207, v[176:177] offset:1224
	ds_write_b64 v207, v[132:133] offset:1360
	ds_write_b64 v207, v[124:125] offset:1496
	ds_write_b64 v207, v[110:111] offset:1632
	ds_write_b64 v207, v[182:183] offset:1768
	ds_write_b64 v207, v[180:181] offset:1904
	ds_write_b64 v207, v[122:123] offset:2040
	v_mov_b32_e32 v104, v208
	s_waitcnt lgkmcnt(0)
	s_nop 0
	v_lshlrev_b32_e32 v105, 4, v104
	v_bfe_i32 v104, v104, 0, 28
	v_add_lshl_u32 v182, v104, v105, 3
	v_add_u32_e32 v188, s35, v182
	ds_read_b64 v[104:105], v188
	ds_read_b64 v[106:107], v188 offset:8
	ds_read_b64 v[108:109], v188 offset:16
	ds_read_b64 v[110:111], v188 offset:24
	ds_read_b64 v[112:113], v188 offset:64
	ds_read_b64 v[114:115], v188 offset:72
	ds_read_b64 v[116:117], v188 offset:32
	ds_read_b64 v[118:119], v188 offset:40
	ds_read_b64 v[120:121], v188 offset:48
	ds_read_b64 v[122:123], v188 offset:56
	ds_read_b64 v[124:125], v188 offset:96
	ds_read_b64 v[126:127], v188 offset:104
	ds_read_b64 v[128:129], v188 offset:80
	ds_read_b64 v[130:131], v188 offset:88
	ds_read_b64 v[132:133], v188 offset:112
	ds_read_b64 v[134:135], v188 offset:120
	s_waitcnt lgkmcnt(10)
	v_pk_add_f32 v[176:177], v[104:105], v[112:113]
	v_pk_add_f32 v[104:105], v[104:105], v[112:113] neg_lo:[0,1] neg_hi:[0,1]
	s_waitcnt lgkmcnt(4)
	v_pk_add_f32 v[112:113], v[116:117], v[124:125]
	v_pk_add_f32 v[116:117], v[116:117], v[124:125] neg_lo:[0,1] neg_hi:[0,1]
	v_add_u32_e32 v189, 0, v182
	v_xor_b32_e32 v125, 0x80000000, v116
	v_mov_b32_e32 v124, v117
	v_pk_add_f32 v[116:117], v[176:177], v[112:113]
	v_pk_add_f32 v[112:113], v[176:177], v[112:113] neg_lo:[0,1] neg_hi:[0,1]
	v_pk_add_f32 v[176:177], v[104:105], v[124:125]
	v_pk_add_f32 v[104:105], v[104:105], v[124:125] neg_lo:[0,1] neg_hi:[0,1]
	v_pk_add_f32 v[124:125], v[106:107], v[114:115]
	v_pk_add_f32 v[106:107], v[106:107], v[114:115] neg_lo:[0,1] neg_hi:[0,1]
	v_pk_add_f32 v[114:115], v[118:119], v[126:127]
	v_pk_add_f32 v[118:119], v[118:119], v[126:127] neg_lo:[0,1] neg_hi:[0,1]
	s_nop 0
	v_xor_b32_e32 v127, 0x80000000, v118
	v_mov_b32_e32 v126, v119
	v_pk_add_f32 v[118:119], v[124:125], v[114:115]
	v_pk_add_f32 v[114:115], v[124:125], v[114:115] neg_lo:[0,1] neg_hi:[0,1]
	v_pk_add_f32 v[124:125], v[106:107], v[126:127]
	v_pk_add_f32 v[106:107], v[106:107], v[126:127] neg_lo:[0,1] neg_hi:[0,1]
	s_waitcnt lgkmcnt(2)
	v_pk_add_f32 v[126:127], v[108:109], v[128:129]
	v_pk_add_f32 v[108:109], v[108:109], v[128:129] neg_lo:[0,1] neg_hi:[0,1]
	s_waitcnt lgkmcnt(0)
	v_pk_add_f32 v[128:129], v[120:121], v[132:133]
	v_pk_add_f32 v[120:121], v[120:121], v[132:133] neg_lo:[0,1] neg_hi:[0,1]
	s_nop 0
	v_xor_b32_e32 v133, 0x80000000, v120
	v_mov_b32_e32 v132, v121
	v_pk_add_f32 v[120:121], v[126:127], v[128:129]
	v_pk_add_f32 v[126:127], v[126:127], v[128:129] neg_lo:[0,1] neg_hi:[0,1]
	v_pk_add_f32 v[128:129], v[108:109], v[132:133]
	v_pk_add_f32 v[108:109], v[108:109], v[132:133] neg_lo:[0,1] neg_hi:[0,1]
	v_pk_add_f32 v[132:133], v[110:111], v[130:131]
	v_pk_add_f32 v[110:111], v[110:111], v[130:131] neg_lo:[0,1] neg_hi:[0,1]
	v_pk_add_f32 v[130:131], v[122:123], v[134:135]
	v_pk_add_f32 v[122:123], v[122:123], v[134:135] neg_lo:[0,1] neg_hi:[0,1]
	s_nop 0
	v_xor_b32_e32 v135, 0x80000000, v122
	v_mov_b32_e32 v134, v123
	v_pk_add_f32 v[122:123], v[132:133], v[130:131]
	v_pk_add_f32 v[130:131], v[132:133], v[130:131] neg_lo:[0,1] neg_hi:[0,1]
	v_pk_add_f32 v[132:133], v[110:111], v[134:135]
	v_pk_add_f32 v[110:111], v[110:111], v[134:135] neg_lo:[0,1] neg_hi:[0,1]
	v_pk_mul_f32 v[134:135], v[124:125], s[30:31] op_sel_hi:[1,0]
	s_nop 0
	v_pk_fma_f32 v[178:179], v[124:125], s[22:23], v[134:135] op_sel:[0,0,1] op_sel_hi:[1,0,0]
	v_pk_fma_f32 v[124:125], v[124:125], s[22:23], v[134:135] op_sel:[0,0,1] op_sel_hi:[1,0,0] neg_lo:[0,0,1] neg_hi:[0,0,1]
	s_nop 0
	v_mov_b32_e32 v179, v125
	v_pk_mul_f32 v[124:125], v[114:115], s[24:25] op_sel_hi:[1,0]
	s_nop 0
	v_pk_fma_f32 v[134:135], v[114:115], s[24:25], v[124:125] op_sel:[0,0,1] op_sel_hi:[1,0,0]
	v_pk_fma_f32 v[114:115], v[114:115], s[24:25], v[124:125] op_sel_hi:[1,0,0] neg_lo:[0,0,1] neg_hi:[0,0,1]
	s_nop 0
	v_mov_b32_e32 v135, v115
	v_pk_mul_f32 v[114:115], v[106:107], s[22:23] op_sel_hi:[1,0]
	s_nop 0
	v_pk_fma_f32 v[124:125], v[106:107], s[30:31], v[114:115] op_sel:[0,0,1] op_sel_hi:[1,0,0]
	v_pk_fma_f32 v[106:107], v[106:107], s[30:31], v[114:115] op_sel:[0,0,1] op_sel_hi:[1,0,0] neg_lo:[0,0,1] neg_hi:[0,0,1]
	s_nop 0
	v_mov_b32_e32 v125, v107
	v_pk_mul_f32 v[106:107], v[128:129], s[24:25] op_sel_hi:[1,0]
	s_nop 0
	v_pk_fma_f32 v[114:115], v[128:129], s[24:25], v[106:107] op_sel:[0,0,1] op_sel_hi:[1,0,0]
	v_pk_fma_f32 v[106:107], v[128:129], s[24:25], v[106:107] op_sel_hi:[1,0,0] neg_lo:[0,0,1] neg_hi:[0,0,1]
	s_nop 0
	v_mov_b32_e32 v115, v107
	v_xor_b32_e32 v107, 0x80000000, v126
	v_mul_f32_e32 v126, 0x3f3504f3, v108
	v_mov_b32_e32 v106, v127
	v_pk_fma_f32 v[108:109], v[108:109], s[24:25], v[126:127] op_sel:[1,0,0] op_sel_hi:[1,1,0] neg_lo:[0,0,1] neg_hi:[0,0,1]
	v_pk_mul_f32 v[126:127], v[132:133], s[22:23] op_sel_hi:[1,0]
	s_nop 0
	v_pk_fma_f32 v[128:129], v[132:133], s[30:31], v[126:127] op_sel:[0,0,1] op_sel_hi:[1,0,0]
	v_pk_fma_f32 v[126:127], v[132:133], s[30:31], v[126:127] op_sel:[0,0,1] op_sel_hi:[1,0,0] neg_lo:[0,0,1] neg_hi:[0,0,1]
	s_nop 0
	v_mul_f32_e32 v126, 0x3f3504f3, v130
	v_mov_b32_e32 v129, v127
	v_pk_fma_f32 v[126:127], v[130:131], s[24:25], v[126:127] op_sel:[1,0,0] op_sel_hi:[1,1,0] neg_lo:[0,0,1] neg_hi:[0,0,1]
	v_pk_mul_f32 v[130:131], v[110:111], s[30:31]
	v_pk_add_f32 v[132:133], v[178:179], v[128:129]
	v_pk_fma_f32 v[110:111], v[110:111], s[22:23], v[130:131] op_sel:[0,0,1] op_sel_hi:[1,0,0] neg_lo:[1,0,0] neg_hi:[1,0,0]
	v_pk_add_f32 v[130:131], v[116:117], v[120:121]
	v_pk_add_f32 v[116:117], v[116:117], v[120:121] neg_lo:[0,1] neg_hi:[0,1]
	v_pk_add_f32 v[120:121], v[118:119], v[122:123]
	v_pk_add_f32 v[118:119], v[118:119], v[122:123] neg_lo:[0,1] neg_hi:[0,1]
	v_pk_add_f32 v[128:129], v[178:179], v[128:129] neg_lo:[0,1] neg_hi:[0,1]
	v_xor_b32_e32 v123, 0x80000000, v118
	v_mov_b32_e32 v122, v119
	v_pk_add_f32 v[118:119], v[130:131], v[120:121]
	v_pk_add_f32 v[120:121], v[130:131], v[120:121] neg_lo:[0,1] neg_hi:[0,1]
	v_pk_add_f32 v[130:131], v[116:117], v[122:123]
	v_pk_add_f32 v[116:117], v[116:117], v[122:123] neg_lo:[0,1] neg_hi:[0,1]
	v_pk_add_f32 v[122:123], v[176:177], v[114:115]
	v_pk_add_f32 v[114:115], v[176:177], v[114:115] neg_lo:[0,1] neg_hi:[0,1]
	v_xor_b32_e32 v177, 0x80000000, v128
	v_mov_b32_e32 v176, v129
	v_pk_add_f32 v[128:129], v[122:123], v[132:133]
	v_pk_add_f32 v[122:123], v[122:123], v[132:133] neg_lo:[0,1] neg_hi:[0,1]
	v_pk_add_f32 v[132:133], v[114:115], v[176:177]
	v_pk_add_f32 v[114:115], v[114:115], v[176:177] neg_lo:[0,1] neg_hi:[0,1]
	v_pk_add_f32 v[176:177], v[112:113], v[106:107]
	v_pk_add_f32 v[106:107], v[112:113], v[106:107] neg_lo:[0,1] neg_hi:[0,1]
	v_pk_add_f32 v[112:113], v[134:135], v[126:127]
	v_pk_add_f32 v[126:127], v[134:135], v[126:127] neg_lo:[0,1] neg_hi:[0,1]
	v_pk_add_f32 v[178:179], v[104:105], v[108:109]
	v_xor_b32_e32 v135, 0x80000000, v126
	v_mov_b32_e32 v134, v127
	v_pk_add_f32 v[108:109], v[104:105], v[108:109] neg_lo:[0,1] neg_hi:[0,1]
	v_pk_add_f32 v[104:105], v[124:125], v[110:111] neg_lo:[0,1] neg_hi:[0,1]
	v_pk_add_f32 v[126:127], v[176:177], v[112:113]
	v_pk_add_f32 v[112:113], v[176:177], v[112:113] neg_lo:[0,1] neg_hi:[0,1]
	v_pk_add_f32 v[176:177], v[106:107], v[134:135]
	v_pk_add_f32 v[134:135], v[106:107], v[134:135] neg_lo:[0,1] neg_hi:[0,1]
	v_pk_add_f32 v[180:181], v[124:125], v[110:111]
	v_xor_b32_e32 v111, 0x80000000, v104
	v_mov_b32_e32 v110, v105
	ds_read_b64 v[104:105], v189
	ds_read_b64 v[106:107], v189 offset:8
	v_pk_add_f32 v[124:125], v[178:179], v[180:181]
	v_pk_add_f32 v[178:179], v[178:179], v[180:181] neg_lo:[0,1] neg_hi:[0,1]
	v_pk_add_f32 v[180:181], v[108:109], v[110:111]
	v_pk_add_f32 v[182:183], v[108:109], v[110:111] neg_lo:[0,1] neg_hi:[0,1]
	ds_read_b64 v[108:109], v189 offset:16
	ds_read_b64 v[110:111], v189 offset:24
	s_waitcnt lgkmcnt(2)
	v_pk_mul_f32 v[184:185], v[104:105], v[118:119] op_sel:[1,1] op_sel_hi:[0,1]
	v_pk_fma_f32 v[186:187], v[104:105], v[118:119], v[184:185] neg_lo:[0,0,1] neg_hi:[0,0,1]
	v_pk_fma_f32 v[104:105], v[104:105], v[118:119], v[184:185] op_sel_hi:[1,0,1]
	s_nop 0
	v_mov_b32_e32 v187, v105
	v_pk_mul_f32 v[104:105], v[106:107], v[128:129] op_sel:[1,1] op_sel_hi:[0,1]
	v_pk_fma_f32 v[184:185], v[106:107], v[128:129], v[104:105] neg_lo:[0,0,1] neg_hi:[0,0,1]
	v_pk_fma_f32 v[104:105], v[106:107], v[128:129], v[104:105] op_sel_hi:[1,0,1]
	v_pk_mul_f32 v[118:119], v[28:29], v[186:187]
	v_mov_b32_e32 v185, v105
	s_waitcnt lgkmcnt(0)
	v_pk_mul_f32 v[104:105], v[108:109], v[126:127] op_sel:[1,1] op_sel_hi:[0,1]
	v_pk_fma_f32 v[106:107], v[108:109], v[126:127], v[104:105] neg_lo:[0,0,1] neg_hi:[0,0,1]
	v_pk_fma_f32 v[104:105], v[108:109], v[126:127], v[104:105] op_sel_hi:[1,0,1]
	v_pk_mul_f32 v[108:109], v[110:111], v[124:125] op_sel:[1,1] op_sel_hi:[0,1]
	v_mov_b32_e32 v107, v105
	v_pk_mul_f32 v[126:127], v[28:29], v[106:107]
	ds_read_b64 v[104:105], v189 offset:32
	ds_read_b64 v[106:107], v189 offset:40
	v_pk_mul_f32 v[128:129], v[28:29], v[184:185]
	v_pk_fma_f32 v[184:185], v[110:111], v[124:125], v[108:109] neg_lo:[0,0,1] neg_hi:[0,0,1]
	v_pk_fma_f32 v[108:109], v[110:111], v[124:125], v[108:109] op_sel_hi:[1,0,1]
	s_nop 0
	v_mov_b32_e32 v185, v109
	ds_read_b64 v[108:109], v189 offset:48
	ds_read_b64 v[110:111], v189 offset:56
	v_pk_mul_f32 v[124:125], v[28:29], v[184:185]
	s_waitcnt lgkmcnt(2)
	v_pk_mul_f32 v[184:185], v[104:105], v[130:131] op_sel:[1,1] op_sel_hi:[0,1]
	v_pk_fma_f32 v[186:187], v[104:105], v[130:131], v[184:185] neg_lo:[0,0,1] neg_hi:[0,0,1]
	v_pk_fma_f32 v[104:105], v[104:105], v[130:131], v[184:185] op_sel_hi:[1,0,1]
	s_nop 0
	v_mov_b32_e32 v187, v105
	v_pk_mul_f32 v[104:105], v[106:107], v[132:133] op_sel:[1,1] op_sel_hi:[0,1]
	v_pk_fma_f32 v[184:185], v[106:107], v[132:133], v[104:105] neg_lo:[0,0,1] neg_hi:[0,0,1]
	v_pk_fma_f32 v[104:105], v[106:107], v[132:133], v[104:105] op_sel_hi:[1,0,1]
	v_pk_mul_f32 v[130:131], v[28:29], v[186:187]
	v_mov_b32_e32 v185, v105
	s_waitcnt lgkmcnt(0)
	v_pk_mul_f32 v[104:105], v[108:109], v[176:177] op_sel:[1,1] op_sel_hi:[0,1]
	v_pk_fma_f32 v[106:107], v[108:109], v[176:177], v[104:105] neg_lo:[0,0,1] neg_hi:[0,0,1]
	v_pk_fma_f32 v[104:105], v[108:109], v[176:177], v[104:105] op_sel_hi:[1,0,1]
	v_pk_mul_f32 v[108:109], v[110:111], v[180:181] op_sel:[1,1] op_sel_hi:[0,1]
	v_mov_b32_e32 v107, v105
	v_pk_mul_f32 v[176:177], v[28:29], v[106:107]
	ds_read_b64 v[104:105], v189 offset:64
	ds_read_b64 v[106:107], v189 offset:72
	v_pk_mul_f32 v[132:133], v[28:29], v[184:185]
	v_pk_fma_f32 v[184:185], v[110:111], v[180:181], v[108:109] neg_lo:[0,0,1] neg_hi:[0,0,1]
	v_pk_fma_f32 v[108:109], v[110:111], v[180:181], v[108:109] op_sel_hi:[1,0,1]
	s_nop 0
	v_mov_b32_e32 v185, v109
	ds_read_b64 v[108:109], v189 offset:80
	ds_read_b64 v[110:111], v189 offset:88
	v_pk_mul_f32 v[180:181], v[28:29], v[184:185]
	s_waitcnt lgkmcnt(2)
	v_pk_mul_f32 v[184:185], v[120:121], v[104:105] op_sel:[1,1] op_sel_hi:[1,0]
	s_nop 0
	v_pk_fma_f32 v[186:187], v[120:121], v[104:105], v[184:185] neg_lo:[0,0,1] neg_hi:[0,0,1]
	v_pk_fma_f32 v[104:105], v[120:121], v[104:105], v[184:185] op_sel_hi:[0,1,1]
	v_mov_b32_e32 v187, v105
	v_pk_mul_f32 v[104:105], v[106:107], v[122:123] op_sel:[1,1] op_sel_hi:[0,1]
	v_pk_fma_f32 v[184:185], v[106:107], v[122:123], v[104:105] neg_lo:[0,0,1] neg_hi:[0,0,1]
	v_pk_fma_f32 v[104:105], v[106:107], v[122:123], v[104:105] op_sel_hi:[1,0,1]
	v_pk_mul_f32 v[120:121], v[28:29], v[186:187]
	v_mov_b32_e32 v185, v105
	s_waitcnt lgkmcnt(0)
	v_pk_mul_f32 v[104:105], v[112:113], v[108:109] op_sel:[1,1] op_sel_hi:[1,0]
	v_pk_mul_f32 v[122:123], v[28:29], v[184:185]
	v_pk_fma_f32 v[106:107], v[112:113], v[108:109], v[104:105] neg_lo:[0,0,1] neg_hi:[0,0,1]
	v_pk_fma_f32 v[104:105], v[112:113], v[108:109], v[104:105] op_sel_hi:[0,1,1]
	v_mov_b32_e32 v107, v105
	v_pk_mul_f32 v[112:113], v[28:29], v[106:107]
	v_pk_mul_f32 v[108:109], v[178:179], v[110:111] op_sel:[1,1] op_sel_hi:[1,0]
	ds_read_b64 v[104:105], v189 offset:96
	ds_read_b64 v[106:107], v189 offset:104
	v_pk_fma_f32 v[184:185], v[178:179], v[110:111], v[108:109] neg_lo:[0,0,1] neg_hi:[0,0,1]
	v_pk_fma_f32 v[108:109], v[178:179], v[110:111], v[108:109] op_sel_hi:[0,1,1]
	v_mov_b32_e32 v185, v109
	ds_read_b64 v[108:109], v189 offset:112
	ds_read_b64 v[110:111], v189 offset:120
	v_pk_mul_f32 v[178:179], v[28:29], v[184:185]
	s_waitcnt lgkmcnt(2)
	v_pk_mul_f32 v[184:185], v[116:117], v[104:105] op_sel:[1,1] op_sel_hi:[1,0]
	s_nop 0
	v_pk_fma_f32 v[186:187], v[116:117], v[104:105], v[184:185] neg_lo:[0,0,1] neg_hi:[0,0,1]
	v_pk_fma_f32 v[104:105], v[116:117], v[104:105], v[184:185] op_sel_hi:[0,1,1]
	v_pk_mul_f32 v[116:117], v[106:107], v[114:115] op_sel:[1,1] op_sel_hi:[0,1]
	v_pk_fma_f32 v[184:185], v[106:107], v[114:115], v[116:117] neg_lo:[0,0,1] neg_hi:[0,0,1]
	v_pk_fma_f32 v[106:107], v[106:107], v[114:115], v[116:117] op_sel_hi:[1,0,1]
	s_waitcnt lgkmcnt(0)
	v_pk_mul_f32 v[114:115], v[134:135], v[108:109] op_sel:[1,1] op_sel_hi:[1,0]
	v_mov_b32_e32 v187, v105
	v_pk_fma_f32 v[116:117], v[134:135], v[108:109], v[114:115] neg_lo:[0,0,1] neg_hi:[0,0,1]
	v_pk_fma_f32 v[108:109], v[134:135], v[108:109], v[114:115] op_sel_hi:[0,1,1]
	v_mov_b32_e32 v117, v109
	v_pk_mul_f32 v[114:115], v[182:183], v[110:111] op_sel:[1,1] op_sel_hi:[1,0]
	v_pk_mul_f32 v[108:109], v[28:29], v[116:117]
	v_pk_fma_f32 v[116:117], v[182:183], v[110:111], v[114:115] neg_lo:[0,0,1] neg_hi:[0,0,1]
	v_pk_fma_f32 v[110:111], v[182:183], v[110:111], v[114:115] op_sel_hi:[0,1,1]
	v_pk_mul_f32 v[104:105], v[28:29], v[186:187]
	v_mov_b32_e32 v185, v107
	v_mov_b32_e32 v117, v111
	v_pk_mul_f32 v[106:107], v[28:29], v[184:185]
	v_pk_mul_f32 v[110:111], v[28:29], v[116:117]
	ds_write_b64 v188, v[118:119]
	ds_write_b64 v188, v[128:129] offset:8
	ds_write_b64 v188, v[126:127] offset:16
	ds_write_b64 v188, v[124:125] offset:24
	ds_write_b64 v188, v[130:131] offset:32
	ds_write_b64 v188, v[132:133] offset:40
	ds_write_b64 v188, v[176:177] offset:48
	ds_write_b64 v188, v[180:181] offset:56
	ds_write_b64 v188, v[120:121] offset:64
	ds_write_b64 v188, v[122:123] offset:72
	ds_write_b64 v188, v[112:113] offset:80
	ds_write_b64 v188, v[178:179] offset:88
	ds_write_b64 v188, v[104:105] offset:96
	ds_write_b64 v188, v[106:107] offset:104
	ds_write_b64 v188, v[108:109] offset:112
	ds_write_b64 v188, v[110:111] offset:120
	v_mov_b32_e32 v104, v208
	s_waitcnt lgkmcnt(0)
	s_barrier
	s_nop 0
	v_lshlrev_b32_e32 v105, 4, v104
	v_ashrrev_i32_e32 v105, 1, v105
	v_lshlrev_b32_e32 v104, 7, v104
	v_add3_u32 v180, s35, v105, v104
	ds_read_b64 v[104:105], v180
	ds_read_b64 v[106:107], v180 offset:8
	ds_read_b64 v[108:109], v180 offset:16
	ds_read_b64 v[110:111], v180 offset:24
	ds_read_b64 v[112:113], v180 offset:64
	ds_read_b64 v[114:115], v180 offset:72
	ds_read_b64 v[116:117], v180 offset:32
	ds_read_b64 v[118:119], v180 offset:40
	ds_read_b64 v[120:121], v180 offset:48
	ds_read_b64 v[122:123], v180 offset:56
	ds_read_b64 v[124:125], v180 offset:96
	ds_read_b64 v[126:127], v180 offset:104
	ds_read_b64 v[128:129], v180 offset:80
	ds_read_b64 v[130:131], v180 offset:88
	ds_read_b64 v[132:133], v180 offset:112
	ds_read_b64 v[134:135], v180 offset:120
	s_waitcnt lgkmcnt(10)
	v_pk_add_f32 v[176:177], v[104:105], v[112:113]
	v_pk_add_f32 v[104:105], v[104:105], v[112:113] neg_lo:[0,1] neg_hi:[0,1]
	s_waitcnt lgkmcnt(4)
	v_pk_add_f32 v[112:113], v[116:117], v[124:125]
	v_pk_add_f32 v[116:117], v[116:117], v[124:125] neg_lo:[0,1] neg_hi:[0,1]
	s_nop 0
	v_xor_b32_e32 v124, 0x80000000, v117
	v_mov_b32_e32 v125, v116
	v_pk_add_f32 v[116:117], v[176:177], v[112:113]
	v_pk_add_f32 v[112:113], v[176:177], v[112:113] neg_lo:[0,1] neg_hi:[0,1]
	v_pk_add_f32 v[176:177], v[104:105], v[124:125]
	v_pk_add_f32 v[104:105], v[104:105], v[124:125] neg_lo:[0,1] neg_hi:[0,1]
	v_pk_add_f32 v[124:125], v[106:107], v[114:115]
	v_pk_add_f32 v[106:107], v[106:107], v[114:115] neg_lo:[0,1] neg_hi:[0,1]
	v_pk_add_f32 v[114:115], v[118:119], v[126:127]
	v_pk_add_f32 v[118:119], v[118:119], v[126:127] neg_lo:[0,1] neg_hi:[0,1]
	s_nop 0
	v_xor_b32_e32 v126, 0x80000000, v119
	v_mov_b32_e32 v127, v118
	v_pk_add_f32 v[118:119], v[124:125], v[114:115]
	v_pk_add_f32 v[114:115], v[124:125], v[114:115] neg_lo:[0,1] neg_hi:[0,1]
	v_pk_add_f32 v[124:125], v[106:107], v[126:127]
	v_pk_add_f32 v[106:107], v[106:107], v[126:127] neg_lo:[0,1] neg_hi:[0,1]
	s_waitcnt lgkmcnt(2)
	v_pk_add_f32 v[126:127], v[108:109], v[128:129]
	v_pk_add_f32 v[108:109], v[108:109], v[128:129] neg_lo:[0,1] neg_hi:[0,1]
	s_waitcnt lgkmcnt(0)
	v_pk_add_f32 v[128:129], v[120:121], v[132:133]
	v_pk_add_f32 v[120:121], v[120:121], v[132:133] neg_lo:[0,1] neg_hi:[0,1]
	s_nop 0
	v_xor_b32_e32 v132, 0x80000000, v121
	v_mov_b32_e32 v133, v120
	v_pk_add_f32 v[120:121], v[126:127], v[128:129]
	v_pk_add_f32 v[126:127], v[126:127], v[128:129] neg_lo:[0,1] neg_hi:[0,1]
	v_pk_add_f32 v[128:129], v[108:109], v[132:133]
	v_pk_add_f32 v[108:109], v[108:109], v[132:133] neg_lo:[0,1] neg_hi:[0,1]
	v_pk_add_f32 v[132:133], v[110:111], v[130:131]
	v_pk_add_f32 v[110:111], v[110:111], v[130:131] neg_lo:[0,1] neg_hi:[0,1]
	v_pk_add_f32 v[130:131], v[122:123], v[134:135]
	v_pk_add_f32 v[122:123], v[122:123], v[134:135] neg_lo:[0,1] neg_hi:[0,1]
	s_nop 0
	v_xor_b32_e32 v134, 0x80000000, v123
	v_mov_b32_e32 v135, v122
	v_pk_add_f32 v[122:123], v[132:133], v[130:131]
	v_pk_add_f32 v[130:131], v[132:133], v[130:131] neg_lo:[0,1] neg_hi:[0,1]
	v_pk_add_f32 v[132:133], v[110:111], v[134:135]
	v_pk_add_f32 v[110:111], v[110:111], v[134:135] neg_lo:[0,1] neg_hi:[0,1]
	v_pk_mul_f32 v[134:135], v[124:125], s[30:31] op_sel_hi:[1,0]
	s_nop 0
	v_pk_fma_f32 v[178:179], v[124:125], s[22:23], v[134:135] op_sel:[0,0,1] op_sel_hi:[1,0,0] neg_lo:[0,0,1] neg_hi:[0,0,1]
	v_pk_fma_f32 v[124:125], v[124:125], s[22:23], v[134:135] op_sel:[0,0,1] op_sel_hi:[1,0,0]
	s_nop 0
	v_mov_b32_e32 v179, v125
	v_pk_mul_f32 v[124:125], v[114:115], s[24:25] op_sel_hi:[1,0]
	s_nop 0
	v_pk_fma_f32 v[134:135], v[114:115], s[24:25], v[124:125] op_sel:[0,0,1] op_sel_hi:[1,0,0] neg_lo:[0,0,1] neg_hi:[0,0,1]
	v_pk_fma_f32 v[114:115], v[114:115], s[24:25], v[124:125] op_sel_hi:[1,0,0]
	s_nop 0
	v_mov_b32_e32 v135, v115
	v_pk_mul_f32 v[114:115], v[106:107], s[22:23] op_sel_hi:[1,0]
	s_nop 0
	v_pk_fma_f32 v[124:125], v[106:107], s[30:31], v[114:115] op_sel:[0,0,1] op_sel_hi:[1,0,0] neg_lo:[0,0,1] neg_hi:[0,0,1]
	v_pk_fma_f32 v[106:107], v[106:107], s[30:31], v[114:115] op_sel:[0,0,1] op_sel_hi:[1,0,0]
	s_nop 0
	v_mov_b32_e32 v125, v107
	v_pk_mul_f32 v[106:107], v[128:129], s[24:25] op_sel_hi:[1,0]
	s_nop 0
	v_pk_fma_f32 v[114:115], v[128:129], s[24:25], v[106:107] op_sel:[0,0,1] op_sel_hi:[1,0,0] neg_lo:[0,0,1] neg_hi:[0,0,1]
	v_pk_fma_f32 v[106:107], v[128:129], s[24:25], v[106:107] op_sel_hi:[1,0,0]
	s_nop 0
	v_mov_b32_e32 v115, v107
	v_mov_b32_e32 v107, v126
	v_mul_f32_e32 v126, 0x3f3504f3, v109
	v_xor_b32_e32 v106, 0x80000000, v127
	v_pk_fma_f32 v[108:109], v[108:109], s[18:19], v[126:127] op_sel_hi:[0,1,0] neg_lo:[0,0,1] neg_hi:[0,0,1]
	v_pk_mul_f32 v[126:127], v[132:133], s[22:23] op_sel_hi:[1,0]
	s_nop 0
	v_pk_fma_f32 v[128:129], v[132:133], s[30:31], v[126:127] op_sel:[0,0,1] op_sel_hi:[1,0,0] neg_lo:[0,0,1] neg_hi:[0,0,1]
	v_pk_fma_f32 v[126:127], v[132:133], s[30:31], v[126:127] op_sel:[0,0,1] op_sel_hi:[1,0,0]
	s_nop 0
	v_mul_f32_e32 v126, 0x3f3504f3, v131
	v_mov_b32_e32 v129, v127
	v_pk_fma_f32 v[126:127], v[130:131], s[18:19], v[126:127] op_sel_hi:[0,1,0] neg_lo:[0,0,1] neg_hi:[0,0,1]
	v_pk_mul_f32 v[130:131], v[110:111], s[88:89]
	v_pk_add_f32 v[132:133], v[178:179], v[128:129]
	v_pk_fma_f32 v[110:111], v[110:111], s[22:23], v[130:131] op_sel:[0,0,1] op_sel_hi:[1,0,0] neg_lo:[1,0,0] neg_hi:[1,0,0]
	v_pk_add_f32 v[130:131], v[116:117], v[120:121]
	v_pk_add_f32 v[116:117], v[116:117], v[120:121] neg_lo:[0,1] neg_hi:[0,1]
	v_pk_add_f32 v[120:121], v[118:119], v[122:123]
	v_pk_add_f32 v[118:119], v[118:119], v[122:123] neg_lo:[0,1] neg_hi:[0,1]
	v_pk_add_f32 v[128:129], v[178:179], v[128:129] neg_lo:[0,1] neg_hi:[0,1]
	v_xor_b32_e32 v122, 0x80000000, v119
	v_mov_b32_e32 v123, v118
	v_pk_add_f32 v[118:119], v[130:131], v[120:121]
	v_pk_add_f32 v[120:121], v[130:131], v[120:121] neg_lo:[0,1] neg_hi:[0,1]
	v_pk_add_f32 v[130:131], v[116:117], v[122:123]
	v_pk_add_f32 v[116:117], v[116:117], v[122:123] neg_lo:[0,1] neg_hi:[0,1]
	v_pk_add_f32 v[122:123], v[176:177], v[114:115]
	v_pk_add_f32 v[114:115], v[176:177], v[114:115] neg_lo:[0,1] neg_hi:[0,1]
	v_xor_b32_e32 v176, 0x80000000, v129
	v_mov_b32_e32 v177, v128
	v_pk_add_f32 v[128:129], v[122:123], v[132:133]
	v_pk_add_f32 v[122:123], v[122:123], v[132:133] neg_lo:[0,1] neg_hi:[0,1]
	v_pk_add_f32 v[132:133], v[114:115], v[176:177]
	v_pk_add_f32 v[114:115], v[114:115], v[176:177] neg_lo:[0,1] neg_hi:[0,1]
	v_pk_add_f32 v[176:177], v[112:113], v[106:107]
	v_pk_add_f32 v[106:107], v[112:113], v[106:107] neg_lo:[0,1] neg_hi:[0,1]
	v_pk_add_f32 v[112:113], v[134:135], v[126:127]
	v_pk_add_f32 v[126:127], v[134:135], v[126:127] neg_lo:[0,1] neg_hi:[0,1]
	s_nop 0
	v_xor_b32_e32 v134, 0x80000000, v127
	v_mov_b32_e32 v135, v126
	v_pk_add_f32 v[126:127], v[176:177], v[112:113]
	v_pk_add_f32 v[112:113], v[176:177], v[112:113] neg_lo:[0,1] neg_hi:[0,1]
	v_pk_add_f32 v[176:177], v[106:107], v[134:135]
	v_pk_add_f32 v[106:107], v[106:107], v[134:135] neg_lo:[0,1] neg_hi:[0,1]
	v_pk_add_f32 v[134:135], v[104:105], v[108:109]
	v_pk_add_f32 v[104:105], v[104:105], v[108:109] neg_lo:[0,1] neg_hi:[0,1]
	v_pk_add_f32 v[108:109], v[124:125], v[110:111]
	v_pk_add_f32 v[110:111], v[124:125], v[110:111] neg_lo:[0,1] neg_hi:[0,1]
	s_nop 0
	v_xor_b32_e32 v124, 0x80000000, v111
	v_mov_b32_e32 v125, v110
	v_pk_add_f32 v[110:111], v[134:135], v[108:109]
	v_pk_add_f32 v[108:109], v[134:135], v[108:109] neg_lo:[0,1] neg_hi:[0,1]
	v_pk_add_f32 v[134:135], v[104:105], v[124:125]
	v_pk_add_f32 v[104:105], v[104:105], v[124:125] neg_lo:[0,1] neg_hi:[0,1]
	ds_write_b64 v180, v[118:119]
	ds_write_b64 v180, v[128:129] offset:8
	ds_write_b64 v180, v[126:127] offset:16
	ds_write_b64 v180, v[110:111] offset:24
	ds_write_b64 v180, v[130:131] offset:32
	ds_write_b64 v180, v[132:133] offset:40
	ds_write_b64 v180, v[176:177] offset:48
	ds_write_b64 v180, v[134:135] offset:56
	ds_write_b64 v180, v[120:121] offset:64
	ds_write_b64 v180, v[122:123] offset:72
	ds_write_b64 v180, v[112:113] offset:80
	ds_write_b64 v180, v[108:109] offset:88
	ds_write_b64 v180, v[116:117] offset:96
	ds_write_b64 v180, v[114:115] offset:104
	ds_write_b64 v180, v[106:107] offset:112
	ds_write_b64 v180, v[104:105] offset:120
	v_mov_b32_e32 v104, v208
	s_waitcnt lgkmcnt(0)
	s_nop 0
	v_and_b32_e32 v128, 15, v104
	v_lshlrev_b32_e32 v106, 3, v128
	v_cvt_f32_ubyte0_e32 v128, v128
	v_mul_f32_e32 v205, 0x3b800000, v128
	v_mul_f32_e32 v128, 0x41400000, v205
	v_sin_f32_e32 v176, v128
	v_sin_f32_e32 v178, v205
	v_cos_f32_e32 v177, v128
	v_cos_f32_e32 v180, v205
	v_lshlrev_b32_e32 v104, 4, v104
	v_and_b32_e32 v104, 0xffffff00, v104
	v_pk_mul_f32 v[182:183], v[178:179], v[176:177] op_sel_hi:[0,1]
	v_ashrrev_i32_e32 v105, 1, v104
	v_pk_fma_f32 v[184:185], v[180:181], v[176:177], v[182:183] op_sel:[0,0,1] op_sel_hi:[0,1,0]
	v_pk_fma_f32 v[182:183], v[180:181], v[176:177], v[182:183] op_sel:[0,0,1] op_sel_hi:[0,1,0] neg_lo:[0,0,1] neg_hi:[0,0,1]
	v_add_u32_e32 v105, s35, v105
	v_lshlrev_b32_e32 v104, 3, v104
	v_pk_mov_b32 v[188:189], v[182:183], v[184:185] op_sel:[1,0]
	v_add3_u32 v204, v105, v104, v106
	v_mov_b32_e32 v186, v184
	v_mov_b32_e32 v187, v183
	v_pk_mul_f32 v[188:189], v[178:179], v[188:189] op_sel_hi:[0,1]
	v_mov_b32_e32 v179, v180
	ds_read_b64 v[104:105], v204
	ds_read_b64 v[106:107], v204 offset:136
	ds_read_b64 v[108:109], v204 offset:272
	ds_read_b64 v[110:111], v204 offset:408
	ds_read_b64 v[112:113], v204 offset:544
	ds_read_b64 v[114:115], v204 offset:680
	ds_read_b64 v[116:117], v204 offset:816
	ds_read_b64 v[118:119], v204 offset:952
	ds_read_b64 v[120:121], v204 offset:1088
	ds_read_b64 v[122:123], v204 offset:1224
	ds_read_b64 v[124:125], v204 offset:1360
	ds_read_b64 v[126:127], v204 offset:1496
	v_pk_fma_f32 v[190:191], v[180:181], v[186:187], v[188:189] op_sel_hi:[0,1,1]
	v_pk_fma_f32 v[186:187], v[180:181], v[186:187], v[188:189] op_sel_hi:[0,1,1] neg_lo:[0,0,1] neg_hi:[0,0,1]
	v_mov_b32_e32 v181, v178
	s_waitcnt lgkmcnt(10)
	v_pk_mul_f32 v[194:195], v[106:107], v[178:179] op_sel_hi:[1,0]
	ds_read_b64 v[128:129], v204 offset:1632
	ds_read_b64 v[130:131], v204 offset:1768
	ds_read_b64 v[132:133], v204 offset:1904
	ds_read_b64 v[134:135], v204 offset:2040
	v_pk_fma_f32 v[196:197], v[106:107], v[180:181], v[194:195] op_sel:[0,0,1] op_sel_hi:[1,1,0] neg_lo:[0,0,1] neg_hi:[0,0,1]
	v_pk_fma_f32 v[106:107], v[106:107], v[180:181], v[194:195] op_sel:[0,0,1] op_sel_hi:[1,0,0]
	v_mov_b32_e32 v188, v190
	v_mov_b32_e32 v197, v107
	v_pk_mul_f32 v[106:107], v[178:179], v[178:179] op_sel:[0,1] op_sel_hi:[0,0]
	v_pk_fma_f32 v[194:195], v[180:181], v[178:179], v[106:107] op_sel_hi:[0,1,1]
	v_pk_fma_f32 v[106:107], v[180:181], v[178:179], v[106:107] op_sel_hi:[0,1,1] neg_lo:[0,0,1] neg_hi:[0,0,1]
	v_mov_b32_e32 v198, v194
	v_mov_b32_e32 v199, v107
	s_waitcnt lgkmcnt(12)
	v_pk_mul_f32 v[194:195], v[108:109], v[194:195] op_sel:[1,0] op_sel_hi:[0,0]
	v_pk_fma_f32 v[200:201], v[108:109], v[106:107], v[194:195] op_sel:[0,1,0] neg_lo:[0,0,1] neg_hi:[0,0,1]
	v_pk_fma_f32 v[106:107], v[108:109], v[106:107], v[194:195] op_sel:[0,1,0]
	v_pk_mul_f32 v[108:109], v[178:179], v[198:199] op_sel:[1,0] op_sel_hi:[0,1]
	v_mov_b32_e32 v201, v107
	v_pk_mul_f32 v[106:107], v[178:179], v[198:199]
	v_pk_add_f32 v[108:109], v[108:109], v[108:109] op_sel:[0,1] op_sel_hi:[0,1]
	v_pk_mul_f32 v[108:109], v[110:111], v[108:109] op_sel:[1,0] op_sel_hi:[0,1]
	v_pk_add_f32 v[106:107], v[106:107], v[106:107] op_sel:[1,0] op_sel_hi:[1,0] neg_lo:[0,1] neg_hi:[0,1]
	v_mov_b32_e32 v189, v187
	v_pk_fma_f32 v[194:195], v[110:111], v[106:107], v[108:109] neg_lo:[0,0,1] neg_hi:[0,0,1]
	v_pk_fma_f32 v[106:107], v[110:111], v[106:107], v[108:109]
	v_mul_f32_e32 v195, 4.0, v205
	v_sin_f32_e32 v198, v195
	v_cos_f32_e32 v202, v195
	v_mov_b32_e32 v195, v107
	v_pk_mul_f32 v[192:193], v[180:181], v[188:189]
	s_waitcnt lgkmcnt(10)
	v_pk_mul_f32 v[106:107], v[198:199], v[112:113] op_sel:[0,1] op_sel_hi:[0,0]
	v_pk_fma_f32 v[108:109], v[202:203], v[112:113], v[106:107] neg_lo:[0,0,1] neg_hi:[0,0,1]
	v_pk_fma_f32 v[106:107], v[202:203], v[112:113], v[106:107] op_sel_hi:[0,1,1]
	v_mov_b32_e32 v199, v202
	v_mov_b32_e32 v109, v107
	v_pk_mul_f32 v[106:107], v[178:179], v[198:199] op_sel_hi:[0,1]
	v_pk_fma_f32 v[110:111], v[180:181], v[198:199], v[106:107] op_sel:[0,0,1] op_sel_hi:[0,1,0]
	v_pk_fma_f32 v[106:107], v[180:181], v[198:199], v[106:107] op_sel:[0,0,1] op_sel_hi:[0,1,0] neg_lo:[0,0,1] neg_hi:[0,0,1]
	v_pk_mul_f32 v[198:199], v[110:111], v[114:115] op_sel:[0,1] op_sel_hi:[0,0]
	v_mov_b32_e32 v112, v110
	v_mov_b32_e32 v113, v107
	v_pk_mov_b32 v[110:111], v[106:107], v[110:111] op_sel:[1,0]
	v_pk_fma_f32 v[202:203], v[106:107], v[114:115], v[198:199] op_sel:[1,0,0] neg_lo:[0,0,1] neg_hi:[0,0,1]
	v_pk_fma_f32 v[106:107], v[106:107], v[114:115], v[198:199] op_sel:[1,0,0]
	v_pk_mul_f32 v[188:189], v[178:179], v[188:189]
	v_mov_b32_e32 v203, v107
	v_pk_mul_f32 v[106:107], v[178:179], v[110:111] op_sel_hi:[0,1]
	v_pk_fma_f32 v[110:111], v[180:181], v[112:113], v[106:107] op_sel_hi:[0,1,1]
	v_pk_fma_f32 v[106:107], v[180:181], v[112:113], v[106:107] op_sel_hi:[0,1,1] neg_lo:[0,0,1] neg_hi:[0,0,1]
	v_mov_b32_e32 v112, v110
	v_mov_b32_e32 v113, v107
	s_waitcnt lgkmcnt(8)
	v_pk_mul_f32 v[110:111], v[116:117], v[110:111] op_sel:[1,0] op_sel_hi:[0,0]
	v_pk_fma_f32 v[114:115], v[116:117], v[106:107], v[110:111] op_sel:[0,1,0] neg_lo:[0,0,1] neg_hi:[0,0,1]
	v_pk_fma_f32 v[106:107], v[116:117], v[106:107], v[110:111] op_sel:[0,1,0]
	v_pk_mul_f32 v[110:111], v[180:181], v[112:113]
	v_mov_b32_e32 v115, v107
	v_pk_mul_f32 v[106:107], v[178:179], v[112:113]
	v_pk_add_f32 v[110:111], v[110:111], v[110:111] op_sel:[0,1] op_sel_hi:[0,1]
	v_pk_mul_f32 v[110:111], v[118:119], v[110:111] op_sel:[1,0] op_sel_hi:[0,1]
	v_pk_add_f32 v[106:107], v[106:107], v[106:107] op_sel:[1,0] op_sel_hi:[1,0] neg_lo:[0,1] neg_hi:[0,1]
	s_nop 0
	v_pk_fma_f32 v[112:113], v[118:119], v[106:107], v[110:111] neg_lo:[0,0,1] neg_hi:[0,0,1]
	v_pk_fma_f32 v[106:107], v[118:119], v[106:107], v[110:111]
	v_mul_f32_e32 v113, 0x41000000, v205
	v_sin_f32_e32 v116, v113
	v_cos_f32_e32 v198, v113
	v_mov_b32_e32 v113, v107
	s_waitcnt lgkmcnt(6)
	v_pk_mul_f32 v[106:107], v[116:117], v[120:121] op_sel:[0,1] op_sel_hi:[0,0]
	v_pk_fma_f32 v[110:111], v[198:199], v[120:121], v[106:107] neg_lo:[0,0,1] neg_hi:[0,0,1]
	v_pk_fma_f32 v[106:107], v[198:199], v[120:121], v[106:107] op_sel_hi:[0,1,1]
	v_mov_b32_e32 v117, v198
	v_mov_b32_e32 v111, v107
	v_pk_mul_f32 v[106:107], v[178:179], v[116:117] op_sel_hi:[0,1]
	v_pk_fma_f32 v[118:119], v[180:181], v[116:117], v[106:107] op_sel:[0,0,1] op_sel_hi:[0,1,0]
	v_pk_fma_f32 v[106:107], v[180:181], v[116:117], v[106:107] op_sel:[0,0,1] op_sel_hi:[0,1,0] neg_lo:[0,0,1] neg_hi:[0,0,1]
	v_pk_mul_f32 v[120:121], v[118:119], v[122:123] op_sel:[0,1] op_sel_hi:[0,0]
	v_mov_b32_e32 v116, v118
	v_mov_b32_e32 v117, v107
	v_pk_mov_b32 v[118:119], v[106:107], v[118:119] op_sel:[1,0]
	v_pk_fma_f32 v[198:199], v[106:107], v[122:123], v[120:121] op_sel:[1,0,0] neg_lo:[0,0,1] neg_hi:[0,0,1]
	v_pk_fma_f32 v[106:107], v[106:107], v[122:123], v[120:121] op_sel:[1,0,0]
	v_mov_b32_e32 v122, v177
	v_mov_b32_e32 v199, v107
	v_pk_mul_f32 v[106:107], v[178:179], v[118:119] op_sel_hi:[0,1]
	v_pk_fma_f32 v[118:119], v[180:181], v[116:117], v[106:107] op_sel_hi:[0,1,1]
	v_pk_fma_f32 v[106:107], v[180:181], v[116:117], v[106:107] op_sel_hi:[0,1,1] neg_lo:[0,0,1] neg_hi:[0,0,1]
	v_mov_b32_e32 v116, v118
	s_waitcnt lgkmcnt(4)
	v_pk_mul_f32 v[118:119], v[118:119], v[124:125] op_sel:[0,1] op_sel_hi:[0,0]
	v_mov_b32_e32 v117, v107
	v_pk_fma_f32 v[120:121], v[106:107], v[124:125], v[118:119] op_sel:[1,0,0] neg_lo:[0,0,1] neg_hi:[0,0,1]
	v_pk_fma_f32 v[106:107], v[106:107], v[124:125], v[118:119] op_sel:[1,0,0]
	s_nop 0
	v_mov_b32_e32 v121, v107
	v_pk_mul_f32 v[106:107], v[178:179], v[116:117]
	v_pk_mul_f32 v[116:117], v[180:181], v[116:117]
	v_pk_add_f32 v[106:107], v[106:107], v[106:107] op_sel:[1,0] op_sel_hi:[1,0] neg_lo:[0,1] neg_hi:[0,1]
	v_pk_add_f32 v[116:117], v[116:117], v[116:117] op_sel:[0,1] op_sel_hi:[0,1]
	v_pk_mul_f32 v[116:117], v[116:117], v[126:127] op_sel:[0,1] op_sel_hi:[1,0]
	s_nop 0
	v_pk_fma_f32 v[118:119], v[106:107], v[126:127], v[116:117] neg_lo:[0,0,1] neg_hi:[0,0,1]
	v_pk_fma_f32 v[106:107], v[106:107], v[126:127], v[116:117]
	v_mov_b32_e32 v116, v177
	v_mov_b32_e32 v119, v107
	s_waitcnt lgkmcnt(2)
	v_pk_mul_f32 v[106:107], v[176:177], v[128:129] op_sel:[0,1] op_sel_hi:[0,0]
	v_pk_fma_f32 v[116:117], v[116:117], v[128:129], v[106:107] neg_lo:[0,0,1] neg_hi:[0,0,1]
	v_pk_fma_f32 v[106:107], v[122:123], v[128:129], v[106:107] op_sel_hi:[0,1,1]
	v_mov_b32_e32 v117, v107
	v_pk_mul_f32 v[106:107], v[184:185], v[130:131] op_sel:[0,1] op_sel_hi:[0,0]
	v_pk_fma_f32 v[122:123], v[182:183], v[130:131], v[106:107] op_sel:[1,0,0] neg_lo:[0,0,1] neg_hi:[0,0,1]
	v_pk_fma_f32 v[106:107], v[182:183], v[130:131], v[106:107] op_sel:[1,0,0]
	v_pk_add_f32 v[126:127], v[192:193], v[192:193] op_sel:[0,1] op_sel_hi:[0,1]
	v_mov_b32_e32 v123, v107
	s_waitcnt lgkmcnt(0)
	v_pk_mul_f32 v[106:107], v[190:191], v[132:133] op_sel:[0,1] op_sel_hi:[0,0]
	v_pk_fma_f32 v[124:125], v[186:187], v[132:133], v[106:107] op_sel:[1,0,0] neg_lo:[0,0,1] neg_hi:[0,0,1]
	v_pk_fma_f32 v[106:107], v[186:187], v[132:133], v[106:107] op_sel:[1,0,0]
	v_pk_mul_f32 v[126:127], v[126:127], v[134:135] op_sel:[0,1] op_sel_hi:[1,0]
	v_mov_b32_e32 v125, v107
	v_pk_add_f32 v[106:107], v[188:189], v[188:189] op_sel:[1,0] op_sel_hi:[1,0] neg_lo:[0,1] neg_hi:[0,1]
	v_pk_add_f32 v[130:131], v[202:203], v[122:123]
	v_pk_fma_f32 v[128:129], v[106:107], v[134:135], v[126:127] neg_lo:[0,0,1] neg_hi:[0,0,1]
	v_pk_fma_f32 v[106:107], v[106:107], v[134:135], v[126:127]
	v_pk_add_f32 v[122:123], v[202:203], v[122:123] neg_lo:[0,1] neg_hi:[0,1]
	v_mov_b32_e32 v129, v107
	v_pk_add_f32 v[106:107], v[104:105], v[110:111]
	v_pk_add_f32 v[104:105], v[104:105], v[110:111] neg_lo:[0,1] neg_hi:[0,1]
	v_pk_add_f32 v[110:111], v[108:109], v[116:117]
	v_pk_add_f32 v[108:109], v[108:109], v[116:117] neg_lo:[0,1] neg_hi:[0,1]
	v_pk_add_f32 v[126:127], v[196:197], v[198:199] neg_lo:[0,1] neg_hi:[0,1]
	v_xor_b32_e32 v116, 0x80000000, v109
	v_mov_b32_e32 v117, v108
	v_pk_add_f32 v[108:109], v[106:107], v[110:111]
	v_pk_add_f32 v[106:107], v[106:107], v[110:111] neg_lo:[0,1] neg_hi:[0,1]
	v_pk_add_f32 v[110:111], v[104:105], v[116:117]
	v_pk_add_f32 v[104:105], v[104:105], v[116:117] neg_lo:[0,1] neg_hi:[0,1]
	v_pk_add_f32 v[116:117], v[196:197], v[198:199]
	v_xor_b32_e32 v132, 0x80000000, v123
	v_mov_b32_e32 v133, v122
	v_pk_add_f32 v[134:135], v[114:115], v[124:125]
	v_pk_add_f32 v[114:115], v[114:115], v[124:125] neg_lo:[0,1] neg_hi:[0,1]
	v_pk_add_f32 v[122:123], v[116:117], v[130:131]
	v_pk_add_f32 v[116:117], v[116:117], v[130:131] neg_lo:[0,1] neg_hi:[0,1]
	v_pk_add_f32 v[130:131], v[126:127], v[132:133]
	v_pk_add_f32 v[126:127], v[126:127], v[132:133] neg_lo:[0,1] neg_hi:[0,1]
	v_pk_add_f32 v[132:133], v[200:201], v[120:121]
	v_pk_add_f32 v[120:121], v[200:201], v[120:121] neg_lo:[0,1] neg_hi:[0,1]
	v_xor_b32_e32 v124, 0x80000000, v115
	v_mov_b32_e32 v125, v114
	v_pk_add_f32 v[176:177], v[112:113], v[128:129]
	v_pk_add_f32 v[112:113], v[112:113], v[128:129] neg_lo:[0,1] neg_hi:[0,1]
	v_pk_add_f32 v[114:115], v[132:133], v[134:135]
	v_pk_add_f32 v[132:133], v[132:133], v[134:135] neg_lo:[0,1] neg_hi:[0,1]
	v_pk_add_f32 v[134:135], v[120:121], v[124:125]
	v_pk_add_f32 v[120:121], v[120:121], v[124:125] neg_lo:[0,1] neg_hi:[0,1]
	v_pk_add_f32 v[124:125], v[194:195], v[118:119]
	v_pk_add_f32 v[118:119], v[194:195], v[118:119] neg_lo:[0,1] neg_hi:[0,1]
	v_xor_b32_e32 v128, 0x80000000, v113
	v_mov_b32_e32 v129, v112
	v_pk_add_f32 v[112:113], v[124:125], v[176:177]
	v_pk_add_f32 v[124:125], v[124:125], v[176:177] neg_lo:[0,1] neg_hi:[0,1]
	v_pk_add_f32 v[176:177], v[118:119], v[128:129]
	v_pk_add_f32 v[118:119], v[118:119], v[128:129] neg_lo:[0,1] neg_hi:[0,1]
	v_pk_mul_f32 v[128:129], v[130:131], s[30:31] op_sel_hi:[1,0]
	s_nop 0
	v_pk_fma_f32 v[178:179], v[130:131], s[22:23], v[128:129] op_sel:[0,0,1] op_sel_hi:[1,0,0] neg_lo:[0,0,1] neg_hi:[0,0,1]
	v_pk_fma_f32 v[128:129], v[130:131], s[22:23], v[128:129] op_sel:[0,0,1] op_sel_hi:[1,0,0]
	s_nop 0
	v_mov_b32_e32 v179, v129
	v_pk_mul_f32 v[128:129], v[116:117], s[24:25] op_sel_hi:[1,0]
	s_nop 0
	v_pk_fma_f32 v[130:131], v[116:117], s[24:25], v[128:129] op_sel:[0,0,1] op_sel_hi:[1,0,0] neg_lo:[0,0,1] neg_hi:[0,0,1]
	v_pk_fma_f32 v[116:117], v[116:117], s[24:25], v[128:129] op_sel_hi:[1,0,0]
	s_nop 0
	v_mov_b32_e32 v131, v117
	v_pk_mul_f32 v[116:117], v[126:127], s[22:23] op_sel_hi:[1,0]
	s_nop 0
	v_pk_fma_f32 v[128:129], v[126:127], s[30:31], v[116:117] op_sel:[0,0,1] op_sel_hi:[1,0,0] neg_lo:[0,0,1] neg_hi:[0,0,1]
	v_pk_fma_f32 v[116:117], v[126:127], s[30:31], v[116:117] op_sel:[0,0,1] op_sel_hi:[1,0,0]
	s_nop 0
	v_mov_b32_e32 v129, v117
	v_pk_mul_f32 v[116:117], v[134:135], s[24:25] op_sel_hi:[1,0]
	s_nop 0
	v_pk_fma_f32 v[126:127], v[134:135], s[24:25], v[116:117] op_sel:[0,0,1] op_sel_hi:[1,0,0] neg_lo:[0,0,1] neg_hi:[0,0,1]
	v_pk_fma_f32 v[116:117], v[134:135], s[24:25], v[116:117] op_sel_hi:[1,0,0]
	s_nop 0
	v_mov_b32_e32 v127, v117
	v_mov_b32_e32 v117, v132
	v_mul_f32_e32 v132, 0x3f3504f3, v121
	v_xor_b32_e32 v116, 0x80000000, v133
	v_pk_fma_f32 v[120:121], v[120:121], s[18:19], v[132:133] op_sel_hi:[0,1,0] neg_lo:[0,0,1] neg_hi:[0,0,1]
	v_pk_mul_f32 v[132:133], v[176:177], s[22:23] op_sel_hi:[1,0]
	s_nop 0
	v_pk_fma_f32 v[134:135], v[176:177], s[30:31], v[132:133] op_sel:[0,0,1] op_sel_hi:[1,0,0] neg_lo:[0,0,1] neg_hi:[0,0,1]
	v_pk_fma_f32 v[132:133], v[176:177], s[30:31], v[132:133] op_sel:[0,0,1] op_sel_hi:[1,0,0]
	s_nop 0
	v_mul_f32_e32 v132, 0x3f3504f3, v125
	v_mov_b32_e32 v135, v133
	v_pk_fma_f32 v[124:125], v[124:125], s[18:19], v[132:133] op_sel_hi:[0,1,0] neg_lo:[0,0,1] neg_hi:[0,0,1]
	v_pk_mul_f32 v[132:133], v[118:119], s[88:89]
	s_nop 0
	v_pk_fma_f32 v[118:119], v[118:119], s[22:23], v[132:133] op_sel:[0,0,1] op_sel_hi:[1,0,0] neg_lo:[1,0,0] neg_hi:[1,0,0]
	v_pk_add_f32 v[132:133], v[108:109], v[114:115]
	v_pk_add_f32 v[108:109], v[108:109], v[114:115] neg_lo:[0,1] neg_hi:[0,1]
	v_pk_add_f32 v[114:115], v[122:123], v[112:113]
	v_pk_add_f32 v[112:113], v[122:123], v[112:113] neg_lo:[0,1] neg_hi:[0,1]
	s_nop 0
	v_xor_b32_e32 v122, 0x80000000, v113
	v_mov_b32_e32 v123, v112
	v_pk_add_f32 v[112:113], v[132:133], v[114:115]
	v_pk_add_f32 v[114:115], v[132:133], v[114:115] neg_lo:[0,1] neg_hi:[0,1]
	v_pk_add_f32 v[132:133], v[108:109], v[122:123]
	v_pk_add_f32 v[108:109], v[108:109], v[122:123] neg_lo:[0,1] neg_hi:[0,1]
	v_pk_add_f32 v[122:123], v[110:111], v[126:127]
	v_pk_add_f32 v[110:111], v[110:111], v[126:127] neg_lo:[0,1] neg_hi:[0,1]
	v_pk_add_f32 v[126:127], v[178:179], v[134:135]
	v_pk_add_f32 v[134:135], v[178:179], v[134:135] neg_lo:[0,1] neg_hi:[0,1]
	s_nop 0
	v_xor_b32_e32 v176, 0x80000000, v135
	v_mov_b32_e32 v177, v134
	v_pk_add_f32 v[134:135], v[122:123], v[126:127]
	v_pk_add_f32 v[122:123], v[122:123], v[126:127] neg_lo:[0,1] neg_hi:[0,1]
	v_pk_add_f32 v[126:127], v[110:111], v[176:177]
	v_pk_add_f32 v[110:111], v[110:111], v[176:177] neg_lo:[0,1] neg_hi:[0,1]
	v_pk_add_f32 v[176:177], v[106:107], v[116:117]
	v_pk_add_f32 v[106:107], v[106:107], v[116:117] neg_lo:[0,1] neg_hi:[0,1]
	v_pk_add_f32 v[116:117], v[130:131], v[124:125]
	v_pk_add_f32 v[124:125], v[130:131], v[124:125] neg_lo:[0,1] neg_hi:[0,1]
	s_nop 0
	v_xor_b32_e32 v130, 0x80000000, v125
	v_mov_b32_e32 v131, v124
	v_pk_add_f32 v[124:125], v[176:177], v[116:117]
	v_pk_add_f32 v[116:117], v[176:177], v[116:117] neg_lo:[0,1] neg_hi:[0,1]
	v_pk_add_f32 v[176:177], v[106:107], v[130:131]
	v_pk_add_f32 v[106:107], v[106:107], v[130:131] neg_lo:[0,1] neg_hi:[0,1]
	v_pk_add_f32 v[130:131], v[104:105], v[120:121]
	v_pk_add_f32 v[104:105], v[104:105], v[120:121] neg_lo:[0,1] neg_hi:[0,1]
	v_pk_add_f32 v[120:121], v[128:129], v[118:119]
	v_pk_add_f32 v[118:119], v[128:129], v[118:119] neg_lo:[0,1] neg_hi:[0,1]
	s_nop 0
	v_xor_b32_e32 v128, 0x80000000, v119
	v_mov_b32_e32 v129, v118
	v_pk_add_f32 v[118:119], v[130:131], v[120:121]
	v_pk_add_f32 v[120:121], v[130:131], v[120:121] neg_lo:[0,1] neg_hi:[0,1]
	v_pk_add_f32 v[130:131], v[104:105], v[128:129]
	v_pk_add_f32 v[104:105], v[104:105], v[128:129] neg_lo:[0,1] neg_hi:[0,1]
	v_mov_b32_e32 v128, v208
	ds_write_b64 v204, v[112:113]
	ds_write_b64 v204, v[134:135] offset:136
	ds_write_b64 v204, v[124:125] offset:272
	ds_write_b64 v204, v[118:119] offset:408
	ds_write_b64 v204, v[132:133] offset:544
	ds_write_b64 v204, v[126:127] offset:680
	ds_write_b64 v204, v[176:177] offset:816
	ds_write_b64 v204, v[130:131] offset:952
	ds_write_b64 v204, v[114:115] offset:1088
	ds_write_b64 v204, v[122:123] offset:1224
	ds_write_b64 v204, v[116:117] offset:1360
	ds_write_b64 v204, v[120:121] offset:1496
	ds_write_b64 v204, v[108:109] offset:1632
	ds_write_b64 v204, v[110:111] offset:1768
	ds_write_b64 v204, v[106:107] offset:1904
	ds_write_b64 v204, v[104:105] offset:2040
	s_waitcnt lgkmcnt(0)
	s_barrier
	s_nop 0
	v_and_b32_e32 v104, 0xff, v128
	v_lshlrev_b32_e32 v105, 4, v128
	v_cvt_f32_ubyte0_e32 v128, v128
	v_mul_f32_e32 v205, 0x39800000, v128
	v_mul_f32_e32 v129, 0x41400000, v205
	v_sin_f32_e32 v130, v129
	v_sin_f32_e32 v132, v205
	v_cos_f32_e32 v131, v129
	v_cos_f32_e32 v128, v205
	v_and_or_b32 v104, v105, s93, v104
	v_ashrrev_i32_e32 v105, 4, v104
	v_pk_mul_f32 v[182:183], v[132:133], v[130:131] op_sel_hi:[0,1]
	v_pk_fma_f32 v[184:185], v[128:129], v[130:131], v[182:183] op_sel:[0,0,1] op_sel_hi:[0,1,0]
	v_pk_fma_f32 v[182:183], v[128:129], v[130:131], v[182:183] op_sel:[0,0,1] op_sel_hi:[0,1,0] neg_lo:[0,0,1] neg_hi:[0,0,1]
	v_lshlrev_b32_e32 v105, 3, v105
	v_lshlrev_b32_e32 v104, 3, v104
	v_pk_mov_b32 v[188:189], v[182:183], v[184:185] op_sel:[1,0]
	v_add3_u32 v204, s35, v105, v104
	v_mov_b32_e32 v186, v184
	v_mov_b32_e32 v187, v183
	v_pk_mul_f32 v[188:189], v[132:133], v[188:189] op_sel_hi:[0,1]
	v_mov_b32_e32 v133, v128
	ds_read_b64 v[104:105], v204
	ds_read_b64 v[106:107], v204 offset:2176
	ds_read_b64 v[108:109], v204 offset:4352
	ds_read_b64 v[110:111], v204 offset:6528
	ds_read_b64 v[112:113], v204 offset:8704
	ds_read_b64 v[114:115], v204 offset:10880
	ds_read_b64 v[116:117], v204 offset:13056
	ds_read_b64 v[118:119], v204 offset:15232
	ds_read_b64 v[120:121], v204 offset:17408
	ds_read_b64 v[122:123], v204 offset:19584
	ds_read_b64 v[124:125], v204 offset:21760
	ds_read_b64 v[126:127], v204 offset:23936
	v_pk_fma_f32 v[190:191], v[128:129], v[186:187], v[188:189] op_sel_hi:[0,1,1]
	v_pk_fma_f32 v[186:187], v[128:129], v[186:187], v[188:189] op_sel_hi:[0,1,1] neg_lo:[0,0,1] neg_hi:[0,0,1]
	v_mov_b32_e32 v129, v132
	s_waitcnt lgkmcnt(10)
	v_pk_mul_f32 v[194:195], v[106:107], v[132:133] op_sel_hi:[1,0]
	ds_read_b64 v[134:135], v204 offset:26112
	ds_read_b64 v[176:177], v204 offset:28288
	ds_read_b64 v[178:179], v204 offset:30464
	ds_read_b64 v[180:181], v204 offset:32640
	v_pk_fma_f32 v[196:197], v[106:107], v[128:129], v[194:195] op_sel:[0,0,1] op_sel_hi:[1,1,0] neg_lo:[0,0,1] neg_hi:[0,0,1]
	v_pk_fma_f32 v[106:107], v[106:107], v[128:129], v[194:195] op_sel:[0,0,1] op_sel_hi:[1,0,0]
	v_mov_b32_e32 v188, v190
	v_mov_b32_e32 v197, v107
	v_pk_mul_f32 v[106:107], v[132:133], v[132:133] op_sel:[0,1] op_sel_hi:[0,0]
	v_pk_fma_f32 v[194:195], v[128:129], v[132:133], v[106:107] op_sel_hi:[0,1,1]
	v_pk_fma_f32 v[106:107], v[128:129], v[132:133], v[106:107] op_sel_hi:[0,1,1] neg_lo:[0,0,1] neg_hi:[0,0,1]
	v_mov_b32_e32 v198, v194
	v_mov_b32_e32 v199, v107
	s_waitcnt lgkmcnt(13)
	v_pk_mul_f32 v[194:195], v[108:109], v[194:195] op_sel:[1,0] op_sel_hi:[0,0]
	v_pk_fma_f32 v[200:201], v[108:109], v[106:107], v[194:195] op_sel:[0,1,0] neg_lo:[0,0,1] neg_hi:[0,0,1]
	v_pk_fma_f32 v[106:107], v[108:109], v[106:107], v[194:195] op_sel:[0,1,0]
	v_pk_mul_f32 v[108:109], v[132:133], v[198:199] op_sel:[1,0] op_sel_hi:[0,1]
	v_mov_b32_e32 v201, v107
	v_pk_mul_f32 v[106:107], v[132:133], v[198:199]
	v_pk_add_f32 v[108:109], v[108:109], v[108:109] op_sel:[0,1] op_sel_hi:[0,1]
	s_waitcnt lgkmcnt(12)
	v_pk_mul_f32 v[108:109], v[110:111], v[108:109] op_sel:[1,0] op_sel_hi:[0,1]
	v_pk_add_f32 v[106:107], v[106:107], v[106:107] op_sel:[1,0] op_sel_hi:[1,0] neg_lo:[0,1] neg_hi:[0,1]
	v_mov_b32_e32 v189, v187
	v_pk_fma_f32 v[194:195], v[110:111], v[106:107], v[108:109] neg_lo:[0,0,1] neg_hi:[0,0,1]
	v_pk_fma_f32 v[106:107], v[110:111], v[106:107], v[108:109]
	v_mul_f32_e32 v195, 4.0, v205
	v_sin_f32_e32 v198, v195
	v_cos_f32_e32 v202, v195
	v_mov_b32_e32 v195, v107
	v_pk_mul_f32 v[192:193], v[128:129], v[188:189]
	s_waitcnt lgkmcnt(11)
	v_pk_mul_f32 v[106:107], v[198:199], v[112:113] op_sel:[0,1] op_sel_hi:[0,0]
	v_pk_fma_f32 v[108:109], v[202:203], v[112:113], v[106:107] neg_lo:[0,0,1] neg_hi:[0,0,1]
	v_pk_fma_f32 v[106:107], v[202:203], v[112:113], v[106:107] op_sel_hi:[0,1,1]
	v_mov_b32_e32 v199, v202
	v_mov_b32_e32 v109, v107
	v_pk_mul_f32 v[106:107], v[132:133], v[198:199] op_sel_hi:[0,1]
	v_pk_fma_f32 v[110:111], v[128:129], v[198:199], v[106:107] op_sel:[0,0,1] op_sel_hi:[0,1,0]
	v_pk_fma_f32 v[106:107], v[128:129], v[198:199], v[106:107] op_sel:[0,0,1] op_sel_hi:[0,1,0] neg_lo:[0,0,1] neg_hi:[0,0,1]
	s_waitcnt lgkmcnt(10)
	v_pk_mul_f32 v[198:199], v[110:111], v[114:115] op_sel:[0,1] op_sel_hi:[0,0]
	v_mov_b32_e32 v112, v110
	v_mov_b32_e32 v113, v107
	v_pk_mov_b32 v[110:111], v[106:107], v[110:111] op_sel:[1,0]
	v_pk_fma_f32 v[202:203], v[106:107], v[114:115], v[198:199] op_sel:[1,0,0] neg_lo:[0,0,1] neg_hi:[0,0,1]
	v_pk_fma_f32 v[106:107], v[106:107], v[114:115], v[198:199] op_sel:[1,0,0]
	v_pk_mul_f32 v[188:189], v[132:133], v[188:189]
	v_mov_b32_e32 v203, v107
	v_pk_mul_f32 v[106:107], v[132:133], v[110:111] op_sel_hi:[0,1]
	v_pk_fma_f32 v[110:111], v[128:129], v[112:113], v[106:107] op_sel_hi:[0,1,1]
	v_pk_fma_f32 v[106:107], v[128:129], v[112:113], v[106:107] op_sel_hi:[0,1,1] neg_lo:[0,0,1] neg_hi:[0,0,1]
	v_mov_b32_e32 v112, v110
	v_mov_b32_e32 v113, v107
	s_waitcnt lgkmcnt(9)
	v_pk_mul_f32 v[110:111], v[116:117], v[110:111] op_sel:[1,0] op_sel_hi:[0,0]
	v_pk_fma_f32 v[114:115], v[116:117], v[106:107], v[110:111] op_sel:[0,1,0] neg_lo:[0,0,1] neg_hi:[0,0,1]
	v_pk_fma_f32 v[106:107], v[116:117], v[106:107], v[110:111] op_sel:[0,1,0]
	v_pk_mul_f32 v[110:111], v[128:129], v[112:113]
	v_mov_b32_e32 v115, v107
	v_pk_mul_f32 v[106:107], v[132:133], v[112:113]
	v_pk_add_f32 v[110:111], v[110:111], v[110:111] op_sel:[0,1] op_sel_hi:[0,1]
	s_waitcnt lgkmcnt(8)
	v_pk_mul_f32 v[110:111], v[118:119], v[110:111] op_sel:[1,0] op_sel_hi:[0,1]
	v_pk_add_f32 v[106:107], v[106:107], v[106:107] op_sel:[1,0] op_sel_hi:[1,0] neg_lo:[0,1] neg_hi:[0,1]
	s_nop 0
	v_pk_fma_f32 v[112:113], v[118:119], v[106:107], v[110:111] neg_lo:[0,0,1] neg_hi:[0,0,1]
	v_pk_fma_f32 v[106:107], v[118:119], v[106:107], v[110:111]
	v_mul_f32_e32 v113, 0x41000000, v205
	v_sin_f32_e32 v116, v113
	v_cos_f32_e32 v198, v113
	v_mov_b32_e32 v113, v107
	s_waitcnt lgkmcnt(7)
	v_pk_mul_f32 v[106:107], v[116:117], v[120:121] op_sel:[0,1] op_sel_hi:[0,0]
	v_pk_fma_f32 v[110:111], v[198:199], v[120:121], v[106:107] neg_lo:[0,0,1] neg_hi:[0,0,1]
	v_pk_fma_f32 v[106:107], v[198:199], v[120:121], v[106:107] op_sel_hi:[0,1,1]
	v_mov_b32_e32 v117, v198
	v_mov_b32_e32 v111, v107
	v_pk_mul_f32 v[106:107], v[132:133], v[116:117] op_sel_hi:[0,1]
	v_pk_fma_f32 v[118:119], v[128:129], v[116:117], v[106:107] op_sel:[0,0,1] op_sel_hi:[0,1,0]
	v_pk_fma_f32 v[106:107], v[128:129], v[116:117], v[106:107] op_sel:[0,0,1] op_sel_hi:[0,1,0] neg_lo:[0,0,1] neg_hi:[0,0,1]
	s_waitcnt lgkmcnt(6)
	v_pk_mul_f32 v[120:121], v[118:119], v[122:123] op_sel:[0,1] op_sel_hi:[0,0]
	v_mov_b32_e32 v116, v118
	v_mov_b32_e32 v117, v107
	v_pk_mov_b32 v[118:119], v[106:107], v[118:119] op_sel:[1,0]
	v_pk_fma_f32 v[198:199], v[106:107], v[122:123], v[120:121] op_sel:[1,0,0] neg_lo:[0,0,1] neg_hi:[0,0,1]
	v_pk_fma_f32 v[106:107], v[106:107], v[122:123], v[120:121] op_sel:[1,0,0]
	v_mov_b32_e32 v122, v131
	v_mov_b32_e32 v199, v107
	v_pk_mul_f32 v[106:107], v[132:133], v[118:119] op_sel_hi:[0,1]
	v_pk_fma_f32 v[118:119], v[128:129], v[116:117], v[106:107] op_sel_hi:[0,1,1]
	v_pk_fma_f32 v[106:107], v[128:129], v[116:117], v[106:107] op_sel_hi:[0,1,1] neg_lo:[0,0,1] neg_hi:[0,0,1]
	v_mov_b32_e32 v116, v118
	s_waitcnt lgkmcnt(5)
	v_pk_mul_f32 v[118:119], v[118:119], v[124:125] op_sel:[0,1] op_sel_hi:[0,0]
	v_mov_b32_e32 v117, v107
	v_pk_fma_f32 v[120:121], v[106:107], v[124:125], v[118:119] op_sel:[1,0,0] neg_lo:[0,0,1] neg_hi:[0,0,1]
	v_pk_fma_f32 v[106:107], v[106:107], v[124:125], v[118:119] op_sel:[1,0,0]
	s_nop 0
	v_mov_b32_e32 v121, v107
	v_pk_mul_f32 v[106:107], v[132:133], v[116:117]
	v_pk_mul_f32 v[116:117], v[128:129], v[116:117]
	v_pk_add_f32 v[106:107], v[106:107], v[106:107] op_sel:[1,0] op_sel_hi:[1,0] neg_lo:[0,1] neg_hi:[0,1]
	v_pk_add_f32 v[116:117], v[116:117], v[116:117] op_sel:[0,1] op_sel_hi:[0,1]
	s_waitcnt lgkmcnt(4)
	v_pk_mul_f32 v[116:117], v[116:117], v[126:127] op_sel:[0,1] op_sel_hi:[1,0]
	s_nop 0
	v_pk_fma_f32 v[118:119], v[106:107], v[126:127], v[116:117] neg_lo:[0,0,1] neg_hi:[0,0,1]
	v_pk_fma_f32 v[106:107], v[106:107], v[126:127], v[116:117]
	v_mov_b32_e32 v116, v131
	v_mov_b32_e32 v119, v107
	s_waitcnt lgkmcnt(3)
	v_pk_mul_f32 v[106:107], v[130:131], v[134:135] op_sel:[0,1] op_sel_hi:[0,0]
	v_pk_fma_f32 v[116:117], v[116:117], v[134:135], v[106:107] neg_lo:[0,0,1] neg_hi:[0,0,1]
	v_pk_fma_f32 v[106:107], v[122:123], v[134:135], v[106:107] op_sel_hi:[0,1,1]
	v_mov_b32_e32 v117, v107
	s_waitcnt lgkmcnt(2)
	v_pk_mul_f32 v[106:107], v[184:185], v[176:177] op_sel:[0,1] op_sel_hi:[0,0]
	v_pk_fma_f32 v[122:123], v[182:183], v[176:177], v[106:107] op_sel:[1,0,0] neg_lo:[0,0,1] neg_hi:[0,0,1]
	v_pk_fma_f32 v[106:107], v[182:183], v[176:177], v[106:107] op_sel:[1,0,0]
	v_pk_add_f32 v[126:127], v[192:193], v[192:193] op_sel:[0,1] op_sel_hi:[0,1]
	v_mov_b32_e32 v123, v107
	s_waitcnt lgkmcnt(1)
	v_pk_mul_f32 v[106:107], v[190:191], v[178:179] op_sel:[0,1] op_sel_hi:[0,0]
	v_pk_fma_f32 v[124:125], v[186:187], v[178:179], v[106:107] op_sel:[1,0,0] neg_lo:[0,0,1] neg_hi:[0,0,1]
	v_pk_fma_f32 v[106:107], v[186:187], v[178:179], v[106:107] op_sel:[1,0,0]
	s_waitcnt lgkmcnt(0)
	v_pk_mul_f32 v[126:127], v[126:127], v[180:181] op_sel:[0,1] op_sel_hi:[1,0]
	v_mov_b32_e32 v125, v107
	v_pk_add_f32 v[106:107], v[188:189], v[188:189] op_sel:[1,0] op_sel_hi:[1,0] neg_lo:[0,1] neg_hi:[0,1]
	v_pk_add_f32 v[130:131], v[202:203], v[122:123]
	v_pk_fma_f32 v[128:129], v[106:107], v[180:181], v[126:127] neg_lo:[0,0,1] neg_hi:[0,0,1]
	v_pk_fma_f32 v[106:107], v[106:107], v[180:181], v[126:127]
	v_pk_add_f32 v[122:123], v[202:203], v[122:123] neg_lo:[0,1] neg_hi:[0,1]
	v_mov_b32_e32 v129, v107
	v_pk_add_f32 v[106:107], v[104:105], v[110:111]
	v_pk_add_f32 v[104:105], v[104:105], v[110:111] neg_lo:[0,1] neg_hi:[0,1]
	v_pk_add_f32 v[110:111], v[108:109], v[116:117]
	v_pk_add_f32 v[108:109], v[108:109], v[116:117] neg_lo:[0,1] neg_hi:[0,1]
	v_pk_add_f32 v[126:127], v[196:197], v[198:199] neg_lo:[0,1] neg_hi:[0,1]
	v_xor_b32_e32 v116, 0x80000000, v109
	v_mov_b32_e32 v117, v108
	v_pk_add_f32 v[108:109], v[106:107], v[110:111]
	v_pk_add_f32 v[106:107], v[106:107], v[110:111] neg_lo:[0,1] neg_hi:[0,1]
	v_pk_add_f32 v[110:111], v[104:105], v[116:117]
	v_pk_add_f32 v[104:105], v[104:105], v[116:117] neg_lo:[0,1] neg_hi:[0,1]
	v_pk_add_f32 v[116:117], v[196:197], v[198:199]
	v_xor_b32_e32 v132, 0x80000000, v123
	v_mov_b32_e32 v133, v122
	v_pk_add_f32 v[134:135], v[114:115], v[124:125]
	v_pk_add_f32 v[114:115], v[114:115], v[124:125] neg_lo:[0,1] neg_hi:[0,1]
	v_pk_add_f32 v[122:123], v[116:117], v[130:131]
	v_pk_add_f32 v[116:117], v[116:117], v[130:131] neg_lo:[0,1] neg_hi:[0,1]
	v_pk_add_f32 v[130:131], v[126:127], v[132:133]
	v_pk_add_f32 v[126:127], v[126:127], v[132:133] neg_lo:[0,1] neg_hi:[0,1]
	v_pk_add_f32 v[132:133], v[200:201], v[120:121]
	v_pk_add_f32 v[120:121], v[200:201], v[120:121] neg_lo:[0,1] neg_hi:[0,1]
	v_xor_b32_e32 v124, 0x80000000, v115
	v_mov_b32_e32 v125, v114
	v_pk_add_f32 v[176:177], v[112:113], v[128:129]
	v_pk_add_f32 v[112:113], v[112:113], v[128:129] neg_lo:[0,1] neg_hi:[0,1]
	v_pk_add_f32 v[114:115], v[132:133], v[134:135]
	v_pk_add_f32 v[132:133], v[132:133], v[134:135] neg_lo:[0,1] neg_hi:[0,1]
	v_pk_add_f32 v[134:135], v[120:121], v[124:125]
	v_pk_add_f32 v[120:121], v[120:121], v[124:125] neg_lo:[0,1] neg_hi:[0,1]
	v_pk_add_f32 v[124:125], v[194:195], v[118:119]
	v_pk_add_f32 v[118:119], v[194:195], v[118:119] neg_lo:[0,1] neg_hi:[0,1]
	v_xor_b32_e32 v128, 0x80000000, v113
	v_mov_b32_e32 v129, v112
	v_pk_add_f32 v[112:113], v[124:125], v[176:177]
	v_pk_add_f32 v[124:125], v[124:125], v[176:177] neg_lo:[0,1] neg_hi:[0,1]
	v_pk_add_f32 v[176:177], v[118:119], v[128:129]
	v_pk_add_f32 v[118:119], v[118:119], v[128:129] neg_lo:[0,1] neg_hi:[0,1]
	v_pk_mul_f32 v[128:129], v[130:131], s[30:31] op_sel_hi:[1,0]
	s_nop 0
	v_pk_fma_f32 v[178:179], v[130:131], s[22:23], v[128:129] op_sel:[0,0,1] op_sel_hi:[1,0,0] neg_lo:[0,0,1] neg_hi:[0,0,1]
	v_pk_fma_f32 v[128:129], v[130:131], s[22:23], v[128:129] op_sel:[0,0,1] op_sel_hi:[1,0,0]
	s_nop 0
	v_mov_b32_e32 v179, v129
	v_pk_mul_f32 v[128:129], v[116:117], s[24:25] op_sel_hi:[1,0]
	s_nop 0
	v_pk_fma_f32 v[130:131], v[116:117], s[24:25], v[128:129] op_sel:[0,0,1] op_sel_hi:[1,0,0] neg_lo:[0,0,1] neg_hi:[0,0,1]
	v_pk_fma_f32 v[116:117], v[116:117], s[24:25], v[128:129] op_sel_hi:[1,0,0]
	s_nop 0
	v_mov_b32_e32 v131, v117
	v_pk_mul_f32 v[116:117], v[126:127], s[22:23] op_sel_hi:[1,0]
	s_nop 0
	v_pk_fma_f32 v[128:129], v[126:127], s[30:31], v[116:117] op_sel:[0,0,1] op_sel_hi:[1,0,0] neg_lo:[0,0,1] neg_hi:[0,0,1]
	v_pk_fma_f32 v[116:117], v[126:127], s[30:31], v[116:117] op_sel:[0,0,1] op_sel_hi:[1,0,0]
	s_nop 0
	v_mov_b32_e32 v129, v117
	v_pk_mul_f32 v[116:117], v[134:135], s[24:25] op_sel_hi:[1,0]
	s_nop 0
	v_pk_fma_f32 v[126:127], v[134:135], s[24:25], v[116:117] op_sel:[0,0,1] op_sel_hi:[1,0,0] neg_lo:[0,0,1] neg_hi:[0,0,1]
	v_pk_fma_f32 v[116:117], v[134:135], s[24:25], v[116:117] op_sel_hi:[1,0,0]
	s_nop 0
	v_mov_b32_e32 v127, v117
	v_mov_b32_e32 v117, v132
	v_mul_f32_e32 v132, 0x3f3504f3, v121
	v_xor_b32_e32 v116, 0x80000000, v133
	v_pk_fma_f32 v[120:121], v[120:121], s[18:19], v[132:133] op_sel_hi:[0,1,0] neg_lo:[0,0,1] neg_hi:[0,0,1]
	v_pk_mul_f32 v[132:133], v[176:177], s[22:23] op_sel_hi:[1,0]
	s_nop 0
	v_pk_fma_f32 v[134:135], v[176:177], s[30:31], v[132:133] op_sel:[0,0,1] op_sel_hi:[1,0,0] neg_lo:[0,0,1] neg_hi:[0,0,1]
	v_pk_fma_f32 v[132:133], v[176:177], s[30:31], v[132:133] op_sel:[0,0,1] op_sel_hi:[1,0,0]
	s_nop 0
	v_mul_f32_e32 v132, 0x3f3504f3, v125
	v_mov_b32_e32 v135, v133
	v_pk_fma_f32 v[124:125], v[124:125], s[18:19], v[132:133] op_sel_hi:[0,1,0] neg_lo:[0,0,1] neg_hi:[0,0,1]
	v_pk_mul_f32 v[132:133], v[118:119], s[88:89]
	s_nop 0
	v_pk_fma_f32 v[118:119], v[118:119], s[22:23], v[132:133] op_sel:[0,0,1] op_sel_hi:[1,0,0] neg_lo:[1,0,0] neg_hi:[1,0,0]
	v_pk_add_f32 v[132:133], v[108:109], v[114:115]
	v_pk_add_f32 v[108:109], v[108:109], v[114:115] neg_lo:[0,1] neg_hi:[0,1]
	v_pk_add_f32 v[114:115], v[122:123], v[112:113]
	v_pk_add_f32 v[112:113], v[122:123], v[112:113] neg_lo:[0,1] neg_hi:[0,1]
	s_nop 0
	v_xor_b32_e32 v122, 0x80000000, v113
	v_mov_b32_e32 v123, v112
	v_pk_add_f32 v[112:113], v[132:133], v[114:115]
	v_pk_add_f32 v[114:115], v[132:133], v[114:115] neg_lo:[0,1] neg_hi:[0,1]
	v_pk_add_f32 v[132:133], v[108:109], v[122:123]
	v_pk_add_f32 v[108:109], v[108:109], v[122:123] neg_lo:[0,1] neg_hi:[0,1]
	v_pk_add_f32 v[122:123], v[110:111], v[126:127]
	v_pk_add_f32 v[110:111], v[110:111], v[126:127] neg_lo:[0,1] neg_hi:[0,1]
	v_pk_add_f32 v[126:127], v[178:179], v[134:135]
	v_pk_add_f32 v[134:135], v[178:179], v[134:135] neg_lo:[0,1] neg_hi:[0,1]
	s_nop 0
	v_xor_b32_e32 v176, 0x80000000, v135
	v_mov_b32_e32 v177, v134
	v_pk_add_f32 v[134:135], v[122:123], v[126:127]
	v_pk_add_f32 v[122:123], v[122:123], v[126:127] neg_lo:[0,1] neg_hi:[0,1]
	v_pk_add_f32 v[126:127], v[110:111], v[176:177]
	v_pk_add_f32 v[110:111], v[110:111], v[176:177] neg_lo:[0,1] neg_hi:[0,1]
	v_pk_add_f32 v[176:177], v[106:107], v[116:117]
	v_pk_add_f32 v[106:107], v[106:107], v[116:117] neg_lo:[0,1] neg_hi:[0,1]
	v_pk_add_f32 v[116:117], v[130:131], v[124:125]
	v_pk_add_f32 v[124:125], v[130:131], v[124:125] neg_lo:[0,1] neg_hi:[0,1]
	s_nop 0
	v_xor_b32_e32 v130, 0x80000000, v125
	v_mov_b32_e32 v131, v124
	v_pk_add_f32 v[124:125], v[176:177], v[116:117]
	v_pk_add_f32 v[116:117], v[176:177], v[116:117] neg_lo:[0,1] neg_hi:[0,1]
	v_pk_add_f32 v[176:177], v[106:107], v[130:131]
	v_pk_add_f32 v[106:107], v[106:107], v[130:131] neg_lo:[0,1] neg_hi:[0,1]
	v_pk_add_f32 v[130:131], v[104:105], v[120:121]
	v_pk_add_f32 v[104:105], v[104:105], v[120:121] neg_lo:[0,1] neg_hi:[0,1]
	v_pk_add_f32 v[120:121], v[128:129], v[118:119]
	v_pk_add_f32 v[118:119], v[128:129], v[118:119] neg_lo:[0,1] neg_hi:[0,1]
	s_nop 0
	v_xor_b32_e32 v128, 0x80000000, v119
	v_mov_b32_e32 v129, v118
	v_pk_add_f32 v[118:119], v[130:131], v[120:121]
	v_pk_add_f32 v[120:121], v[130:131], v[120:121] neg_lo:[0,1] neg_hi:[0,1]
	v_pk_add_f32 v[130:131], v[104:105], v[128:129]
	v_pk_add_f32 v[104:105], v[104:105], v[128:129] neg_lo:[0,1] neg_hi:[0,1]
	ds_write_b64 v204, v[112:113]
	ds_write_b64 v204, v[134:135] offset:2176
	ds_write_b64 v204, v[124:125] offset:4352
	ds_write_b64 v204, v[118:119] offset:6528
	ds_write_b64 v204, v[132:133] offset:8704
	ds_write_b64 v204, v[126:127] offset:10880
	ds_write_b64 v204, v[176:177] offset:13056
	ds_write_b64 v204, v[130:131] offset:15232
	ds_write_b64 v204, v[114:115] offset:17408
	ds_write_b64 v204, v[122:123] offset:19584
	ds_write_b64 v204, v[116:117] offset:21760
	ds_write_b64 v204, v[120:121] offset:23936
	ds_write_b64 v204, v[108:109] offset:26112
	ds_write_b64 v204, v[110:111] offset:28288
	ds_write_b64 v204, v[106:107] offset:30464
	ds_write_b64 v204, v[104:105] offset:32640
	s_waitcnt lgkmcnt(0)
	s_barrier
	s_and_saveexec_b64 s[18:19], s[48:49]
	s_cbranch_execz .LBB0_276
	ds_read_b64 v[110:111], v154
	ds_read_b64 v[112:113], v154 offset:8
	ds_read_b64 v[106:107], v0
	ds_read_b64 v[114:115], v165 offset:8
	s_waitcnt vmcnt(1)
	v_lshlrev_b32_e32 v105, 16, v2
	v_lshlrev_b32_e32 v104, 16, v162
	v_and_b32_e32 v109, 16, v3
	v_and_b32_e32 v108, 0xffff0000, v2
	s_waitcnt lgkmcnt(0)
	v_mov_b32_e32 v127, v114
	v_mov_b32_e32 v114, v107
	v_mov_b32_e32 v116, v108
	v_pk_mov_b32 v[108:109], v[104:105], v[108:109] op_sel:[1,0]
	v_pk_fma_f32 v[104:105], v[54:55], v[104:105], v[60:61]
	v_mov_b32_e32 v126, v106
	v_pk_mul_f32 v[106:107], v[32:33], v[114:115]
	v_pk_fma_f32 v[104:105], v[56:57], v[108:109], v[104:105]
	v_pk_fma_f32 v[106:107], v[30:31], v[126:127], v[106:107] neg_lo:[0,0,1] neg_hi:[0,0,1]
	v_mov_b32_e32 v108, v110
	v_mov_b32_e32 v109, v112
	ds_read_b64 v[118:119], v166 offset:16
	ds_read_b64 v[124:125], v167 offset:24
	v_pk_add_f32 v[108:109], v[108:109], v[106:107]
	s_waitcnt vmcnt(0)
	v_lshlrev_b32_e32 v107, 16, v24
	v_lshlrev_b32_e32 v106, 16, v164
	v_and_b32_e32 v129, 16, v25
	v_and_b32_e32 v128, 0xffff0000, v24
	v_mov_b32_e32 v130, v128
	v_pk_mov_b32 v[128:129], v[106:107], v[128:129] op_sel:[1,0]
	v_pk_fma_f32 v[106:107], v[54:55], v[106:107], v[60:61]
	v_pk_mul_f32 v[126:127], v[32:33], v[126:127]
	ds_read_b64 v[120:121], v154 offset:16
	ds_read_b64 v[122:123], v154 offset:24
	v_pk_fma_f32 v[106:107], v[56:57], v[128:129], v[106:107]
	v_pk_fma_f32 v[114:115], v[30:31], v[114:115], v[126:127]
	ds_read_b64 v[126:127], v154 offset:32
	ds_read_b64 v[128:129], v154 offset:40
	ds_read_b64 v[132:133], v168 offset:32
	ds_read_b64 v[134:135], v169 offset:40
	v_mov_b32_e32 v112, v111
	v_pk_add_f32 v[110:111], v[112:113], v[114:115]
	v_and_b32_e32 v114, 0xffff0000, v3
	v_lshlrev_b32_e32 v177, 16, v4
	v_mov_b32_e32 v176, v114
	v_and_b32_e32 v113, 16, v5
	v_and_b32_e32 v112, 0xffff0000, v4
	s_waitcnt lgkmcnt(6)
	v_mov_b32_e32 v185, v124
	v_mov_b32_e32 v124, v119
	v_mov_b32_e32 v180, v112
	v_pk_mov_b32 v[178:179], v[176:177], v[112:113] op_sel:[1,0]
	v_mov_b32_e32 v184, v118
	v_pk_mul_f32 v[112:113], v[62:63], v[124:125]
	s_waitcnt lgkmcnt(4)
	v_mov_b32_e32 v118, v120
	v_pk_fma_f32 v[112:113], v[34:35], v[184:185], v[112:113] neg_lo:[0,0,1] neg_hi:[0,0,1]
	v_mov_b32_e32 v119, v122
	s_waitcnt lgkmcnt(0)
	v_mov_b32_e32 v189, v134
	v_mov_b32_e32 v134, v133
	v_lshlrev_b32_e32 v117, 16, v3
	v_and_b32_e32 v115, 16, v4
	v_pk_add_f32 v[112:113], v[118:119], v[112:113]
	v_mov_b32_e32 v188, v132
	v_pk_mul_f32 v[118:119], v[66:67], v[134:135]
	v_pk_fma_f32 v[182:183], v[54:55], v[116:117], v[60:61]
	v_pk_mov_b32 v[114:115], v[116:117], v[114:115] op_sel:[1,0]
	v_pk_fma_f32 v[118:119], v[64:65], v[188:189], v[118:119] neg_lo:[0,0,1] neg_hi:[0,0,1]
	v_mov_b32_e32 v132, v126
	v_mov_b32_e32 v133, v128
	v_pk_mul_f32 v[184:185], v[62:63], v[184:185]
	v_lshlrev_b32_e32 v131, 16, v25
	v_pk_fma_f32 v[114:115], v[56:57], v[114:115], v[182:183]
	ds_read_b64 v[182:183], v174 offset:48
	ds_read_b64 v[186:187], v175 offset:56
	v_pk_add_f32 v[118:119], v[132:133], v[118:119]
	v_and_b32_e32 v133, 16, v26
	v_and_b32_e32 v132, 0xffff0000, v25
	v_pk_fma_f32 v[124:125], v[34:35], v[124:125], v[184:185]
	v_mov_b32_e32 v122, v121
	v_pk_fma_f32 v[104:105], v[58:59], v[116:117], v[104:105]
	v_pk_fma_f32 v[106:107], v[58:59], v[130:131], v[106:107]
	v_pk_fma_f32 v[116:117], v[58:59], v[176:177], v[114:115]
	v_pk_fma_f32 v[114:115], v[54:55], v[176:177], v[60:61]
	v_pk_fma_f32 v[196:197], v[54:55], v[130:131], v[60:61]
	v_pk_add_f32 v[120:121], v[122:123], v[124:125]
	v_pk_mov_b32 v[122:123], v[130:131], v[132:133] op_sel:[1,0]
	v_pk_mul_f32 v[130:131], v[66:67], v[188:189]
	v_pk_fma_f32 v[114:115], v[56:57], v[178:179], v[114:115]
	ds_read_b64 v[176:177], v154 offset:48
	ds_read_b64 v[178:179], v154 offset:56
	v_pk_fma_f32 v[130:131], v[64:65], v[134:135], v[130:131]
	v_mov_b32_e32 v128, v127
	v_lshlrev_b32_e32 v181, 16, v5
	v_pk_add_f32 v[126:127], v[128:129], v[130:131]
	v_and_b32_e32 v129, 16, v161
	v_and_b32_e32 v128, 0xffff0000, v5
	v_mov_b32_e32 v190, v132
	v_mov_b32_e32 v130, v128
	v_pk_mov_b32 v[128:129], v[180:181], v[128:129] op_sel:[1,0]
	v_pk_fma_f32 v[132:133], v[54:55], v[180:181], v[60:61]
	v_lshlrev_b32_e32 v131, 16, v161
	v_pk_fma_f32 v[128:129], v[56:57], v[128:129], v[132:133]
	s_waitcnt lgkmcnt(2)
	v_mov_b32_e32 v135, v186
	v_mov_b32_e32 v186, v183
	v_pk_fma_f32 v[128:129], v[58:59], v[130:131], v[128:129]
	v_mov_b32_e32 v134, v182
	v_pk_mul_f32 v[130:131], v[70:71], v[186:187]
	v_and_b32_e32 v192, 0xffff0000, v26
	v_pk_fma_f32 v[130:131], v[68:69], v[134:135], v[130:131] neg_lo:[0,0,1] neg_hi:[0,0,1]
	s_waitcnt lgkmcnt(0)
	v_mov_b32_e32 v132, v176
	v_mov_b32_e32 v133, v178
	v_lshlrev_b32_e32 v191, 16, v26
	v_and_b32_e32 v193, 16, v27
	v_lshlrev_b32_e32 v195, 16, v27
	v_mov_b32_e32 v194, v192
	v_pk_fma_f32 v[122:123], v[56:57], v[122:123], v[196:197]
	v_pk_add_f32 v[132:133], v[132:133], v[130:131]
	v_and_b32_e32 v131, 16, v163
	v_and_b32_e32 v130, 0xffff0000, v27
	v_pk_fma_f32 v[114:115], v[58:59], v[180:181], v[114:115]
	v_pk_mov_b32 v[192:193], v[190:191], v[192:193] op_sel:[1,0]
	v_pk_fma_f32 v[124:125], v[58:59], v[190:191], v[122:123]
	v_pk_fma_f32 v[122:123], v[54:55], v[190:191], v[60:61]
	v_mov_b32_e32 v180, v130
	v_pk_mov_b32 v[130:131], v[194:195], v[130:131] op_sel:[1,0]
	v_pk_fma_f32 v[182:183], v[54:55], v[194:195], v[60:61]
	v_pk_mul_f32 v[134:135], v[70:71], v[134:135]
	v_pk_fma_f32 v[122:123], v[56:57], v[192:193], v[122:123]
	v_lshlrev_b32_e32 v181, 16, v163
	v_pk_fma_f32 v[130:131], v[56:57], v[130:131], v[182:183]
	v_pk_fma_f32 v[134:135], v[68:69], v[186:187], v[134:135]
	v_mov_b32_e32 v178, v177
	v_pk_fma_f32 v[122:123], v[58:59], v[194:195], v[122:123]
	v_pk_fma_f32 v[130:131], v[58:59], v[180:181], v[130:131]
	v_pk_add_f32 v[134:135], v[178:179], v[134:135]
	s_andn2_b64 vcc, exec, s[8:9]
	s_mov_b64 s[88:89], -1
	s_cbranch_vccnz .LBB0_302
	s_mov_b64 s[88:89], 0
	v_fma_f32 v108, v6, v8, v108
	v_fma_f32 v109, v6, v9, v109
	v_fma_f32 v112, v6, v10, v112
	v_fma_f32 v113, v6, v11, v113
	v_fma_f32 v118, v6, v12, v118
	v_fma_f32 v119, v6, v13, v119
	v_fma_f32 v132, v6, v14, v132
	v_fma_f32 v133, v6, v15, v133
	v_fma_f32 v110, v6, v16, v110
	v_fma_f32 v111, v6, v17, v111
	v_fma_f32 v120, v6, v18, v120
	v_fma_f32 v121, v6, v19, v121
	v_fma_f32 v126, v6, v20, v126
	v_fma_f32 v127, v6, v21, v127
	v_fma_f32 v134, v6, v22, v134
	v_fma_f32 v135, v6, v23, v135
	v_mul_f32_e32 v108, v104, v108
	v_mul_f32_e32 v109, v105, v109
	v_mul_f32_e32 v112, v116, v112
	v_mul_f32_e32 v113, v117, v113
	v_mul_f32_e32 v118, v114, v118
	v_mul_f32_e32 v119, v115, v119
	v_mul_f32_e32 v132, v128, v132
	v_mul_f32_e32 v133, v129, v133
	v_mul_f32_e32 v110, v106, v110
	v_mul_f32_e32 v111, v107, v111
	v_mul_f32_e32 v120, v124, v120
	v_mul_f32_e32 v121, v125, v121
	v_mul_f32_e32 v126, v122, v126
	v_mul_f32_e32 v127, v123, v127
	v_mul_f32_e32 v134, v130, v134
	v_mul_f32_e32 v135, v131, v135
	v_cvt_pk_bf16_f32 v8, v108, v109
	v_cvt_pk_bf16_f32 v9, v112, v113
	v_cvt_pk_bf16_f32 v10, v118, v119
	v_cvt_pk_bf16_f32 v11, v132, v133
	v_cvt_pk_bf16_f32 v12, v110, v111
	v_cvt_pk_bf16_f32 v13, v120, v121
	v_cvt_pk_bf16_f32 v14, v126, v127
	v_cvt_pk_bf16_f32 v15, v134, v135
	s_mul_i32 s36, s2, 0x11000
	s_add_u32 s36, s36, 0x6d00000
	s_add_u32 s36, s64, s36
	s_addc_u32 s37, s65, 0
	v_add_u32_e32 v176, s14, v44
	v_lshlrev_b32_e32 v176, 1, v176
	v_add_u32_e32 v177, 0x2000, v176
	global_store_dwordx4 v176, v[8:11], s[36:37]
	global_store_dwordx4 v177, v[12:15], s[36:37]
